# v58 + hyena: 65 multiply-by-(+-i) ops folded into their packed consumers via op_sel/neg modifiers with register role swap (checked numerically)
# baseline (speedup 1.0000x reference)
; template <int R, bool INV> DEV void dft_regs(cf (&v)[R]) {
;     ...
;     for (int s = R; s >= 2; s >>= 1) {
;         const int h = s >> 1;
; #pragma unroll
;         for (int b = 0; b < R; b += s) {
; #pragma unroll
;             for (int k = 0; k < h; ++k) {
;                 const cf a = v[b + k], c = v[b + k + h];
;                 v[b + k] = a + c;
;                 const cf d = a - c;
;                 const int m = k * (32 / s);
;                 const float wr = tw_cos(m), wi = INV ? tw_sin(m) : -tw_sin(m);
;                 v[b + k + h] = cf{d.x * wr - d.y * wi, d.x * wi + d.y * wr};
;             }
;         }
;     }
; DEV void fft_i1x2(LAS cf* buf0, LAS cf* buf1, cf (&y0)[8], cf (&y1)[8], int tid) {
;     ...
;     dft_regs<16, true>(v); dft_regs<16, true>(u);
.LBB0_518:
	v_pk_add_f32 v[126:127], v[76:77], v[100:101]
	v_pk_add_f32 v[76:77], v[76:77], v[100:101] neg_lo:[0,1] neg_hi:[0,1]
	s_mov_b32 s10, s85
	s_mov_b32 s8, s97
	s_xor_b64 s[2:3], s[22:23], -1
	v_pk_add_f32 v[164:165], v[78:79], v[112:113]
	v_pk_add_f32 v[78:79], v[78:79], v[112:113] neg_lo:[0,1] neg_hi:[0,1]
	s_lshl_b64 s[6:7], s[6:7], 2
	v_pk_mul_f32 v[100:101], v[78:79], s[84:85] op_sel_hi:[1,0]
	s_add_u32 s22, s76, s6
	v_pk_fma_f32 v[112:113], v[78:79], s[10:11], v[100:101] op_sel:[0,0,1] op_sel_hi:[1,0,0] neg_lo:[0,0,1]
	s_addc_u32 s23, s77, s7
	v_pk_add_f32 v[78:79], v[82:83], v[116:117]
	v_pk_add_f32 v[82:83], v[82:83], v[116:117] neg_lo:[0,1] neg_hi:[0,1]
	s_add_u32 s6, s74, s6
	v_pk_mul_f32 v[100:101], v[82:83], s[8:9] op_sel_hi:[1,0]
	s_waitcnt lgkmcnt(0)
	v_pk_fma_f32 v[116:117], v[82:83], s[8:9], v[100:101] op_sel:[0,0,1] op_sel_hi:[1,0,0] neg_lo:[0,0,1] neg_hi:[0,0,1]
	v_pk_fma_f32 v[82:83], v[82:83], s[8:9], v[100:101] op_sel_hi:[1,0,0]
	v_pk_add_f32 v[100:101], v[84:85], v[118:119]
	v_pk_add_f32 v[84:85], v[84:85], v[118:119] neg_lo:[0,1] neg_hi:[0,1]
	v_mov_b32_e32 v117, v83
	v_pk_mul_f32 v[118:119], v[84:85], s[10:11] op_sel_hi:[1,0]
	s_barrier
	v_pk_fma_f32 v[166:167], v[84:85], s[84:85], v[118:119] op_sel:[0,0,1] op_sel_hi:[1,0,0] neg_lo:[0,0,1]
	v_pk_add_f32 v[84:85], v[86:87], v[120:121]
	v_pk_add_f32 v[86:87], v[86:87], v[120:121] neg_lo:[0,1] neg_hi:[0,1]
	s_addc_u32 s7, s75, s7
	s_mov_b32 s19, 1
	v_pk_add_f32 v[118:119], v[90:91], v[122:123]
	v_pk_add_f32 v[90:91], v[90:91], v[122:123] neg_lo:[0,1] neg_hi:[0,1]
	v_pk_add_f32 v[122:123], v[98:99], v[92:93]
	v_pk_add_f32 v[92:93], v[98:99], v[92:93] neg_lo:[0,1] neg_hi:[0,1]
	v_pk_mul_f32 v[120:121], v[90:91], s[24:25] op_sel:[1,0]
	v_pk_mul_f32 v[98:99], v[92:93], s[84:85] op_sel:[1,0]
	v_pk_fma_f32 v[90:91], v[90:91], s[0:1], v[120:121] op_sel_hi:[0,1,1] neg_lo:[0,0,1] neg_hi:[0,0,1]
	v_pk_fma_f32 v[92:93], v[92:93], s[88:89], v[98:99] op_sel_hi:[0,1,1] neg_lo:[0,0,1] neg_hi:[0,0,1]
	v_pk_add_f32 v[98:99], v[126:127], v[84:85]
	v_pk_add_f32 v[84:85], v[126:127], v[84:85] neg_lo:[0,1] neg_hi:[0,1]
	v_pk_add_f32 v[120:121], v[94:95], v[124:125]
	v_pk_add_f32 v[94:95], v[94:95], v[124:125] neg_lo:[0,1] neg_hi:[0,1]
	v_mul_f32_e32 v82, 0x3f3504f3, v95
	v_pk_fma_f32 v[94:95], v[94:95], s[96:97], v[82:83] op_sel_hi:[0,1,0] neg_lo:[0,0,1] neg_hi:[0,0,1]
	v_pk_add_f32 v[126:127], v[164:165], v[118:119]
	v_pk_add_f32 v[164:165], v[164:165], v[118:119] neg_lo:[0,1] neg_hi:[0,1]
	v_pk_add_f32 v[82:83], v[116:117], v[94:95]
	v_pk_mul_f32 v[118:119], v[164:165], s[8:9] op_sel_hi:[1,0]
	s_mov_b64 s[26:27], -1
	v_pk_fma_f32 v[124:125], v[164:165], s[8:9], v[118:119] op_sel:[0,0,1] op_sel_hi:[1,0,0] neg_lo:[0,0,1] neg_hi:[0,0,1]
	v_pk_fma_f32 v[164:165], v[164:165], s[8:9], v[118:119] op_sel_hi:[1,0,0]
	v_pk_add_f32 v[118:119], v[78:79], v[120:121]
	v_pk_add_f32 v[78:79], v[78:79], v[120:121] neg_lo:[0,1] neg_hi:[0,1]
	v_mov_b32_e32 v125, v165
	v_pk_add_f32 v[120:121], v[100:101], v[122:123]
	v_pk_add_f32 v[100:101], v[100:101], v[122:123] neg_lo:[0,1] neg_hi:[0,1]
	v_pk_add_f32 v[122:123], v[76:77], v[86:87] op_sel:[0,1] op_sel_hi:[1,0] neg_lo:[0,1]
	v_pk_add_f32 v[86:87], v[76:77], v[86:87] op_sel:[0,1] op_sel_hi:[1,0] neg_hi:[0,1]
	v_mul_f32_e32 v164, 0x3f3504f3, v101
	v_pk_fma_f32 v[100:101], v[100:101], s[96:97], v[164:165] op_sel_hi:[0,1,0] neg_lo:[0,0,1] neg_hi:[0,0,1]
	v_mov_b32_e32 v168, v86
	v_mov_b32_e32 v169, v87
	v_pk_add_f32 v[86:87], v[112:113], v[90:91]
	v_pk_add_f32 v[90:91], v[112:113], v[90:91] neg_lo:[0,1] neg_hi:[0,1]
	v_pk_mul_f32 v[112:113], v[90:91], s[8:9] op_sel_hi:[1,0]
	v_pk_fma_f32 v[76:77], v[90:91], s[8:9], v[112:113] op_sel:[0,0,1] op_sel_hi:[1,0,0] neg_lo:[0,0,1]
	v_pk_add_f32 v[112:113], v[98:99], v[118:119]
	v_pk_add_f32 v[118:119], v[98:99], v[118:119] neg_lo:[0,1] neg_hi:[0,1]
	v_pk_add_f32 v[90:91], v[116:117], v[94:95] neg_lo:[0,1] neg_hi:[0,1]
	v_pk_add_f32 v[98:99], v[84:85], v[78:79] op_sel:[0,1] op_sel_hi:[1,0] neg_hi:[0,1]
	v_pk_add_f32 v[116:117], v[126:127], v[120:121]
	v_pk_add_f32 v[120:121], v[126:127], v[120:121] neg_lo:[0,1] neg_hi:[0,1]
	v_pk_add_f32 v[126:127], v[84:85], v[78:79] op_sel:[0,1] op_sel_hi:[1,0] neg_lo:[0,1]
	v_pk_add_f32 v[94:95], v[166:167], v[92:93]
	v_pk_add_f32 v[92:93], v[166:167], v[92:93] neg_lo:[0,1] neg_hi:[0,1]
	v_mul_f32_e32 v164, 0x3f3504f3, v93
	v_pk_add_f32 v[84:85], v[124:125], v[100:101] neg_lo:[0,1] neg_hi:[0,1]
	v_pk_fma_f32 v[92:93], v[92:93], s[96:97], v[164:165] op_sel_hi:[0,1,0] neg_lo:[0,0,1] neg_hi:[0,0,1]
	v_pk_add_f32 v[164:165], v[124:125], v[100:101]
	v_pk_add_f32 v[78:79], v[122:123], v[82:83]
	v_pk_add_f32 v[82:83], v[122:123], v[82:83] neg_lo:[0,1] neg_hi:[0,1]
	v_pk_add_f32 v[124:125], v[168:169], v[90:91] op_sel:[0,1] op_sel_hi:[1,0] neg_lo:[0,1]
	v_pk_add_f32 v[100:101], v[126:127], v[164:165]
	v_pk_add_f32 v[122:123], v[86:87], v[94:95]
	v_pk_add_f32 v[94:95], v[86:87], v[94:95] neg_lo:[0,1] neg_hi:[0,1]
	v_pk_add_f32 v[164:165], v[16:17], v[88:89]
	v_pk_add_f32 v[16:17], v[16:17], v[88:89] neg_lo:[0,1] neg_hi:[0,1]
	v_pk_add_f32 v[86:87], v[168:169], v[90:91] op_sel:[0,1] op_sel_hi:[1,0] neg_hi:[0,1]
	v_pk_add_f32 v[112:113], v[112:113], v[116:117]
	v_mov_b32_e32 v166, v86
	v_mov_b32_e32 v167, v87
	v_pk_add_f32 v[86:87], v[76:77], v[92:93]
	v_pk_add_f32 v[90:91], v[76:77], v[92:93] neg_lo:[0,1] neg_hi:[0,1]
	v_pk_add_f32 v[92:93], v[118:119], v[120:121] op_sel:[0,1] op_sel_hi:[1,0] neg_lo:[0,1]
	v_pk_add_f32 v[76:77], v[90:91], 0 op_sel:[1,0] op_sel_hi:[0,0] neg_lo:[1,0]
	v_pk_add_f32 v[126:127], v[18:19], v[96:97]
	v_pk_add_f32 v[18:19], v[18:19], v[96:97] neg_lo:[0,1] neg_hi:[0,1]
; #define LAS __attribute__((address_space(3)))
; #define U2F(x) __uint_as_float(x)
; template <int R, bool INV> DEV void dft_regs(cf (&v)[R]) {
;     ...
;     for (int s = R; s >= 2; s >>= 1) {
;         const int h = s >> 1;
; #pragma unroll
;         for (int b = 0; b < R; b += s) {
; #pragma unroll
;             for (int k = 0; k < h; ++k) {
;                 const cf a = v[b + k], c = v[b + k + h];
;                 v[b + k] = a + c;
;                 const cf d = a - c;
;                 const int m = k * (32 / s);
;                 const float wr = tw_cos(m), wi = INV ? tw_sin(m) : -tw_sin(m);
;                 v[b + k + h] = cf{d.x * wr - d.y * wi, d.x * wi + d.y * wr};
;             }
;         }
;     }
; template <int MODE> DEV void hyena_conv_rows(const LAS unsigned char* lds, int slot0, float w0, float w1, float w2, float bs, cf (&z)[2][8], const cf (&y)[2][8], float hb, int tid) {
; #pragma unroll
;     for (int b = 0; b < 4; ++b) {
;         const LAS bf16_t* row = (const LAS bf16_t*)(lds + (slot0 + b) * 8192);
; #pragma unroll
;         for (int i = 0; i < 8; ++i) {
;             const int t = tid + 512 * i, par = tid & 1, d0 = (tid >> 1) + par;
;             const LAS unsigned* rw = (const LAS unsigned*)row + d0;
;             const unsigned dw0 = (i == 0) ? rw[d0 > 0 ? -1 : 0] : rw[256 * i - 1], dw1 = rw[256 * i];
;             float um = par ? U2F(dw0 << 16) : U2F(dw0 & 0xffff0000u);
;             const float u0 = par ? U2F(dw0 & 0xffff0000u) : U2F(dw1 << 16);
;             float up = par ? U2F(dw1 << 16) : U2F(dw1 & 0xffff0000u);
;             um = (t > 0) ? um : 0.f; up = (t < 4095) ? up : 0.f;
;             const float r = um * w0 + u0 * w1 + up * w2 + bs;
	v_pk_mul_f32 v[120:121], v[18:19], s[84:85] op_sel_hi:[1,0]
	v_pk_fma_f32 v[88:89], v[18:19], s[10:11], v[120:121] op_sel:[0,0,1] op_sel_hi:[1,0,0] neg_lo:[0,0,1]
	v_pk_add_f32 v[90:91], v[82:83], v[94:95] op_sel:[0,1] op_sel_hi:[1,0] neg_lo:[0,1]
	v_pk_add_f32 v[18:19], v[66:67], v[102:103]
	v_pk_add_f32 v[66:67], v[66:67], v[102:103] neg_lo:[0,1] neg_hi:[0,1]
	v_pk_add_f32 v[94:95], v[98:99], v[84:85] op_sel:[0,1] op_sel_hi:[1,0] neg_lo:[0,1]
	v_pk_mul_f32 v[120:121], v[66:67], s[8:9] op_sel_hi:[1,0]
	v_pk_add_f32 v[84:85], v[78:79], v[122:123]
	v_pk_fma_f32 v[96:97], v[66:67], s[8:9], v[120:121] op_sel:[0,0,1] op_sel_hi:[1,0,0] neg_lo:[0,0,1]
	v_pk_add_f32 v[86:87], v[124:125], v[86:87]
	v_pk_add_f32 v[66:67], v[68:69], v[104:105]
	v_pk_add_f32 v[68:69], v[68:69], v[104:105] neg_lo:[0,1] neg_hi:[0,1]
	v_pk_add_f32 v[82:83], v[166:167], v[76:77]
	v_pk_mul_f32 v[78:79], v[68:69], s[10:11] op_sel_hi:[1,0]
	v_pk_fma_f32 v[102:103], v[68:69], s[84:85], v[78:79] op_sel:[0,0,1] op_sel_hi:[1,0,0] neg_lo:[0,0,1]
	v_pk_add_f32 v[68:69], v[70:71], v[106:107]
	v_pk_add_f32 v[70:71], v[70:71], v[106:107] neg_lo:[0,1] neg_hi:[0,1]
	v_pk_add_f32 v[78:79], v[70:71], 0 op_sel:[1,0] op_sel_hi:[0,0] neg_lo:[1,0]
	v_pk_add_f32 v[70:71], v[72:73], v[108:109]
	v_pk_add_f32 v[72:73], v[72:73], v[108:109] neg_lo:[0,1] neg_hi:[0,1]
	v_pk_add_f32 v[120:121], v[16:17], v[78:79]
	v_pk_mul_f32 v[104:105], v[72:73], s[24:25] op_sel:[1,0]
	v_pk_fma_f32 v[72:73], v[72:73], s[0:1], v[104:105] op_sel_hi:[0,1,1] neg_lo:[0,0,1] neg_hi:[0,0,1]
	v_pk_add_f32 v[104:105], v[74:75], v[110:111]
	v_pk_add_f32 v[74:75], v[74:75], v[110:111] neg_lo:[0,1] neg_hi:[0,1]
	v_pk_add_f32 v[116:117], v[18:19], v[104:105]
	v_mul_f32_e32 v106, 0x3f3504f3, v75
	v_pk_fma_f32 v[74:75], v[74:75], s[96:97], v[106:107] op_sel_hi:[0,1,0] neg_lo:[0,0,1] neg_hi:[0,0,1]
	v_pk_add_f32 v[106:107], v[80:81], v[114:115]
	v_pk_add_f32 v[80:81], v[80:81], v[114:115] neg_lo:[0,1] neg_hi:[0,1]
	v_pk_add_f32 v[118:119], v[66:67], v[106:107]
	v_pk_mul_f32 v[108:109], v[80:81], s[84:85] op_sel:[1,0]
	v_pk_fma_f32 v[80:81], v[80:81], s[88:89], v[108:109] op_sel_hi:[0,1,1] neg_lo:[0,0,1] neg_hi:[0,0,1]
	v_pk_add_f32 v[108:109], v[164:165], v[68:69]
	v_pk_add_f32 v[68:69], v[164:165], v[68:69] neg_lo:[0,1] neg_hi:[0,1]
	v_mov_b32_e32 v110, v68
	v_mov_b32_e32 v111, v69
	v_pk_add_f32 v[76:77], v[126:127], v[70:71]
	v_pk_add_f32 v[126:127], v[126:127], v[70:71] neg_lo:[0,1] neg_hi:[0,1]
	v_pk_mul_f32 v[68:69], v[126:127], s[8:9] op_sel_hi:[1,0]
	v_pk_fma_f32 v[114:115], v[126:127], s[8:9], v[68:69] op_sel:[0,0,1] op_sel_hi:[1,0,0] neg_lo:[0,0,1]
	v_pk_add_f32 v[126:127], v[18:19], v[104:105] neg_lo:[0,1] neg_hi:[0,1]
	v_pk_add_f32 v[104:105], v[126:127], 0 op_sel:[1,0] op_sel_hi:[0,0] neg_lo:[1,0]
	v_pk_add_f32 v[126:127], v[66:67], v[106:107] neg_lo:[0,1] neg_hi:[0,1]
	v_mul_f32_e32 v18, 0x3f3504f3, v127
	v_pk_fma_f32 v[106:107], v[126:127], s[96:97], v[18:19] op_sel_hi:[0,1,0] neg_lo:[0,0,1] neg_hi:[0,0,1]
	v_pk_add_f32 v[126:127], v[16:17], v[78:79] neg_lo:[0,1] neg_hi:[0,1]
	v_pk_add_f32 v[98:99], v[88:89], v[72:73]
	v_mov_b32_e32 v78, v126
	v_mov_b32_e32 v79, v127
	v_pk_add_f32 v[16:17], v[88:89], v[72:73] neg_lo:[0,1] neg_hi:[0,1]
	v_pk_add_f32 v[88:89], v[96:97], v[74:75]
	v_pk_mul_f32 v[18:19], v[16:17], s[8:9] op_sel_hi:[1,0]
	v_pk_fma_f32 v[72:73], v[16:17], s[8:9], v[18:19] op_sel:[0,0,1] op_sel_hi:[1,0,0] neg_lo:[0,0,1]
	v_pk_add_f32 v[16:17], v[96:97], v[74:75] neg_lo:[0,1] neg_hi:[0,1]
	v_pk_add_f32 v[96:97], v[102:103], v[80:81]
	v_pk_fma_f32 v[74:75], v[16:17], 0, v[16:17] op_sel:[0,0,1] op_sel_hi:[1,0,0] neg_lo:[0,0,1] neg_hi:[0,0,1]
	v_pk_fma_f32 v[16:17], v[16:17], 0, v[16:17] op_sel:[0,0,1] op_sel_hi:[1,0,0]
	global_load_dword v18, v20, s[22:23]
	global_load_dword v66, v245, s[22:23]
	global_load_dword v16, v206, s[22:23]
	s_add_i32 s22, s5, s78
	s_ashr_i32 s23, s22, 31
	s_lshl_b64 s[22:23], s[22:23], 2
	s_add_u32 s22, s72, s22
	s_addc_u32 s23, s73, s23
	global_load_dword v68, v20, s[6:7]
	global_load_dword v70, v20, s[22:23]
	v_pk_add_f32 v[80:81], v[102:103], v[80:81] neg_lo:[0,1] neg_hi:[0,1]
	v_mov_b32_e32 v75, v17
	v_mul_f32_e32 v102, 0x3f3504f3, v81
	v_pk_fma_f32 v[80:81], v[80:81], s[96:97], v[102:103] op_sel_hi:[0,1,0] neg_lo:[0,0,1] neg_hi:[0,0,1]
	v_pk_add_f32 v[102:103], v[108:109], v[116:117]
	v_pk_add_f32 v[108:109], v[108:109], v[116:117] neg_lo:[0,1] neg_hi:[0,1]
	v_pk_add_f32 v[124:125], v[78:79], v[74:75]
	v_pk_add_f32 v[74:75], v[78:79], v[74:75] neg_lo:[0,1] neg_hi:[0,1]
	v_pk_add_f32 v[122:123], v[76:77], v[118:119]
	v_pk_add_f32 v[76:77], v[76:77], v[118:119] neg_lo:[0,1] neg_hi:[0,1]
	v_mov_b32_e32 v126, v74
	v_mov_b32_e32 v127, v75
	v_pk_add_f32 v[116:117], v[110:111], v[104:105]
	v_pk_add_f32 v[104:105], v[110:111], v[104:105] neg_lo:[0,1] neg_hi:[0,1]
	v_pk_add_f32 v[78:79], v[108:109], v[76:77] op_sel:[0,1] op_sel_hi:[1,0] neg_lo:[0,1]
	v_pk_add_f32 v[164:165], v[72:73], v[80:81]
	v_pk_add_f32 v[118:119], v[114:115], v[106:107]
	v_pk_add_f32 v[106:107], v[114:115], v[106:107] neg_lo:[0,1] neg_hi:[0,1]
	v_pk_add_f32 v[72:73], v[72:73], v[80:81] neg_lo:[0,1] neg_hi:[0,1]
	v_pk_add_f32 v[110:111], v[106:107], 0 op_sel:[1,0] op_sel_hi:[0,0] neg_lo:[1,0]
	v_pk_add_f32 v[80:81], v[124:125], v[164:165]
	v_pk_add_f32 v[106:107], v[120:121], v[88:89]
	v_pk_add_f32 v[88:89], v[120:121], v[88:89] neg_lo:[0,1] neg_hi:[0,1]
	v_pk_add_f32 v[74:75], v[104:105], v[110:111]
	v_pk_fma_f32 v[166:167], v[72:73], 0, v[72:73] op_sel:[0,0,1] op_sel_hi:[1,0,0] neg_lo:[0,0,1]
	v_mov_b32_e32 v120, v88
	v_mov_b32_e32 v121, v89
	v_pk_add_f32 v[88:89], v[98:99], v[96:97]
	v_pk_add_f32 v[98:99], v[98:99], v[96:97] neg_lo:[0,1] neg_hi:[0,1]
	v_pk_add_f32 v[96:97], v[102:103], v[122:123]
	ds_read2st64_b32 v[102:103], v130 offset1:32
	v_pk_add_f32 v[114:115], v[98:99], 0 op_sel:[1,0] op_sel_hi:[0,0] neg_lo:[1,0]
	v_pk_add_f32 v[88:89], v[106:107], v[88:89]
	v_pk_add_f32 v[98:99], v[116:117], v[118:119]
	ds_read2st64_b32 v[104:105], v129 offset1:32
	s_waitcnt lgkmcnt(1)
; #define LAS __attribute__((address_space(3)))
; #define U2F(x) __uint_as_float(x)
; template <int MODE> DEV void hyena_conv_rows(const LAS unsigned char* lds, int slot0, float w0, float w1, float w2, float bs, cf (&z)[2][8], const cf (&y)[2][8], float hb, int tid) {
; #pragma unroll
;     for (int b = 0; b < 4; ++b) {
;         const LAS bf16_t* row = (const LAS bf16_t*)(lds + (slot0 + b) * 8192);
; #pragma unroll
;         for (int i = 0; i < 8; ++i) {
;             const int t = tid + 512 * i, par = tid & 1, d0 = (tid >> 1) + par;
;             const LAS unsigned* rw = (const LAS unsigned*)row + d0;
;             const unsigned dw0 = (i == 0) ? rw[d0 > 0 ? -1 : 0] : rw[256 * i - 1], dw1 = rw[256 * i];
;             float um = par ? U2F(dw0 << 16) : U2F(dw0 & 0xffff0000u);
;             const float u0 = par ? U2F(dw0 & 0xffff0000u) : U2F(dw1 << 16);
;             float up = par ? U2F(dw1 << 16) : U2F(dw1 & 0xffff0000u);
;             um = (t > 0) ? um : 0.f; up = (t < 4095) ? up : 0.f;
;             const float r = um * w0 + u0 * w1 + up * w2 + bs;
;             if (MODE == 0) { if (b & 1) z[b >> 1][i].y = r; else z[b >> 1][i].x = r; }
;             else { if (b & 1) z[b >> 1][i].y = r * (y[b >> 1][i].y + hb * z[b >> 1][i].y); else z[b >> 1][i].x = r * (y[b >> 1][i].x + hb * z[b >> 1][i].x); }
;         }
	v_and_b32_e32 v17, 0xffff0000, v103
	v_and_b32_e32 v19, 0xffff0000, v102
	v_lshlrev_b32_e32 v67, 16, v103
	v_lshlrev_b32_e32 v69, 16, v102
	v_cndmask_b32_e64 v69, v69, v19, s[38:39]
	v_cndmask_b32_e64 v67, v67, v17, s[38:39]
	v_cndmask_b32_e64 v103, 0, v67, s[40:41]
	v_cndmask_b32_e64 v102, 0, v69, s[40:41]
	s_waitcnt lgkmcnt(0)
	v_lshlrev_b32_e32 v67, 16, v104
	v_lshlrev_b32_e32 v69, 16, v105
	v_cndmask_b32_e64 v107, v17, v69, s[38:39]
	v_cndmask_b32_e64 v106, v19, v67, s[38:39]
	v_and_b32_e32 v17, 0xffff0000, v105
	v_cndmask_b32_e64 v17, v69, v17, s[38:39]
	v_cndmask_b32_e64 v105, 0, v17, s[42:43]
	v_pk_add_f32 v[76:77], v[120:121], v[114:115]
	s_waitcnt vmcnt(3)
	v_pk_mul_f32 v[106:107], v[66:67], v[106:107] op_sel_hi:[0,1]
	v_pk_fma_f32 v[102:103], v[18:19], v[102:103], v[106:107] op_sel_hi:[0,1,1]
	v_and_b32_e32 v19, 0xffff0000, v104
	v_cndmask_b32_e64 v19, v67, v19, s[38:39]
	v_cndmask_b32_e64 v104, 0, v19, s[42:43]
	s_waitcnt vmcnt(2)
	v_pk_fma_f32 v[102:103], v[16:17], v[104:105], v[102:103] op_sel_hi:[0,1,1]
	s_waitcnt vmcnt(1)
	v_pk_add_f32 v[102:103], v[68:69], v[102:103] op_sel_hi:[0,1]
	s_waitcnt vmcnt(0)
	v_pk_fma_f32 v[24:25], v[24:25], v[70:71], v[112:113] op_sel_hi:[1,0,1]
	v_pk_fma_f32 v[30:31], v[30:31], v[70:71], v[84:85] op_sel_hi:[1,0,1]
	v_pk_mul_f32 v[24:25], v[24:25], v[102:103]
	ds_read2_b32 v[106:107], v138 offset1:1
	ds_read2_b32 v[108:109], v131 offset1:1
	ds_read2_b32 v[110:111], v135 offset1:1
	ds_read2_b32 v[102:103], v136 offset1:1
	ds_read2_b32 v[104:105], v137 offset1:1
	s_waitcnt lgkmcnt(4)
	v_and_b32_e32 v17, 0xffff0000, v106
	s_waitcnt lgkmcnt(3)
	v_and_b32_e32 v19, 0xffff0000, v108
	v_lshlrev_b32_e32 v67, 16, v106
	v_lshlrev_b32_e32 v69, 16, v108
	v_cndmask_b32_e64 v69, v69, v19, s[38:39]
	v_cndmask_b32_e64 v67, v67, v17, s[38:39]
	v_cndmask_b32_e64 v119, 0, v67, s[44:45]
	v_cndmask_b32_e64 v118, 0, v69, s[44:45]
	v_lshlrev_b32_e32 v67, 16, v109
	v_lshlrev_b32_e32 v69, 16, v107
	v_cndmask_b32_e64 v121, v17, v69, s[38:39]
	v_cndmask_b32_e64 v120, v19, v67, s[38:39]
	ds_read2_b32 v[112:113], v132 offset1:1
	ds_read2_b32 v[114:115], v133 offset1:1
	ds_read2_b32 v[116:117], v134 offset1:1
	v_pk_mul_f32 v[120:121], v[66:67], v[120:121] op_sel_hi:[0,1]
	ds_read2_b32 v[84:85], v139 offset1:1
	v_pk_fma_f32 v[118:119], v[18:19], v[118:119], v[120:121] op_sel_hi:[0,1,1]
	v_and_b32_e32 v17, 0xffff0000, v107
	v_and_b32_e32 v19, 0xffff0000, v109
	v_cndmask_b32_e64 v19, v67, v19, s[38:39]
	v_cndmask_b32_e64 v17, v69, v17, s[38:39]
	v_cndmask_b32_e64 v107, 0, v17, s[46:47]
	v_cndmask_b32_e64 v106, 0, v19, s[46:47]
	v_pk_fma_f32 v[106:107], v[16:17], v[106:107], v[118:119] op_sel_hi:[0,1,1]
	v_pk_add_f32 v[106:107], v[68:69], v[106:107] op_sel_hi:[0,1]
	s_waitcnt lgkmcnt(0)
	v_and_b32_e32 v17, 0xffff0000, v84
	v_and_b32_e32 v19, 0xffff0000, v112
	v_lshlrev_b32_e32 v67, 16, v84
	v_lshlrev_b32_e32 v69, 16, v112
	v_cndmask_b32_e64 v69, v69, v19, s[38:39]
	v_cndmask_b32_e64 v67, v67, v17, s[38:39]
	v_cndmask_b32_e64 v121, 0, v67, s[48:49]
	v_cndmask_b32_e64 v120, 0, v69, s[48:49]
	v_lshlrev_b32_e32 v67, 16, v113
	v_lshlrev_b32_e32 v69, 16, v85
	v_cndmask_b32_e64 v123, v17, v69, s[38:39]
	v_cndmask_b32_e64 v122, v19, v67, s[38:39]
	v_pk_mul_f32 v[122:123], v[66:67], v[122:123] op_sel_hi:[0,1]
	v_pk_fma_f32 v[120:121], v[18:19], v[120:121], v[122:123] op_sel_hi:[0,1,1]
	v_and_b32_e32 v17, 0xffff0000, v85
	v_and_b32_e32 v19, 0xffff0000, v113
	v_pk_mul_f32 v[30:31], v[30:31], v[106:107]
	ds_read2_b32 v[106:107], v140 offset1:1
	ds_read2_b32 v[108:109], v141 offset1:1
	ds_read2_b32 v[118:119], v142 offset1:1
	v_cndmask_b32_e64 v19, v67, v19, s[38:39]
	v_cndmask_b32_e64 v17, v69, v17, s[38:39]
	v_cndmask_b32_e64 v85, 0, v17, s[50:51]
	v_cndmask_b32_e64 v84, 0, v19, s[50:51]
	v_pk_fma_f32 v[84:85], v[16:17], v[84:85], v[120:121] op_sel_hi:[0,1,1]
	v_pk_add_f32 v[84:85], v[68:69], v[84:85] op_sel_hi:[0,1]
	s_waitcnt lgkmcnt(2)
	v_and_b32_e32 v17, 0xffff0000, v106
	v_and_b32_e32 v19, 0xffff0000, v114
	v_lshlrev_b32_e32 v67, 16, v106
	v_lshlrev_b32_e32 v69, 16, v114
	v_cndmask_b32_e64 v69, v69, v19, s[38:39]
	v_cndmask_b32_e64 v67, v67, v17, s[38:39]
	v_pk_fma_f32 v[28:29], v[28:29], v[70:71], v[100:101] op_sel_hi:[1,0,1]
	v_cndmask_b32_e64 v101, 0, v67, s[52:53]
	v_cndmask_b32_e64 v100, 0, v69, s[52:53]
	v_lshlrev_b32_e32 v67, 16, v115
	v_lshlrev_b32_e32 v69, 16, v107
	v_pk_mul_f32 v[28:29], v[28:29], v[84:85]
	v_cndmask_b32_e64 v85, v17, v69, s[38:39]
	v_cndmask_b32_e64 v84, v19, v67, s[38:39]
	v_pk_mul_f32 v[84:85], v[66:67], v[84:85] op_sel_hi:[0,1]
	v_pk_fma_f32 v[100:101], v[18:19], v[100:101], v[84:85] op_sel_hi:[0,1,1]
	v_and_b32_e32 v17, 0xffff0000, v107
	v_and_b32_e32 v19, 0xffff0000, v115
	v_cndmask_b32_e64 v19, v67, v19, s[38:39]
	v_cndmask_b32_e64 v17, v69, v17, s[38:39]
	v_cndmask_b32_e64 v85, 0, v17, s[54:55]
	v_cndmask_b32_e64 v84, 0, v19, s[54:55]
	v_pk_fma_f32 v[100:101], v[16:17], v[84:85], v[100:101] op_sel_hi:[0,1,1]
	v_pk_add_f32 v[84:85], v[68:69], v[100:101] op_sel_hi:[0,1]
	s_waitcnt lgkmcnt(1)
	v_and_b32_e32 v17, 0xffff0000, v108
	v_and_b32_e32 v19, 0xffff0000, v116
	v_lshlrev_b32_e32 v67, 16, v108
	v_lshlrev_b32_e32 v69, 16, v116
	v_cndmask_b32_e64 v69, v69, v19, s[38:39]
	v_cndmask_b32_e64 v67, v67, v17, s[38:39]
	v_pk_fma_f32 v[26:27], v[26:27], v[70:71], v[86:87] op_sel_hi:[1,0,1]
	v_cndmask_b32_e64 v87, 0, v67, s[56:57]
	v_cndmask_b32_e64 v86, 0, v69, s[56:57]
	v_lshlrev_b32_e32 v67, 16, v117
	v_lshlrev_b32_e32 v69, 16, v109
	v_pk_mul_f32 v[26:27], v[26:27], v[84:85]
	v_cndmask_b32_e64 v85, v17, v69, s[38:39]
	v_cndmask_b32_e64 v84, v19, v67, s[38:39]
	v_pk_mul_f32 v[84:85], v[66:67], v[84:85] op_sel_hi:[0,1]
	v_pk_fma_f32 v[86:87], v[18:19], v[86:87], v[84:85] op_sel_hi:[0,1,1]
	v_and_b32_e32 v17, 0xffff0000, v109
	v_and_b32_e32 v19, 0xffff0000, v117
	v_cndmask_b32_e64 v19, v67, v19, s[38:39]
	v_cndmask_b32_e64 v17, v69, v17, s[38:39]
	v_cndmask_b32_e64 v85, 0, v17, s[58:59]
	v_cndmask_b32_e64 v84, 0, v19, s[58:59]
	v_pk_fma_f32 v[86:87], v[16:17], v[84:85], v[86:87] op_sel_hi:[0,1,1]
	v_pk_add_f32 v[86:87], v[68:69], v[86:87] op_sel_hi:[0,1]
	s_waitcnt lgkmcnt(0)
; #define LAS __attribute__((address_space(3)))
; #define U2F(x) __uint_as_float(x)
; template <int MODE> DEV void hyena_conv_rows(const LAS unsigned char* lds, int slot0, float w0, float w1, float w2, float bs, cf (&z)[2][8], const cf (&y)[2][8], float hb, int tid) {
; #pragma unroll
;     for (int b = 0; b < 4; ++b) {
;         const LAS bf16_t* row = (const LAS bf16_t*)(lds + (slot0 + b) * 8192);
; #pragma unroll
;         for (int i = 0; i < 8; ++i) {
;             const int t = tid + 512 * i, par = tid & 1, d0 = (tid >> 1) + par;
;             const LAS unsigned* rw = (const LAS unsigned*)row + d0;
;             const unsigned dw0 = (i == 0) ? rw[d0 > 0 ? -1 : 0] : rw[256 * i - 1], dw1 = rw[256 * i];
;             float um = par ? U2F(dw0 << 16) : U2F(dw0 & 0xffff0000u);
;             const float u0 = par ? U2F(dw0 & 0xffff0000u) : U2F(dw1 << 16);
;             float up = par ? U2F(dw1 << 16) : U2F(dw1 & 0xffff0000u);
;             um = (t > 0) ? um : 0.f; up = (t < 4095) ? up : 0.f;
;             const float r = um * w0 + u0 * w1 + up * w2 + bs;
;             if (MODE == 0) { if (b & 1) z[b >> 1][i].y = r; else z[b >> 1][i].x = r; }
;             else { if (b & 1) z[b >> 1][i].y = r * (y[b >> 1][i].y + hb * z[b >> 1][i].y); else z[b >> 1][i].x = r * (y[b >> 1][i].x + hb * z[b >> 1][i].x); }
;         }
	v_and_b32_e32 v17, 0xffff0000, v118
	v_and_b32_e32 v19, 0xffff0000, v110
	v_lshlrev_b32_e32 v67, 16, v118
	v_lshlrev_b32_e32 v69, 16, v110
	v_cndmask_b32_e64 v69, v69, v19, s[38:39]
	v_cndmask_b32_e64 v67, v67, v17, s[38:39]
	v_pk_fma_f32 v[22:23], v[22:23], v[70:71], v[92:93] op_sel_hi:[1,0,1]
	v_cndmask_b32_e64 v93, 0, v67, s[60:61]
	v_cndmask_b32_e64 v92, 0, v69, s[60:61]
	v_lshlrev_b32_e32 v67, 16, v111
	v_lshlrev_b32_e32 v69, 16, v119
	v_pk_mul_f32 v[22:23], v[22:23], v[86:87]
	v_cndmask_b32_e64 v87, v17, v69, s[38:39]
	v_cndmask_b32_e64 v86, v19, v67, s[38:39]
	v_pk_mul_f32 v[86:87], v[66:67], v[86:87] op_sel_hi:[0,1]
	v_pk_fma_f32 v[92:93], v[18:19], v[92:93], v[86:87] op_sel_hi:[0,1,1]
	v_and_b32_e32 v17, 0xffff0000, v119
	v_and_b32_e32 v19, 0xffff0000, v111
	v_cndmask_b32_e64 v19, v67, v19, s[38:39]
	v_cndmask_b32_e64 v17, v69, v17, s[38:39]
	v_cndmask_b32_e64 v87, 0, v17, s[62:63]
	v_cndmask_b32_e64 v86, 0, v19, s[62:63]
	v_pk_fma_f32 v[92:93], v[16:17], v[86:87], v[92:93] op_sel_hi:[0,1,1]
	ds_read2_b32 v[86:87], v143 offset1:1
	v_pk_add_f32 v[92:93], v[68:69], v[92:93] op_sel_hi:[0,1]
	v_and_b32_e32 v19, 0xffff0000, v102
	v_lshlrev_b32_e32 v69, 16, v102
	v_cndmask_b32_e64 v69, v69, v19, s[38:39]
	s_waitcnt lgkmcnt(0)
	v_and_b32_e32 v17, 0xffff0000, v86
	v_lshlrev_b32_e32 v67, 16, v86
	v_cndmask_b32_e64 v67, v67, v17, s[38:39]
	v_cndmask_b32_e64 v101, 0, v67, s[64:65]
	v_cndmask_b32_e64 v100, 0, v69, s[64:65]
	v_lshlrev_b32_e32 v67, 16, v103
	v_lshlrev_b32_e32 v69, 16, v87
	v_cndmask_b32_e64 v107, v17, v69, s[38:39]
	v_cndmask_b32_e64 v106, v19, v67, s[38:39]
	v_pk_mul_f32 v[106:107], v[66:67], v[106:107] op_sel_hi:[0,1]
	v_pk_fma_f32 v[32:33], v[32:33], v[70:71], v[90:91] op_sel_hi:[1,0,1]
	v_pk_fma_f32 v[100:101], v[18:19], v[100:101], v[106:107] op_sel_hi:[0,1,1]
	v_and_b32_e32 v17, 0xffff0000, v87
	v_and_b32_e32 v19, 0xffff0000, v103
	v_pk_mul_f32 v[32:33], v[32:33], v[92:93]
	ds_read2_b32 v[84:85], v144 offset1:1
	ds_read2_b32 v[90:91], v145 offset1:1
	ds_read2_b32 v[92:93], v146 offset1:1
	v_cndmask_b32_e64 v19, v67, v19, s[38:39]
	v_cndmask_b32_e64 v17, v69, v17, s[38:39]
	v_cndmask_b32_e64 v87, 0, v17, s[66:67]
	v_cndmask_b32_e64 v86, 0, v19, s[66:67]
	v_pk_fma_f32 v[86:87], v[16:17], v[86:87], v[100:101] op_sel_hi:[0,1,1]
	v_pk_add_f32 v[86:87], v[68:69], v[86:87] op_sel_hi:[0,1]
	s_waitcnt lgkmcnt(2)
	v_and_b32_e32 v17, 0xffff0000, v84
	v_and_b32_e32 v19, 0xffff0000, v104
	v_lshlrev_b32_e32 v67, 16, v84
	v_lshlrev_b32_e32 v69, 16, v104
	v_cndmask_b32_e64 v69, v69, v19, s[38:39]
	v_cndmask_b32_e64 v67, v67, v17, s[38:39]
	v_pk_fma_f32 v[34:35], v[34:35], v[70:71], v[94:95] op_sel_hi:[1,0,1]
	v_cndmask_b32_e64 v95, 0, v67, s[68:69]
	v_cndmask_b32_e64 v94, 0, v69, s[68:69]
	v_lshlrev_b32_e32 v67, 16, v105
	v_lshlrev_b32_e32 v69, 16, v85
	v_pk_mul_f32 v[34:35], v[34:35], v[86:87]
	v_cndmask_b32_e64 v87, v17, v69, s[38:39]
	v_cndmask_b32_e64 v86, v19, v67, s[38:39]
	v_pk_mul_f32 v[86:87], v[66:67], v[86:87] op_sel_hi:[0,1]
	v_pk_fma_f32 v[94:95], v[18:19], v[94:95], v[86:87] op_sel_hi:[0,1,1]
	v_and_b32_e32 v17, 0xffff0000, v85
	v_and_b32_e32 v19, 0xffff0000, v105
	v_cndmask_b32_e64 v19, v67, v19, s[38:39]
	v_cndmask_b32_e64 v17, v69, v17, s[38:39]
	v_cndmask_b32_e64 v87, 0, v17, s[70:71]
	v_cndmask_b32_e64 v86, 0, v19, s[70:71]
	v_pk_fma_f32 v[94:95], v[16:17], v[86:87], v[94:95] op_sel_hi:[0,1,1]
	ds_read2st64_b32 v[86:87], v130 offset0:64 offset1:96
	v_pk_fma_f32 v[36:37], v[36:37], v[70:71], v[82:83] op_sel_hi:[1,0,1]
	ds_read2st64_b32 v[82:83], v129 offset0:64 offset1:96
	v_pk_add_f32 v[94:95], v[68:69], v[94:95] op_sel_hi:[0,1]
	v_pk_mul_f32 v[36:37], v[36:37], v[94:95]
	s_waitcnt lgkmcnt(1)
	v_and_b32_e32 v17, 0xffff0000, v87
	v_and_b32_e32 v19, 0xffff0000, v86
	v_lshlrev_b32_e32 v67, 16, v87
	v_lshlrev_b32_e32 v69, 16, v86
	v_cndmask_b32_e64 v69, v69, v19, s[38:39]
	v_cndmask_b32_e64 v67, v67, v17, s[38:39]
	v_cndmask_b32_e64 v95, 0, v67, s[40:41]
	v_cndmask_b32_e64 v94, 0, v69, s[40:41]
	s_waitcnt lgkmcnt(0)
	v_lshlrev_b32_e32 v67, 16, v82
	v_lshlrev_b32_e32 v69, 16, v83
	v_cndmask_b32_e64 v87, v17, v69, s[38:39]
	v_cndmask_b32_e64 v86, v19, v67, s[38:39]
	v_pk_mul_f32 v[86:87], v[66:67], v[86:87] op_sel_hi:[0,1]
	v_pk_fma_f32 v[94:95], v[18:19], v[94:95], v[86:87] op_sel_hi:[0,1,1]
	v_and_b32_e32 v17, 0xffff0000, v83
	v_and_b32_e32 v19, 0xffff0000, v82
	v_cndmask_b32_e64 v19, v67, v19, s[38:39]
	v_cndmask_b32_e64 v17, v69, v17, s[38:39]
	v_cndmask_b32_e64 v83, 0, v17, s[42:43]
	v_cndmask_b32_e64 v82, 0, v19, s[42:43]
	v_pk_fma_f32 v[82:83], v[16:17], v[82:83], v[94:95] op_sel_hi:[0,1,1]
	ds_read2_b32 v[86:87], v152 offset1:1
	v_pk_add_f32 v[82:83], v[68:69], v[82:83] op_sel_hi:[0,1]
	v_and_b32_e32 v19, 0xffff0000, v90
	v_lshlrev_b32_e32 v69, 16, v90
	v_cndmask_b32_e64 v69, v69, v19, s[38:39]
	s_waitcnt lgkmcnt(0)
	v_and_b32_e32 v17, 0xffff0000, v86
	v_lshlrev_b32_e32 v67, 16, v86
	v_cndmask_b32_e64 v67, v67, v17, s[38:39]
	v_cndmask_b32_e64 v85, 0, v67, s[44:45]
	v_cndmask_b32_e64 v84, 0, v69, s[44:45]
	v_lshlrev_b32_e32 v67, 16, v91
	v_lshlrev_b32_e32 v69, 16, v87
	v_cndmask_b32_e64 v101, v17, v69, s[38:39]
	v_cndmask_b32_e64 v100, v19, v67, s[38:39]
	v_pk_mul_f32 v[100:101], v[66:67], v[100:101] op_sel_hi:[0,1]
	v_pk_fma_f32 v[38:39], v[38:39], v[70:71], v[96:97] op_sel_hi:[1,0,1]
	v_pk_fma_f32 v[84:85], v[18:19], v[84:85], v[100:101] op_sel_hi:[0,1,1]
	v_and_b32_e32 v17, 0xffff0000, v87
	v_and_b32_e32 v19, 0xffff0000, v91
	v_pk_mul_f32 v[38:39], v[38:39], v[82:83]
	ds_read2_b32 v[82:83], v153 offset1:1
	ds_read2_b32 v[94:95], v154 offset1:1
	ds_read2_b32 v[96:97], v151 offset1:1
	v_cndmask_b32_e64 v19, v67, v19, s[38:39]
	v_cndmask_b32_e64 v17, v69, v17, s[38:39]
	v_cndmask_b32_e64 v87, 0, v17, s[46:47]
	v_cndmask_b32_e64 v86, 0, v19, s[46:47]
	v_pk_fma_f32 v[86:87], v[16:17], v[86:87], v[84:85] op_sel_hi:[0,1,1]
	v_pk_add_f32 v[86:87], v[68:69], v[86:87] op_sel_hi:[0,1]
	s_waitcnt lgkmcnt(2)
; #define LAS __attribute__((address_space(3)))
; #define U2F(x) __uint_as_float(x)
; template <int MODE> DEV void hyena_conv_rows(const LAS unsigned char* lds, int slot0, float w0, float w1, float w2, float bs, cf (&z)[2][8], const cf (&y)[2][8], float hb, int tid) {
; #pragma unroll
;     for (int b = 0; b < 4; ++b) {
;         const LAS bf16_t* row = (const LAS bf16_t*)(lds + (slot0 + b) * 8192);
; #pragma unroll
;         for (int i = 0; i < 8; ++i) {
;             const int t = tid + 512 * i, par = tid & 1, d0 = (tid >> 1) + par;
;             const LAS unsigned* rw = (const LAS unsigned*)row + d0;
;             const unsigned dw0 = (i == 0) ? rw[d0 > 0 ? -1 : 0] : rw[256 * i - 1], dw1 = rw[256 * i];
;             float um = par ? U2F(dw0 << 16) : U2F(dw0 & 0xffff0000u);
;             const float u0 = par ? U2F(dw0 & 0xffff0000u) : U2F(dw1 << 16);
;             float up = par ? U2F(dw1 << 16) : U2F(dw1 & 0xffff0000u);
;             um = (t > 0) ? um : 0.f; up = (t < 4095) ? up : 0.f;
;             const float r = um * w0 + u0 * w1 + up * w2 + bs;
;             if (MODE == 0) { if (b & 1) z[b >> 1][i].y = r; else z[b >> 1][i].x = r; }
;             else { if (b & 1) z[b >> 1][i].y = r * (y[b >> 1][i].y + hb * z[b >> 1][i].y); else z[b >> 1][i].x = r * (y[b >> 1][i].x + hb * z[b >> 1][i].x); }
;         }
	v_and_b32_e32 v17, 0xffff0000, v82
	v_and_b32_e32 v19, 0xffff0000, v92
	v_lshlrev_b32_e32 v67, 16, v82
	v_lshlrev_b32_e32 v69, 16, v92
	v_pk_fma_f32 v[42:43], v[42:43], v[70:71], v[88:89] op_sel_hi:[1,0,1]
	v_cndmask_b32_e64 v69, v69, v19, s[38:39]
	v_cndmask_b32_e64 v67, v67, v17, s[38:39]
	v_pk_mul_f32 v[42:43], v[42:43], v[86:87]
	v_cndmask_b32_e64 v87, 0, v67, s[48:49]
	v_cndmask_b32_e64 v86, 0, v69, s[48:49]
	v_lshlrev_b32_e32 v67, 16, v93
	v_lshlrev_b32_e32 v69, 16, v83
	v_cndmask_b32_e64 v89, v17, v69, s[38:39]
	v_cndmask_b32_e64 v88, v19, v67, s[38:39]
	v_pk_mul_f32 v[88:89], v[66:67], v[88:89] op_sel_hi:[0,1]
	v_pk_fma_f32 v[86:87], v[18:19], v[86:87], v[88:89] op_sel_hi:[0,1,1]
	v_and_b32_e32 v17, 0xffff0000, v83
	v_and_b32_e32 v19, 0xffff0000, v93
	v_cndmask_b32_e64 v19, v67, v19, s[38:39]
	v_cndmask_b32_e64 v17, v69, v17, s[38:39]
	v_cndmask_b32_e64 v83, 0, v17, s[50:51]
	v_cndmask_b32_e64 v82, 0, v19, s[50:51]
	v_pk_fma_f32 v[82:83], v[16:17], v[82:83], v[86:87] op_sel_hi:[0,1,1]
	v_pk_add_f32 v[82:83], v[68:69], v[82:83] op_sel_hi:[0,1]
	v_pk_fma_f32 v[44:45], v[44:45], v[70:71], v[98:99] op_sel_hi:[1,0,1]
	s_waitcnt lgkmcnt(1)
	v_and_b32_e32 v17, 0xffff0000, v94
	v_pk_mul_f32 v[44:45], v[44:45], v[82:83]
	ds_read2_b32 v[82:83], v147 offset1:1
	v_lshlrev_b32_e32 v67, 16, v94
	v_cndmask_b32_e64 v67, v67, v17, s[38:39]
	v_cndmask_b32_e64 v91, 0, v67, s[52:53]
	ds_read2_b32 v[84:85], v148 offset1:1
	ds_read2_b32 v[86:87], v149 offset1:1
	ds_read2_b32 v[88:89], v150 offset1:1
	s_waitcnt lgkmcnt(3)
	v_and_b32_e32 v19, 0xffff0000, v82
	v_lshlrev_b32_e32 v69, 16, v82
	v_cndmask_b32_e64 v69, v69, v19, s[38:39]
	v_cndmask_b32_e64 v90, 0, v69, s[52:53]
	v_lshlrev_b32_e32 v67, 16, v83
	v_lshlrev_b32_e32 v69, 16, v95
	v_cndmask_b32_e64 v93, v17, v69, s[38:39]
	v_cndmask_b32_e64 v92, v19, v67, s[38:39]
	v_pk_mul_f32 v[92:93], v[66:67], v[92:93] op_sel_hi:[0,1]
	v_pk_fma_f32 v[50:51], v[50:51], v[70:71], v[80:81] op_sel_hi:[1,0,1]
	ds_read2_b32 v[80:81], v155 offset1:1
	v_pk_fma_f32 v[90:91], v[18:19], v[90:91], v[92:93] op_sel_hi:[0,1,1]
	v_and_b32_e32 v17, 0xffff0000, v95
	v_and_b32_e32 v19, 0xffff0000, v83
	v_cndmask_b32_e64 v19, v67, v19, s[38:39]
	v_cndmask_b32_e64 v17, v69, v17, s[38:39]
	v_cndmask_b32_e64 v83, 0, v17, s[54:55]
	v_cndmask_b32_e64 v82, 0, v19, s[54:55]
	v_pk_fma_f32 v[82:83], v[16:17], v[82:83], v[90:91] op_sel_hi:[0,1,1]
	v_pk_add_f32 v[82:83], v[68:69], v[82:83] op_sel_hi:[0,1]
	s_waitcnt lgkmcnt(0)
	v_and_b32_e32 v17, 0xffff0000, v80
	v_and_b32_e32 v19, 0xffff0000, v84
	v_lshlrev_b32_e32 v67, 16, v80
	v_lshlrev_b32_e32 v69, 16, v84
	v_cndmask_b32_e64 v69, v69, v19, s[38:39]
	v_cndmask_b32_e64 v67, v67, v17, s[38:39]
	v_cndmask_b32_e64 v95, 0, v67, s[56:57]
	v_cndmask_b32_e64 v94, 0, v69, s[56:57]
	v_lshlrev_b32_e32 v67, 16, v85
	v_lshlrev_b32_e32 v69, 16, v81
	v_cndmask_b32_e64 v99, v17, v69, s[38:39]
	v_cndmask_b32_e64 v98, v19, v67, s[38:39]
	v_pk_mul_f32 v[98:99], v[66:67], v[98:99] op_sel_hi:[0,1]
	v_pk_fma_f32 v[94:95], v[18:19], v[94:95], v[98:99] op_sel_hi:[0,1,1]
	v_and_b32_e32 v17, 0xffff0000, v81
	v_and_b32_e32 v19, 0xffff0000, v85
	v_pk_mul_f32 v[50:51], v[50:51], v[82:83]
	ds_read2_b32 v[82:83], v156 offset1:1
	ds_read2_b32 v[90:91], v157 offset1:1
	ds_read2_b32 v[92:93], v158 offset1:1
	v_cndmask_b32_e64 v19, v67, v19, s[38:39]
	v_cndmask_b32_e64 v17, v69, v17, s[38:39]
	v_cndmask_b32_e64 v81, 0, v17, s[58:59]
	v_cndmask_b32_e64 v80, 0, v19, s[58:59]
	v_pk_fma_f32 v[80:81], v[16:17], v[80:81], v[94:95] op_sel_hi:[0,1,1]
	v_pk_add_f32 v[80:81], v[68:69], v[80:81] op_sel_hi:[0,1]
	s_waitcnt lgkmcnt(2)
	v_and_b32_e32 v17, 0xffff0000, v82
	v_and_b32_e32 v19, 0xffff0000, v86
	v_lshlrev_b32_e32 v67, 16, v82
	v_lshlrev_b32_e32 v69, 16, v86
	v_cndmask_b32_e64 v69, v69, v19, s[38:39]
	v_cndmask_b32_e64 v67, v67, v17, s[38:39]
	v_pk_fma_f32 v[46:47], v[46:47], v[70:71], v[78:79] op_sel_hi:[1,0,1]
	v_cndmask_b32_e64 v79, 0, v67, s[60:61]
	v_cndmask_b32_e64 v78, 0, v69, s[60:61]
	v_lshlrev_b32_e32 v67, 16, v87
	v_lshlrev_b32_e32 v69, 16, v83
	v_pk_mul_f32 v[46:47], v[46:47], v[80:81]
	v_cndmask_b32_e64 v81, v17, v69, s[38:39]
	v_cndmask_b32_e64 v80, v19, v67, s[38:39]
	v_pk_mul_f32 v[80:81], v[66:67], v[80:81] op_sel_hi:[0,1]
	v_pk_fma_f32 v[78:79], v[18:19], v[78:79], v[80:81] op_sel_hi:[0,1,1]
	v_and_b32_e32 v17, 0xffff0000, v83
	v_and_b32_e32 v19, 0xffff0000, v87
	v_cndmask_b32_e64 v19, v67, v19, s[38:39]
	v_cndmask_b32_e64 v17, v69, v17, s[38:39]
	v_cndmask_b32_e64 v81, 0, v17, s[62:63]
	v_cndmask_b32_e64 v80, 0, v19, s[62:63]
	v_pk_fma_f32 v[78:79], v[16:17], v[80:81], v[78:79] op_sel_hi:[0,1,1]
	v_pk_add_f32 v[78:79], v[68:69], v[78:79] op_sel_hi:[0,1]
	s_waitcnt lgkmcnt(1)
	v_and_b32_e32 v17, 0xffff0000, v90
	v_and_b32_e32 v19, 0xffff0000, v88
	v_lshlrev_b32_e32 v67, 16, v90
	v_lshlrev_b32_e32 v69, 16, v88
	v_cndmask_b32_e64 v69, v69, v19, s[38:39]
	v_cndmask_b32_e64 v67, v67, v17, s[38:39]
	v_pk_fma_f32 v[48:49], v[48:49], v[70:71], v[76:77] op_sel_hi:[1,0,1]
	v_cndmask_b32_e64 v77, 0, v67, s[64:65]
	v_cndmask_b32_e64 v76, 0, v69, s[64:65]
	v_lshlrev_b32_e32 v67, 16, v89
	v_lshlrev_b32_e32 v69, 16, v91
	v_pk_mul_f32 v[48:49], v[48:49], v[78:79]
	v_cndmask_b32_e64 v79, v17, v69, s[38:39]
	v_cndmask_b32_e64 v78, v19, v67, s[38:39]
	v_pk_mul_f32 v[78:79], v[66:67], v[78:79] op_sel_hi:[0,1]
	v_pk_fma_f32 v[76:77], v[18:19], v[76:77], v[78:79] op_sel_hi:[0,1,1]
	v_and_b32_e32 v17, 0xffff0000, v91
	v_and_b32_e32 v19, 0xffff0000, v89
	v_cndmask_b32_e64 v19, v67, v19, s[38:39]
	v_cndmask_b32_e64 v17, v69, v17, s[38:39]
	v_cndmask_b32_e64 v79, 0, v17, s[66:67]
	v_cndmask_b32_e64 v78, 0, v19, s[66:67]
	v_pk_fma_f32 v[76:77], v[16:17], v[78:79], v[76:77] op_sel_hi:[0,1,1]
	v_pk_add_f32 v[76:77], v[68:69], v[76:77] op_sel_hi:[0,1]
	v_and_b32_e32 v19, 0xffff0000, v96
	v_lshlrev_b32_e32 v69, 16, v96
	v_cndmask_b32_e64 v69, v69, v19, s[38:39]
	v_pk_fma_f32 v[52:53], v[52:53], v[70:71], v[74:75] op_sel_hi:[1,0,1]
	s_waitcnt lgkmcnt(0)
; #define U2F(x) __uint_as_float(x)
; template <int R, bool INV> DEV void dft_regs(cf (&v)[R]) {
; #pragma unroll
;     for (int s = R; s >= 2; s >>= 1) {
;         const int h = s >> 1;
; #pragma unroll
;         for (int b = 0; b < R; b += s) {
; #pragma unroll
;             for (int k = 0; k < h; ++k) {
;                 const cf a = v[b + k], c = v[b + k + h];
;                 v[b + k] = a + c;
;                 const cf d = a - c;
;                 const int m = k * (32 / s);
;                 const float wr = tw_cos(m), wi = INV ? tw_sin(m) : -tw_sin(m);
;                 v[b + k + h] = cf{d.x * wr - d.y * wi, d.x * wi + d.y * wr};
;             }
;         }
;     }
; }
; template <int MODE> DEV void hyena_conv_rows(const LAS unsigned char* lds, int slot0, float w0, float w1, float w2, float bs, cf (&z)[2][8], const cf (&y)[2][8], float hb, int tid) {
;     ...
;             const unsigned dw0 = (i == 0) ? rw[d0 > 0 ? -1 : 0] : rw[256 * i - 1], dw1 = rw[256 * i];
;             float um = par ? U2F(dw0 << 16) : U2F(dw0 & 0xffff0000u);
;             const float u0 = par ? U2F(dw0 & 0xffff0000u) : U2F(dw1 << 16);
;             float up = par ? U2F(dw1 << 16) : U2F(dw1 & 0xffff0000u);
;             um = (t > 0) ? um : 0.f; up = (t < 4095) ? up : 0.f;
;             const float r = um * w0 + u0 * w1 + up * w2 + bs;
;             if (MODE == 0) { if (b & 1) z[b >> 1][i].y = r; else z[b >> 1][i].x = r; }
;             else { if (b & 1) z[b >> 1][i].y = r * (y[b >> 1][i].y + hb * z[b >> 1][i].y); else z[b >> 1][i].x = r * (y[b >> 1][i].x + hb * z[b >> 1][i].x); }
	v_and_b32_e32 v17, 0xffff0000, v92
	v_lshlrev_b32_e32 v67, 16, v92
	v_cndmask_b32_e64 v74, 0, v69, s[68:69]
	v_lshlrev_b32_e32 v69, 16, v97
	v_lshlrev_b32_e32 v71, 16, v93
	v_pk_mul_f32 v[52:53], v[52:53], v[76:77]
	v_cndmask_b32_e64 v67, v67, v17, s[38:39]
	v_cndmask_b32_e64 v77, v17, v71, s[38:39]
	v_cndmask_b32_e64 v76, v19, v69, s[38:39]
	v_cndmask_b32_e64 v75, 0, v67, s[68:69]
	v_pk_mul_f32 v[66:67], v[66:67], v[76:77] op_sel_hi:[0,1]
	v_pk_fma_f32 v[18:19], v[18:19], v[74:75], v[66:67] op_sel_hi:[0,1,1]
	v_and_b32_e32 v17, 0xffff0000, v93
	v_and_b32_e32 v66, 0xffff0000, v97
	v_cndmask_b32_e64 v66, v69, v66, s[38:39]
	v_cndmask_b32_e64 v17, v71, v17, s[38:39]
	v_cndmask_b32_e64 v67, 0, v17, s[70:71]
	v_cndmask_b32_e64 v66, 0, v66, s[70:71]
	v_pk_add_f32 v[72:73], v[126:127], v[166:167]
	v_pk_fma_f32 v[16:17], v[16:17], v[66:67], v[18:19] op_sel_hi:[0,1,1]
	v_pk_add_f32 v[16:17], v[68:69], v[16:17] op_sel_hi:[0,1]
	v_pk_fma_f32 v[18:19], v[40:41], v[70:71], v[72:73] op_sel_hi:[1,0,1]
	s_mov_b64 s[22:23], 0
	v_pk_mul_f32 v[40:41], v[18:19], v[16:17]
	s_and_b64 vcc, exec, s[2:3]
	s_barrier
	s_cbranch_vccnz .LBB0_522
.LBB0_519:
	v_pk_mul_f32 v[16:17], v[26:27], s[16:17] op_sel_hi:[1,0]
	v_pk_add_f32 v[0:1], v[24:25], 0 op_sel_hi:[1,0]
	v_pk_fma_f32 v[18:19], v[26:27], s[84:85], v[16:17] op_sel:[0,0,1] op_sel_hi:[1,0,0] neg_hi:[0,0,1]
	v_pk_add_f32 v[16:17], v[22:23], 0 op_sel_hi:[1,0]
	v_mov_b32_e32 v4, v24
	v_mov_b32_e32 v5, v25
	v_pk_add_f32 v[80:81], v[0:1], v[16:17]
	v_pk_add_f32 v[0:1], v[0:1], v[16:17] neg_lo:[0,1] neg_hi:[0,1]
	v_pk_fma_f32 v[66:67], v[22:23], 0, v[22:23] op_sel:[0,0,1] op_sel_hi:[1,0,0] neg_hi:[0,0,1]
	v_mov_b32_e32 v5, v25
	v_pk_add_f32 v[2:3], v[30:31], 0 op_sel_hi:[1,0]
	v_pk_mul_f32 v[6:7], v[30:31], s[84:85] op_sel_hi:[1,0]
	v_pk_add_f32 v[68:69], v[32:33], 0 op_sel_hi:[1,0]
	v_pk_fma_f32 v[8:9], v[30:31], s[16:17], v[6:7] op_sel:[0,0,1] op_sel_hi:[1,0,0] neg_hi:[0,0,1]
	v_pk_add_f32 v[82:83], v[2:3], v[68:69]
	v_pk_add_f32 v[2:3], v[2:3], v[68:69] neg_lo:[0,1] neg_hi:[0,1]
	v_pk_add_f32 v[6:7], v[28:29], 0 op_sel_hi:[1,0]
	v_pk_add_f32 v[72:73], v[34:35], 0 op_sel_hi:[1,0]
	v_pk_mul_f32 v[16:17], v[2:3], s[18:19] op_sel_hi:[1,0]
	v_pk_mul_f32 v[10:11], v[28:29], s[18:19] op_sel_hi:[1,0]
	v_pk_fma_f32 v[68:69], v[2:3], s[18:19], v[16:17] op_sel:[0,0,1] op_sel_hi:[1,0,0]
	v_pk_fma_f32 v[2:3], v[2:3], s[18:19], v[16:17] op_sel_hi:[1,0,0] neg_lo:[0,0,1] neg_hi:[0,0,1]
	v_pk_add_f32 v[16:17], v[6:7], v[72:73]
	v_pk_add_f32 v[6:7], v[6:7], v[72:73] neg_lo:[0,1] neg_hi:[0,1]
	v_pk_add_f32 v[14:15], v[26:27], 0 op_sel_hi:[1,0]
	v_pk_add_f32 v[76:77], v[36:37], 0 op_sel_hi:[1,0]
	v_pk_fma_f32 v[12:13], v[28:29], s[18:19], v[10:11] op_sel:[0,0,1] op_sel_hi:[1,0,0]
	v_pk_fma_f32 v[10:11], v[28:29], s[18:19], v[10:11] op_sel_hi:[1,0,0] neg_lo:[0,0,1] neg_hi:[0,0,1]
	v_pk_add_f32 v[72:73], v[14:15], v[76:77]
	v_pk_add_f32 v[14:15], v[14:15], v[76:77] neg_lo:[0,1] neg_hi:[0,1]
	v_pk_add_f32 v[76:77], v[4:5], v[66:67]
	v_pk_add_f32 v[4:5], v[4:5], v[66:67] neg_lo:[0,1] neg_hi:[0,1]
	v_mov_b32_e32 v10, v33
	s_mov_b32 s30, s85
	s_mov_b32 s31, s0
	v_pk_mul_f32 v[70:71], v[32:33], s[84:85] op_sel_hi:[0,1]
	v_pk_fma_f32 v[70:71], v[10:11], s[30:31], v[70:71] op_sel_hi:[0,1,1] neg_lo:[0,0,1] neg_hi:[0,0,1]
	v_mul_f32_e32 v10, 0x3f3504f3, v34
	v_mov_b32_e32 v74, v35
	s_mov_b32 s28, s97
	s_mov_b32 s29, s96
	s_mov_b32 s24, s85
	s_mov_b32 s25, s84
	v_pk_add_f32 v[84:85], v[8:9], v[70:71]
	v_pk_add_f32 v[8:9], v[8:9], v[70:71] neg_lo:[0,1] neg_hi:[0,1]
	v_pk_fma_f32 v[74:75], v[74:75], s[28:29], v[10:11] op_sel_hi:[0,1,0] neg_lo:[0,0,1] neg_hi:[0,0,1]
	v_mov_b32_e32 v10, v37
	s_mov_b32 s34, s84
	s_mov_b32 s35, s88
	v_pk_mul_f32 v[78:79], v[36:37], s[24:25] op_sel_hi:[0,1]
	v_pk_mul_f32 v[66:67], v[8:9], s[18:19] op_sel_hi:[1,0]
	v_mov_b32_e32 v13, v11
	v_pk_fma_f32 v[78:79], v[10:11], s[34:35], v[78:79] op_sel_hi:[0,1,1] neg_lo:[0,0,1] neg_hi:[0,0,1]
	v_pk_fma_f32 v[70:71], v[8:9], s[18:19], v[66:67] op_sel:[0,0,1] op_sel_hi:[1,0,0] neg_hi:[0,0,1]
	v_pk_add_f32 v[10:11], v[12:13], v[74:75] neg_lo:[0,1] neg_hi:[0,1]
	v_pk_add_f32 v[66:67], v[80:81], v[16:17]
	v_pk_add_f32 v[16:17], v[80:81], v[16:17] neg_lo:[0,1] neg_hi:[0,1]
	v_pk_add_f32 v[8:9], v[12:13], v[74:75]
	v_pk_add_f32 v[12:13], v[18:19], v[78:79]
	v_pk_add_f32 v[18:19], v[18:19], v[78:79] neg_lo:[0,1] neg_hi:[0,1]
	v_mul_f32_e32 v2, 0x3f3504f3, v14
	v_pk_add_f32 v[78:79], v[82:83], v[72:73]
	v_pk_add_f32 v[82:83], v[82:83], v[72:73] neg_lo:[0,1] neg_hi:[0,1]
	v_pk_add_f32 v[74:75], v[0:1], v[6:7] op_sel:[0,1] op_sel_hi:[1,0] neg_hi:[0,1]
	v_pk_fma_f32 v[14:15], v[14:15], s[28:29], v[2:3] op_sel:[1,0,0] op_sel_hi:[1,1,0] neg_lo:[0,0,1] neg_hi:[0,0,1]
	v_pk_add_f32 v[72:73], v[0:1], v[6:7] op_sel:[0,1] op_sel_hi:[1,0] neg_lo:[0,1]
	v_mov_b32_e32 v69, v3
	v_mul_f32_e32 v2, 0x3f3504f3, v18
	v_mov_b32_e32 v80, v72
	v_mov_b32_e32 v81, v73
	v_pk_fma_f32 v[18:19], v[18:19], s[28:29], v[2:3] op_sel:[1,0,0] op_sel_hi:[1,1,0] neg_lo:[0,0,1] neg_hi:[0,0,1]
	v_pk_add_f32 v[0:1], v[68:69], v[14:15] neg_lo:[0,1] neg_hi:[0,1]
	v_pk_add_f32 v[2:3], v[68:69], v[14:15]
	v_pk_add_f32 v[14:15], v[0:1], 0 op_sel:[1,0] op_sel_hi:[0,0] neg_hi:[1,0]
	v_pk_add_f32 v[6:7], v[76:77], v[8:9]
	v_pk_add_f32 v[0:1], v[76:77], v[8:9] neg_lo:[0,1] neg_hi:[0,1]
	v_pk_add_f32 v[86:87], v[4:5], v[10:11] op_sel:[0,1] op_sel_hi:[1,0] neg_hi:[0,1]
	v_pk_add_f32 v[68:69], v[66:67], v[78:79]
	v_pk_add_f32 v[8:9], v[84:85], v[12:13]
	v_pk_add_f32 v[72:73], v[84:85], v[12:13] neg_lo:[0,1] neg_hi:[0,1]
	v_pk_add_f32 v[88:89], v[70:71], v[18:19]
	v_pk_add_f32 v[76:77], v[6:7], v[8:9]
; #define LAS __attribute__((address_space(3)))
; #define OPAQUE_I(x) asm volatile("" : "+v"(x))
; template <int R, bool INV> DEV void dft_regs(cf (&v)[R]) {
; #pragma unroll
;     for (int s = R; s >= 2; s >>= 1) {
;         const int h = s >> 1;
; #pragma unroll
;         for (int b = 0; b < R; b += s) {
; #pragma unroll
;             for (int k = 0; k < h; ++k) {
;                 const cf a = v[b + k], c = v[b + k + h];
;                 v[b + k] = a + c;
;                 const cf d = a - c;
;                 const int m = k * (32 / s);
;                 const float wr = tw_cos(m), wi = INV ? tw_sin(m) : -tw_sin(m);
;                 v[b + k + h] = cf{d.x * wr - d.y * wi, d.x * wi + d.y * wr};
;             }
;         }
;     }
; }
; DEV void fft_f1x2(LAS cf* buf0, LAS cf* buf1, const cf (&z0)[8], const cf (&z1)[8], int tid) {
;     OPAQUE_I(tid);
;     cf v[16], u[16];
; #pragma unroll
;     for (int q = 0; q < 8; ++q) { v[q] = z0[q]; v[q + 8] = cf{0.f, 0.f}; u[q] = z1[q]; u[q + 8] = cf{0.f, 0.f}; }
;     dft_regs<16, false>(v); dft_regs<16, false>(u);
	v_pk_add_f32 v[12:13], v[4:5], v[10:11] op_sel:[0,1] op_sel_hi:[1,0] neg_lo:[0,1]
	v_pk_add_f32 v[8:9], v[6:7], v[8:9] neg_lo:[0,1] neg_hi:[0,1]
	v_pk_add_f32 v[6:7], v[0:1], v[72:73] op_sel:[0,1] op_sel_hi:[1,0] neg_hi:[0,1]
	v_mov_b32_e32 v4, v12
	v_mov_b32_e32 v5, v13
	v_pk_add_f32 v[10:11], v[0:1], v[72:73] op_sel:[0,1] op_sel_hi:[1,0] neg_lo:[0,1]
	v_pk_add_f32 v[0:1], v[70:71], v[18:19] neg_lo:[0,1] neg_hi:[0,1]
	v_pk_add_f32 v[70:71], v[74:75], v[2:3]
	v_pk_add_f32 v[90:91], v[0:1], 0 op_sel:[1,0] op_sel_hi:[0,0] neg_hi:[1,0]
	v_pk_add_f32 v[2:3], v[74:75], v[2:3] neg_lo:[0,1] neg_hi:[0,1]
	v_pk_add_f32 v[0:1], v[66:67], v[78:79] neg_lo:[0,1] neg_hi:[0,1]
	v_pk_add_f32 v[78:79], v[16:17], v[82:83] op_sel:[0,1] op_sel_hi:[1,0] neg_hi:[0,1]
	v_pk_add_f32 v[72:73], v[16:17], v[82:83] op_sel:[0,1] op_sel_hi:[1,0] neg_lo:[0,1]
	v_mov_b32_e32 v84, v0
	v_mov_b32_e32 v85, v1
	v_mov_b32_e32 v0, v72
	v_mov_b32_e32 v1, v73
	v_mov_b32_e32 v72, v2
	v_mov_b32_e32 v73, v3
	v_pk_add_f32 v[12:13], v[80:81], v[14:15] neg_lo:[0,1] neg_hi:[0,1]
	v_pk_add_f32 v[18:19], v[80:81], v[14:15]
	v_mov_b32_e32 v2, v12
	v_mov_b32_e32 v3, v13
	v_mov_b32_e32 v12, v8
	v_mov_b32_e32 v13, v9
	v_mov_b32_e32 v8, v10
	v_mov_b32_e32 v9, v11
	v_pk_mul_f32 v[92:93], v[50:51], s[16:17] op_sel_hi:[1,0]
	v_pk_add_f32 v[10:11], v[86:87], v[88:89] neg_lo:[0,1] neg_hi:[0,1]
	v_pk_fma_f32 v[94:95], v[50:51], s[84:85], v[92:93] op_sel:[0,0,1] op_sel_hi:[1,0,0] neg_hi:[0,0,1]
	v_mov_b32_e32 v14, v10
	v_mov_b32_e32 v15, v11
	v_pk_add_f32 v[66:67], v[4:5], v[90:91] neg_lo:[0,1] neg_hi:[0,1]
	v_mov_b32_e32 v10, v66
	v_mov_b32_e32 v11, v67
	v_pk_add_f32 v[92:93], v[46:47], 0 op_sel_hi:[1,0]
	v_pk_add_f32 v[66:67], v[38:39], 0 op_sel_hi:[1,0]
	v_mov_b32_e32 v108, v41
	v_pk_mul_f32 v[110:111], v[40:41], s[24:25] op_sel_hi:[0,1]
	v_pk_fma_f32 v[108:109], v[108:109], s[34:35], v[110:111] op_sel_hi:[0,1,1] neg_lo:[0,0,1] neg_hi:[0,0,1]
	v_pk_add_f32 v[110:111], v[66:67], v[92:93]
	v_pk_add_f32 v[66:67], v[66:67], v[92:93] neg_lo:[0,1] neg_hi:[0,1]
	v_mov_b32_e32 v82, v38
	v_mov_b32_e32 v83, v39
	v_pk_fma_f32 v[96:97], v[46:47], 0, v[46:47] op_sel:[0,0,1] op_sel_hi:[1,0,0] neg_hi:[0,0,1]
	v_mov_b32_e32 v83, v39
	v_pk_add_f32 v[80:81], v[42:43], 0 op_sel_hi:[1,0]
	v_pk_add_f32 v[98:99], v[48:49], 0 op_sel_hi:[1,0]
	v_mov_b32_e32 v112, v66
	v_mov_b32_e32 v113, v67
	v_pk_add_f32 v[74:75], v[4:5], v[90:91]
	v_pk_mul_f32 v[4:5], v[42:43], s[84:85] op_sel_hi:[1,0]
	v_pk_add_f32 v[66:67], v[80:81], v[98:99]
	v_pk_add_f32 v[80:81], v[80:81], v[98:99] neg_lo:[0,1] neg_hi:[0,1]
	v_pk_add_f32 v[16:17], v[86:87], v[88:89]
	v_pk_fma_f32 v[86:87], v[42:43], s[16:17], v[4:5] op_sel:[0,0,1] op_sel_hi:[1,0,0] neg_hi:[0,0,1]
	v_mov_b32_e32 v100, v49
	v_pk_mul_f32 v[102:103], v[48:49], s[84:85] op_sel_hi:[0,1]
	v_pk_mul_f32 v[92:93], v[80:81], s[18:19] op_sel_hi:[1,0]
	v_pk_add_f32 v[4:5], v[44:45], 0 op_sel_hi:[1,0]
	v_pk_mul_f32 v[88:89], v[44:45], s[18:19] op_sel_hi:[1,0]
	v_pk_fma_f32 v[100:101], v[100:101], s[30:31], v[102:103] op_sel_hi:[0,1,1] neg_lo:[0,0,1] neg_hi:[0,0,1]
	v_pk_add_f32 v[102:103], v[52:53], 0 op_sel_hi:[1,0]
	v_pk_fma_f32 v[98:99], v[80:81], s[18:19], v[92:93] op_sel:[0,0,1] op_sel_hi:[1,0,0] neg_hi:[0,0,1]
	v_pk_fma_f32 v[90:91], v[44:45], s[18:19], v[88:89] op_sel:[0,0,1] op_sel_hi:[1,0,0] neg_hi:[0,0,1]
	v_mul_f32_e32 v104, 0x3f3504f3, v52
	v_mov_b32_e32 v106, v53
	v_pk_add_f32 v[80:81], v[4:5], v[102:103]
	v_pk_add_f32 v[4:5], v[4:5], v[102:103] neg_lo:[0,1] neg_hi:[0,1]
	v_pk_add_f32 v[88:89], v[50:51], 0 op_sel_hi:[1,0]
	v_pk_fma_f32 v[104:105], v[106:107], s[28:29], v[104:105] op_sel_hi:[0,1,0] neg_lo:[0,0,1] neg_hi:[0,0,1]
	v_pk_add_f32 v[106:107], v[40:41], 0 op_sel_hi:[1,0]
	v_mov_b32_e32 v114, v21
	v_pk_add_f32 v[92:93], v[88:89], v[106:107]
	v_pk_add_f32 v[88:89], v[88:89], v[106:107] neg_lo:[0,1] neg_hi:[0,1]
	s_mov_b32 s2, s86
	v_mul_f32_e32 v102, 0x3f3504f3, v88
	v_pk_fma_f32 v[88:89], v[88:89], s[28:29], v[102:103] op_sel:[1,0,0] op_sel_hi:[1,1,0] neg_lo:[0,0,1] neg_hi:[0,0,1]
	v_pk_add_f32 v[102:103], v[82:83], v[96:97]
	v_pk_add_f32 v[82:83], v[82:83], v[96:97] neg_lo:[0,1] neg_hi:[0,1]
	s_mov_b32 s3, s4
	s_mov_b32 s10, s4
	s_mov_b32 s6, s94
	v_pk_add_f32 v[106:107], v[86:87], v[100:101]
	v_pk_add_f32 v[86:87], v[86:87], v[100:101] neg_lo:[0,1] neg_hi:[0,1]
	s_mov_b32 s7, s82
	v_pk_mul_f32 v[96:97], v[86:87], s[18:19] op_sel_hi:[1,0]
	s_mov_b32 s8, s82
	v_pk_fma_f32 v[100:101], v[86:87], s[18:19], v[96:97] op_sel:[0,0,1] op_sel_hi:[1,0,0] neg_hi:[0,0,1]
	s_lshl_b32 s92, s19, 13
	v_lshl_add_u64 v[232:233], s[92:93], 2, v[54:55]
	global_load_dwordx4 v[170:173], v[232:233], off offset:48
	global_load_dwordx4 v[174:177], v[232:233], off offset:32
	global_load_dwordx4 v[178:181], v[232:233], off offset:16
	global_load_dwordx4 v[182:185], v[232:233], off
	v_pk_add_f32 v[86:87], v[90:91], v[104:105]
	v_pk_add_f32 v[90:91], v[90:91], v[104:105] neg_lo:[0,1] neg_hi:[0,1]
	s_mov_b32 s1, s85
	s_mov_b32 s89, s84
	v_pk_add_f32 v[96:97], v[94:95], v[108:109]
	v_pk_add_f32 v[94:95], v[94:95], v[108:109] neg_lo:[0,1] neg_hi:[0,1]
	v_mul_f32_e32 v104, 0x3f3504f3, v94
	v_pk_fma_f32 v[94:95], v[94:95], s[28:29], v[104:105] op_sel:[1,0,0] op_sel_hi:[1,1,0] neg_lo:[0,0,1] neg_hi:[0,0,1]
	v_pk_add_f32 v[104:105], v[110:111], v[80:81]
	v_pk_add_f32 v[80:81], v[110:111], v[80:81] neg_lo:[0,1] neg_hi:[0,1]
	v_pk_add_f32 v[110:111], v[66:67], v[92:93]
	v_pk_add_f32 v[66:67], v[66:67], v[92:93] neg_lo:[0,1] neg_hi:[0,1]
	v_pk_add_f32 v[92:93], v[66:67], 0 op_sel:[1,0] op_sel_hi:[0,0] neg_hi:[1,0]
	v_pk_add_f32 v[66:67], v[112:113], v[4:5] op_sel:[0,1] op_sel_hi:[1,0] neg_hi:[0,1]
; #define LAS __attribute__((address_space(3)))
; #define SINCOSPI(x, s, c) do { const float hx_ = 0.5f * (x); *(s) = __builtin_amdgcn_sinf(hx_); *(c) = __builtin_amdgcn_cosf(hx_); } while (0)
; #define OPAQUE_I(x) asm volatile("" : "+v"(x))
; DEV void fft_f1x2(LAS cf* buf0, LAS cf* buf1, const cf (&z0)[8], const cf (&z1)[8], int tid) {
;     OPAQUE_I(tid);
;     cf v[16], u[16];
; #pragma unroll
;     for (int q = 0; q < 8; ++q) { v[q] = z0[q]; v[q + 8] = cf{0.f, 0.f}; u[q] = z1[q]; u[q + 8] = cf{0.f, 0.f}; }
;     dft_regs<16, false>(v); dft_regs<16, false>(u);
;     float sn, cs; SINCOSPI(-(float)tid * (2.0f / 8192.0f), &sn, &cs);
;     const cf w = cf{cs, sn}; cf wp = cf{1.f, 0.f};
;     LAS cf* p0 = buf0 + PADI(tid); LAS cf* p1 = buf1 + PADI(tid);
; #pragma unroll
;     for (int p = 0; p < 16; ++p) { p0[544 * p] = cmul(v[BR16[p]], wp); p1[544 * p] = cmul(u[BR16[p]], wp); wp = cmul(wp, w); }
; }
	v_pk_add_f32 v[4:5], v[112:113], v[4:5] op_sel:[0,1] op_sel_hi:[1,0] neg_lo:[0,1]
	v_pk_add_f32 v[112:113], v[98:99], v[88:89]
	v_pk_add_f32 v[88:89], v[98:99], v[88:89] neg_lo:[0,1] neg_hi:[0,1]
	v_pk_add_f32 v[98:99], v[102:103], v[86:87]
	v_pk_add_f32 v[86:87], v[102:103], v[86:87] neg_lo:[0,1] neg_hi:[0,1]
	v_pk_add_f32 v[108:109], v[106:107], v[96:97]
	v_pk_add_f32 v[106:107], v[106:107], v[96:97] neg_lo:[0,1] neg_hi:[0,1]
	v_pk_add_f32 v[96:97], v[82:83], v[90:91] op_sel:[0,1] op_sel_hi:[1,0] neg_hi:[0,1]
	v_pk_add_f32 v[90:91], v[82:83], v[90:91] op_sel:[0,1] op_sel_hi:[1,0] neg_lo:[0,1]
	v_pk_add_f32 v[82:83], v[100:101], v[94:95]
	v_pk_add_f32 v[94:95], v[100:101], v[94:95] neg_lo:[0,1] neg_hi:[0,1]
	v_pk_add_f32 v[100:101], v[94:95], 0 op_sel:[1,0] op_sel_hi:[0,0] neg_hi:[1,0]
	v_pk_add_f32 v[94:95], v[104:105], v[110:111]
	v_pk_add_f32 v[110:111], v[104:105], v[110:111] neg_lo:[0,1] neg_hi:[0,1]
	v_pk_add_f32 v[104:105], v[80:81], v[92:93]
	v_pk_add_f32 v[92:93], v[80:81], v[92:93] neg_lo:[0,1] neg_hi:[0,1]
	v_pk_add_f32 v[80:81], v[66:67], v[112:113]
	v_pk_add_f32 v[66:67], v[66:67], v[112:113] neg_lo:[0,1] neg_hi:[0,1]
	v_mov_b32_e32 v102, v66
	v_mov_b32_e32 v103, v67
	v_pk_add_f32 v[112:113], v[4:5], v[88:89] op_sel:[0,1] op_sel_hi:[1,0] neg_hi:[0,1]
	v_pk_add_f32 v[66:67], v[4:5], v[88:89] op_sel:[0,1] op_sel_hi:[1,0] neg_lo:[0,1]
	v_mov_b32_e32 v4, v66
	v_mov_b32_e32 v5, v67
	v_pk_add_f32 v[88:89], v[98:99], v[108:109]
	v_pk_add_f32 v[66:67], v[98:99], v[108:109] neg_lo:[0,1] neg_hi:[0,1]
	v_mov_b32_e32 v98, v66
	v_mov_b32_e32 v99, v67
	v_pk_add_f32 v[108:109], v[86:87], v[106:107] op_sel:[0,1] op_sel_hi:[1,0] neg_hi:[0,1]
	v_pk_add_f32 v[66:67], v[86:87], v[106:107] op_sel:[0,1] op_sel_hi:[1,0] neg_lo:[0,1]
	v_mov_b32_e32 v86, v66
	v_mov_b32_e32 v87, v67
	v_pk_add_f32 v[106:107], v[96:97], v[82:83]
	v_pk_add_f32 v[66:67], v[96:97], v[82:83] neg_lo:[0,1] neg_hi:[0,1]
	v_mov_b32_e32 v82, v66
	v_mov_b32_e32 v83, v67
	v_pk_add_f32 v[96:97], v[90:91], v[100:101]
	v_pk_add_f32 v[66:67], v[90:91], v[100:101] neg_lo:[0,1] neg_hi:[0,1]
	v_mov_b32_e32 v90, v66
	v_mov_b32_e32 v91, v67
	s_nop 0
	v_cvt_f32_i32_e32 v66, v114
	v_mul_f32_e32 v66, 0xb9800000, v66
	v_mul_f32_e32 v66, 0.5, v66
	v_sin_f32_e32 v101, v66
	v_cos_f32_e32 v100, v66
	v_ashrrev_i32_e32 v66, 4, v114
	v_add_lshl_u32 v66, v66, v114, 3
	v_add_u32_e32 v116, 0, v66
	v_add_u32_e32 v117, s33, v66
	v_mov_b64_e32 v[66:67], s[90:91]
	v_pk_mul_f32 v[114:115], v[68:69], v[66:67] op_sel:[1,1] op_sel_hi:[1,0] neg_lo:[1,0]
	v_pk_fma_f32 v[68:69], v[68:69], v[66:67], v[114:115] op_sel_hi:[0,1,1]
	ds_write_b64 v116, v[68:69]
	v_pk_mul_f32 v[114:115], v[94:95], v[66:67] op_sel:[1,1] op_sel_hi:[1,0] neg_lo:[1,0]
	v_pk_fma_f32 v[68:69], v[94:95], v[66:67], v[114:115] op_sel_hi:[0,1,1]
	ds_write_b64 v117, v[68:69]
	v_pk_mul_f32 v[68:69], v[66:67], v[100:101] op_sel:[1,1] op_sel_hi:[1,0] neg_lo:[1,0]
	v_pk_fma_f32 v[94:95], v[66:67], v[100:101], v[68:69] op_sel_hi:[0,1,1]
	v_pk_mul_f32 v[114:115], v[76:77], v[94:95] op_sel:[1,1] op_sel_hi:[1,0] neg_lo:[1,0]
	v_pk_fma_f32 v[68:69], v[76:77], v[94:95], v[114:115] op_sel_hi:[0,1,1]
	ds_write_b64 v116, v[68:69] offset:4352
	v_pk_mul_f32 v[76:77], v[88:89], v[94:95] op_sel:[1,1] op_sel_hi:[1,0] neg_lo:[1,0]
	v_pk_fma_f32 v[68:69], v[88:89], v[94:95], v[76:77] op_sel_hi:[0,1,1]
	ds_write_b64 v117, v[68:69] offset:4352
	v_pk_mul_f32 v[68:69], v[94:95], v[100:101] op_sel:[1,1] op_sel_hi:[1,0] neg_lo:[1,0]
	v_pk_fma_f32 v[76:77], v[94:95], v[100:101], v[68:69] op_sel_hi:[0,1,1]
	v_pk_mul_f32 v[94:95], v[70:71], v[76:77] op_sel:[1,1] op_sel_hi:[1,0] neg_lo:[1,0]
	v_pk_fma_f32 v[68:69], v[70:71], v[76:77], v[94:95] op_sel_hi:[0,1,1]
	ds_write_b64 v116, v[68:69] offset:8704
	v_pk_mul_f32 v[70:71], v[80:81], v[76:77] op_sel:[1,1] op_sel_hi:[1,0] neg_lo:[1,0]
	v_pk_fma_f32 v[68:69], v[80:81], v[76:77], v[70:71] op_sel_hi:[0,1,1]
	ds_write_b64 v117, v[68:69] offset:8704
	v_pk_mul_f32 v[68:69], v[76:77], v[100:101] op_sel:[1,1] op_sel_hi:[1,0] neg_lo:[1,0]
	v_pk_fma_f32 v[70:71], v[76:77], v[100:101], v[68:69] op_sel_hi:[0,1,1]
	v_pk_mul_f32 v[76:77], v[16:17], v[70:71] op_sel:[1,1] op_sel_hi:[1,0] neg_lo:[1,0]
	v_pk_fma_f32 v[68:69], v[16:17], v[70:71], v[76:77] op_sel_hi:[0,1,1]
	ds_write_b64 v116, v[68:69] offset:13056
	v_pk_mul_f32 v[76:77], v[106:107], v[70:71] op_sel:[1,1] op_sel_hi:[1,0] neg_lo:[1,0]
	v_pk_fma_f32 v[68:69], v[106:107], v[70:71], v[76:77] op_sel_hi:[0,1,1]
	ds_write_b64 v117, v[68:69] offset:13056
	v_pk_mul_f32 v[68:69], v[70:71], v[100:101] op_sel:[1,1] op_sel_hi:[1,0] neg_lo:[1,0]
	v_pk_fma_f32 v[70:71], v[70:71], v[100:101], v[68:69] op_sel_hi:[0,1,1]
	v_pk_mul_f32 v[68:69], v[78:79], v[70:71] op_sel:[1,1] op_sel_hi:[1,0] neg_lo:[1,0]
	v_pk_fma_f32 v[16:17], v[78:79], v[70:71], v[68:69] op_sel_hi:[0,1,1]
	ds_write_b64 v116, v[16:17] offset:17408
	v_pk_mul_f32 v[68:69], v[104:105], v[70:71] op_sel:[1,1] op_sel_hi:[1,0] neg_lo:[1,0]
	v_pk_fma_f32 v[16:17], v[104:105], v[70:71], v[68:69] op_sel_hi:[0,1,1]
	ds_write_b64 v117, v[16:17] offset:17408
	v_pk_mul_f32 v[16:17], v[70:71], v[100:101] op_sel:[1,1] op_sel_hi:[1,0] neg_lo:[1,0]
	v_pk_fma_f32 v[68:69], v[70:71], v[100:101], v[16:17] op_sel_hi:[0,1,1]
	v_pk_mul_f32 v[70:71], v[6:7], v[68:69] op_sel:[1,1] op_sel_hi:[1,0] neg_lo:[1,0]
	v_pk_fma_f32 v[16:17], v[6:7], v[68:69], v[70:71] op_sel_hi:[0,1,1]
	ds_write_b64 v116, v[16:17] offset:21760
	v_pk_mul_f32 v[70:71], v[108:109], v[68:69] op_sel:[1,1] op_sel_hi:[1,0] neg_lo:[1,0]
	v_pk_fma_f32 v[16:17], v[108:109], v[68:69], v[70:71] op_sel_hi:[0,1,1]
	ds_write_b64 v117, v[16:17] offset:21760
; #define LAS __attribute__((address_space(3)))
; DEV void fft_f1x2(LAS cf* buf0, LAS cf* buf1, const cf (&z0)[8], const cf (&z1)[8], int tid) {
;     ...
;     const cf w = cf{cs, sn}; cf wp = cf{1.f, 0.f};
;     LAS cf* p0 = buf0 + PADI(tid); LAS cf* p1 = buf1 + PADI(tid);
; #pragma unroll
;     for (int p = 0; p < 16; ++p) { p0[544 * p] = cmul(v[BR16[p]], wp); p1[544 * p] = cmul(u[BR16[p]], wp); wp = cmul(wp, w); }
	v_pk_mul_f32 v[16:17], v[68:69], v[100:101] op_sel:[1,1] op_sel_hi:[1,0] neg_lo:[1,0]
	v_pk_fma_f32 v[68:69], v[68:69], v[100:101], v[16:17] op_sel_hi:[0,1,1]
	v_pk_mul_f32 v[70:71], v[18:19], v[68:69] op_sel:[1,1] op_sel_hi:[1,0] neg_lo:[1,0]
	v_pk_fma_f32 v[16:17], v[18:19], v[68:69], v[70:71] op_sel_hi:[0,1,1]
	ds_write_b64 v116, v[16:17] offset:26112
	v_pk_mul_f32 v[18:19], v[112:113], v[68:69] op_sel:[1,1] op_sel_hi:[1,0] neg_lo:[1,0]
	v_pk_fma_f32 v[16:17], v[112:113], v[68:69], v[18:19] op_sel_hi:[0,1,1]
	ds_write_b64 v117, v[16:17] offset:26112
	v_pk_mul_f32 v[16:17], v[68:69], v[100:101] op_sel:[1,1] op_sel_hi:[1,0] neg_lo:[1,0]
	v_pk_fma_f32 v[18:19], v[68:69], v[100:101], v[16:17] op_sel_hi:[0,1,1]
	v_pk_mul_f32 v[68:69], v[74:75], v[18:19] op_sel:[1,1] op_sel_hi:[1,0] neg_lo:[1,0]
	v_pk_fma_f32 v[16:17], v[74:75], v[18:19], v[68:69] op_sel_hi:[0,1,1]
	ds_write_b64 v116, v[16:17] offset:30464
	v_pk_mul_f32 v[68:69], v[96:97], v[18:19] op_sel:[1,1] op_sel_hi:[1,0] neg_lo:[1,0]
	v_pk_fma_f32 v[16:17], v[96:97], v[18:19], v[68:69] op_sel_hi:[0,1,1]
	ds_write_b64 v117, v[16:17] offset:30464
	v_pk_mul_f32 v[16:17], v[18:19], v[100:101] op_sel:[1,1] op_sel_hi:[1,0] neg_lo:[1,0]
	v_pk_fma_f32 v[18:19], v[18:19], v[100:101], v[16:17] op_sel_hi:[0,1,1]
	v_pk_mul_f32 v[16:17], v[84:85], v[18:19] op_sel:[1,1] op_sel_hi:[1,0] neg_lo:[1,0]
	v_pk_fma_f32 v[80:81], v[84:85], v[18:19], v[16:17] op_sel_hi:[0,1,1]
	ds_write_b64 v116, v[80:81] offset:34816
	v_pk_mul_f32 v[16:17], v[110:111], v[18:19] op_sel:[1,1] op_sel_hi:[1,0] neg_lo:[1,0]
	v_pk_fma_f32 v[80:81], v[110:111], v[18:19], v[16:17] op_sel_hi:[0,1,1]
	ds_write_b64 v117, v[80:81] offset:34816
	v_pk_mul_f32 v[80:81], v[18:19], v[100:101] op_sel:[1,1] op_sel_hi:[1,0] neg_lo:[1,0]
	v_pk_fma_f32 v[16:17], v[18:19], v[100:101], v[80:81] op_sel_hi:[0,1,1]
	v_pk_mul_f32 v[18:19], v[12:13], v[16:17] op_sel:[1,1] op_sel_hi:[1,0] neg_lo:[1,0]
	v_pk_fma_f32 v[80:81], v[12:13], v[16:17], v[18:19] op_sel_hi:[0,1,1]
	ds_write_b64 v116, v[80:81] offset:39168
	v_pk_mul_f32 v[12:13], v[98:99], v[16:17] op_sel:[1,1] op_sel_hi:[1,0] neg_lo:[1,0]
	v_pk_fma_f32 v[80:81], v[98:99], v[16:17], v[12:13] op_sel_hi:[0,1,1]
	ds_write_b64 v117, v[80:81] offset:39168
	v_pk_mul_f32 v[80:81], v[16:17], v[100:101] op_sel:[1,1] op_sel_hi:[1,0] neg_lo:[1,0]
	v_pk_fma_f32 v[12:13], v[16:17], v[100:101], v[80:81] op_sel_hi:[0,1,1]
	v_pk_mul_f32 v[16:17], v[72:73], v[12:13] op_sel:[1,1] op_sel_hi:[1,0] neg_lo:[1,0]
	v_pk_fma_f32 v[80:81], v[72:73], v[12:13], v[16:17] op_sel_hi:[0,1,1]
	ds_write_b64 v116, v[80:81] offset:43520
	v_pk_mul_f32 v[6:7], v[102:103], v[12:13] op_sel:[1,1] op_sel_hi:[1,0] neg_lo:[1,0]
	v_pk_fma_f32 v[80:81], v[102:103], v[12:13], v[6:7] op_sel_hi:[0,1,1]
	ds_write_b64 v117, v[80:81] offset:43520
	v_pk_mul_f32 v[80:81], v[12:13], v[100:101] op_sel:[1,1] op_sel_hi:[1,0] neg_lo:[1,0]
	v_pk_fma_f32 v[6:7], v[12:13], v[100:101], v[80:81] op_sel_hi:[0,1,1]
	v_pk_mul_f32 v[12:13], v[14:15], v[6:7] op_sel:[1,1] op_sel_hi:[1,0] neg_lo:[1,0]
	v_pk_fma_f32 v[80:81], v[14:15], v[6:7], v[12:13] op_sel_hi:[0,1,1]
	ds_write_b64 v116, v[80:81] offset:47872
	v_pk_mul_f32 v[12:13], v[82:83], v[6:7] op_sel:[1,1] op_sel_hi:[1,0] neg_lo:[1,0]
	v_pk_fma_f32 v[80:81], v[82:83], v[6:7], v[12:13] op_sel_hi:[0,1,1]
	ds_write_b64 v117, v[80:81] offset:47872
	v_pk_mul_f32 v[80:81], v[6:7], v[100:101] op_sel:[1,1] op_sel_hi:[1,0] neg_lo:[1,0]
	v_pk_fma_f32 v[6:7], v[6:7], v[100:101], v[80:81] op_sel_hi:[0,1,1]
	v_pk_mul_f32 v[80:81], v[0:1], v[6:7] op_sel:[1,1] op_sel_hi:[1,0] neg_lo:[1,0]
	v_pk_fma_f32 v[0:1], v[0:1], v[6:7], v[80:81] op_sel_hi:[0,1,1]
	ds_write_b64 v116, v[0:1] offset:52224
	v_pk_mul_f32 v[80:81], v[92:93], v[6:7] op_sel:[1,1] op_sel_hi:[1,0] neg_lo:[1,0]
	v_pk_fma_f32 v[0:1], v[92:93], v[6:7], v[80:81] op_sel_hi:[0,1,1]
	ds_write_b64 v117, v[0:1] offset:52224
	v_pk_mul_f32 v[0:1], v[6:7], v[100:101] op_sel:[1,1] op_sel_hi:[1,0] neg_lo:[1,0]
	v_pk_fma_f32 v[92:93], v[6:7], v[100:101], v[0:1] op_sel_hi:[0,1,1]
	v_pk_mul_f32 v[6:7], v[8:9], v[92:93] op_sel:[1,1] op_sel_hi:[1,0] neg_lo:[1,0]
	v_pk_fma_f32 v[0:1], v[8:9], v[92:93], v[6:7] op_sel_hi:[0,1,1]
	ds_write_b64 v116, v[0:1] offset:56576
	v_pk_mul_f32 v[6:7], v[86:87], v[92:93] op_sel:[1,1] op_sel_hi:[1,0] neg_lo:[1,0]
	v_pk_fma_f32 v[0:1], v[86:87], v[92:93], v[6:7] op_sel_hi:[0,1,1]
	ds_write_b64 v117, v[0:1] offset:56576
	v_pk_mul_f32 v[0:1], v[92:93], v[100:101] op_sel:[1,1] op_sel_hi:[1,0] neg_lo:[1,0]
	v_pk_fma_f32 v[92:93], v[92:93], v[100:101], v[0:1] op_sel_hi:[0,1,1]
	v_pk_mul_f32 v[6:7], v[2:3], v[92:93] op_sel:[1,1] op_sel_hi:[1,0] neg_lo:[1,0]
	v_pk_fma_f32 v[0:1], v[2:3], v[92:93], v[6:7] op_sel_hi:[0,1,1]
	ds_write_b64 v116, v[0:1] offset:60928
	v_pk_mul_f32 v[2:3], v[4:5], v[92:93] op_sel:[1,1] op_sel_hi:[1,0] neg_lo:[1,0]
	v_pk_fma_f32 v[0:1], v[4:5], v[92:93], v[2:3] op_sel_hi:[0,1,1]
	ds_write_b64 v117, v[0:1] offset:60928
	v_pk_mul_f32 v[0:1], v[92:93], v[100:101] op_sel:[1,1] op_sel_hi:[1,0] neg_lo:[1,0]
	v_pk_fma_f32 v[2:3], v[92:93], v[100:101], v[0:1] op_sel_hi:[0,1,1]
	v_pk_mul_f32 v[4:5], v[10:11], v[2:3] op_sel:[1,1] op_sel_hi:[1,0] neg_lo:[1,0]
	v_pk_fma_f32 v[0:1], v[10:11], v[2:3], v[4:5] op_sel_hi:[0,1,1]
	ds_write_b64 v116, v[0:1] offset:65280
	v_pk_mul_f32 v[4:5], v[90:91], v[2:3] op_sel:[1,1] op_sel_hi:[1,0] neg_lo:[1,0]
	v_pk_fma_f32 v[0:1], v[90:91], v[2:3], v[4:5] op_sel_hi:[0,1,1]
	ds_write_b64 v117, v[0:1] offset:65280
	v_mov_b32_e32 v0, v160
	s_waitcnt lgkmcnt(0)
	s_barrier
; #define LAS __attribute__((address_space(3)))
; #define OPAQUE_I(x) asm volatile("" : "+v"(x))
; template <int R, bool INV> DEV void dft_regs(cf (&v)[R]) {
; #pragma unroll
;     for (int s = R; s >= 2; s >>= 1) {
;         const int h = s >> 1;
; #pragma unroll
;         for (int b = 0; b < R; b += s) {
; #pragma unroll
;             for (int k = 0; k < h; ++k) {
;                 const cf a = v[b + k], c = v[b + k + h];
;                 v[b + k] = a + c;
;                 const cf d = a - c;
;                 const int m = k * (32 / s);
;                 const float wr = tw_cos(m), wi = INV ? tw_sin(m) : -tw_sin(m);
;                 v[b + k + h] = cf{d.x * wr - d.y * wi, d.x * wi + d.y * wr};
;             }
;         }
;     }
; }
; DEV void fft_f2(LAS cf* buf, int t8) {
;     OPAQUE_I(t8);
;     LAS cf* pb = buf + (t8 >> 4) * 544 + (t8 & 15);
;     cf v[32];
; #pragma unroll
;     for (int q = 0; q < 32; ++q) v[q] = pb[17 * q];
;     dft_regs<32, false>(v);
	s_nop 0
	v_lshrrev_b32_e32 v1, 4, v0
	v_and_b32_e32 v3, 15, v0
	v_mul_lo_u32 v1, v1, s15
	v_lshlrev_b32_e32 v0, 3, v3
	v_add3_u32 v2, v159, v1, v0
	ds_read2_b64 v[4:7], v2 offset1:17
	ds_read2_b64 v[8:11], v2 offset0:34 offset1:51
	ds_read2_b64 v[12:15], v2 offset0:68 offset1:85
	ds_read2_b64 v[16:19], v2 offset0:102 offset1:119
	ds_read2_b64 v[68:71], v2 offset0:136 offset1:153
	ds_read2_b64 v[72:75], v2 offset0:170 offset1:187
	ds_read2_b64 v[76:79], v2 offset0:204 offset1:221
	ds_read2_b64 v[80:83], v2 offset0:238 offset1:255
	v_add_u32_e32 v0, 0x800, v2
	ds_read2_b64 v[84:87], v0 offset0:16 offset1:33
	ds_read2_b64 v[88:91], v0 offset0:50 offset1:67
	ds_read2_b64 v[92:95], v0 offset0:84 offset1:101
	ds_read2_b64 v[96:99], v0 offset0:118 offset1:135
	ds_read2_b64 v[100:103], v0 offset0:152 offset1:169
	ds_read2_b64 v[104:107], v0 offset0:186 offset1:203
	ds_read2_b64 v[108:111], v0 offset0:220 offset1:237
	s_waitcnt lgkmcnt(6)
	v_pk_add_f32 v[116:117], v[4:5], v[84:85]
	v_pk_add_f32 v[4:5], v[4:5], v[84:85] neg_lo:[0,1] neg_hi:[0,1]
	v_add_u32_e32 v1, 0xc00, v2
	ds_read2_b64 v[112:115], v1 offset0:126 offset1:143
	v_cvt_f32_ubyte0_e32 v3, v3
	v_pk_add_f32 v[118:119], v[6:7], v[86:87]
	v_pk_add_f32 v[6:7], v[6:7], v[86:87] neg_lo:[0,1] neg_hi:[0,1]
	v_mul_f32_e32 v3, 0xbb800000, v3
	v_pk_mul_f32 v[84:85], v[6:7], s[82:83] op_sel_hi:[1,0]
	v_mul_f32_e32 v3, 0.5, v3
	v_pk_fma_f32 v[86:87], v[6:7], s[94:95], v[84:85] op_sel:[0,0,1] op_sel_hi:[1,0,0] neg_hi:[0,0,1]
	s_waitcnt lgkmcnt(6)
	v_pk_add_f32 v[6:7], v[8:9], v[88:89]
	v_pk_add_f32 v[8:9], v[8:9], v[88:89] neg_lo:[0,1] neg_hi:[0,1]
	v_pk_mul_f32 v[84:85], v[8:9], s[84:85] op_sel_hi:[1,0]
	v_pk_fma_f32 v[88:89], v[8:9], s[16:17], v[84:85] op_sel:[0,0,1] op_sel_hi:[1,0,0] neg_hi:[0,0,1]
	v_pk_add_f32 v[8:9], v[10:11], v[90:91]
	v_pk_add_f32 v[10:11], v[10:11], v[90:91] neg_lo:[0,1] neg_hi:[0,1]
	v_pk_mul_f32 v[84:85], v[10:11], s[4:5] op_sel_hi:[1,0]
	v_pk_fma_f32 v[90:91], v[10:11], s[86:87], v[84:85] op_sel:[0,0,1] op_sel_hi:[1,0,0] neg_hi:[0,0,1]
	s_waitcnt lgkmcnt(5)
	v_pk_add_f32 v[10:11], v[12:13], v[92:93]
	v_pk_add_f32 v[12:13], v[12:13], v[92:93] neg_lo:[0,1] neg_hi:[0,1]
	v_pk_mul_f32 v[84:85], v[12:13], s[18:19] op_sel_hi:[1,0]
	v_pk_fma_f32 v[92:93], v[12:13], s[18:19], v[84:85] op_sel:[0,0,1] op_sel_hi:[1,0,0] neg_hi:[0,0,1]
	v_pk_add_f32 v[12:13], v[14:15], v[94:95]
	v_pk_add_f32 v[14:15], v[14:15], v[94:95] neg_lo:[0,1] neg_hi:[0,1]
	v_pk_mul_f32 v[84:85], v[14:15], s[86:87] op_sel_hi:[1,0]
	v_pk_fma_f32 v[94:95], v[14:15], s[4:5], v[84:85] op_sel:[0,0,1] op_sel_hi:[1,0,0] neg_hi:[0,0,1]
	s_mov_b32 s5, s86
	s_waitcnt lgkmcnt(4)
	v_pk_add_f32 v[14:15], v[16:17], v[96:97]
	v_pk_add_f32 v[16:17], v[16:17], v[96:97] neg_lo:[0,1] neg_hi:[0,1]
	v_pk_mul_f32 v[84:85], v[16:17], s[16:17] op_sel_hi:[1,0]
	v_pk_fma_f32 v[96:97], v[16:17], s[84:85], v[84:85] op_sel:[0,0,1] op_sel_hi:[1,0,0] neg_hi:[0,0,1]
	v_pk_add_f32 v[16:17], v[18:19], v[98:99]
	v_pk_add_f32 v[18:19], v[18:19], v[98:99] neg_lo:[0,1] neg_hi:[0,1]
	v_pk_mul_f32 v[84:85], v[18:19], s[94:95] op_sel_hi:[1,0]
	v_pk_fma_f32 v[98:99], v[18:19], s[82:83], v[84:85] op_sel:[0,0,1] op_sel_hi:[1,0,0] neg_hi:[0,0,1]
	s_mov_b32 s83, s94
	s_waitcnt lgkmcnt(3)
	v_pk_add_f32 v[18:19], v[68:69], v[100:101]
	v_pk_add_f32 v[68:69], v[68:69], v[100:101] neg_lo:[0,1] neg_hi:[0,1]
	v_pk_add_f32 v[84:85], v[70:71], v[102:103]
	v_pk_add_f32 v[70:71], v[70:71], v[102:103] neg_lo:[0,1] neg_hi:[0,1]
	v_pk_mul_f32 v[100:101], v[70:71], s[82:83] op_sel_hi:[0,1]
	v_pk_fma_f32 v[70:71], v[70:71], s[94:95], v[100:101] op_sel:[1,0,0] neg_lo:[0,0,1] neg_hi:[0,0,1]
	s_waitcnt lgkmcnt(2)
	v_pk_add_f32 v[100:101], v[72:73], v[104:105]
	v_pk_add_f32 v[72:73], v[72:73], v[104:105] neg_lo:[0,1] neg_hi:[0,1]
	v_pk_mul_f32 v[102:103], v[72:73], s[84:85] op_sel_hi:[0,1]
	v_pk_fma_f32 v[72:73], v[72:73], s[30:31], v[102:103] op_sel:[1,0,0] neg_lo:[0,0,1] neg_hi:[0,0,1]
	v_pk_add_f32 v[102:103], v[74:75], v[106:107]
	v_pk_add_f32 v[74:75], v[74:75], v[106:107] neg_lo:[0,1] neg_hi:[0,1]
	v_pk_mul_f32 v[104:105], v[74:75], s[4:5] op_sel_hi:[0,1]
	v_pk_fma_f32 v[74:75], v[74:75], s[86:87], v[104:105] op_sel:[1,0,0] neg_lo:[0,0,1] neg_hi:[0,0,1]
	s_waitcnt lgkmcnt(1)
	v_pk_add_f32 v[104:105], v[76:77], v[108:109]
	v_pk_add_f32 v[76:77], v[76:77], v[108:109] neg_lo:[0,1] neg_hi:[0,1]
	v_mul_f32_e32 v106, 0x3f3504f3, v76
	v_pk_fma_f32 v[76:77], v[76:77], s[28:29], v[106:107] op_sel:[1,0,0] op_sel_hi:[1,1,0] neg_lo:[0,0,1] neg_hi:[0,0,1]
	v_pk_add_f32 v[106:107], v[78:79], v[110:111]
	v_pk_add_f32 v[78:79], v[78:79], v[110:111] neg_lo:[0,1] neg_hi:[0,1]
	v_pk_mul_f32 v[108:109], v[78:79], s[2:3] op_sel_hi:[0,1]
	v_pk_fma_f32 v[78:79], v[78:79], s[10:11], v[108:109] op_sel:[1,0,0] neg_lo:[0,0,1] neg_hi:[0,0,1]
	s_waitcnt lgkmcnt(0)
; template <int R, bool INV> DEV void dft_regs(cf (&v)[R]) {
; #pragma unroll
;     for (int s = R; s >= 2; s >>= 1) {
;         const int h = s >> 1;
; #pragma unroll
;         for (int b = 0; b < R; b += s) {
; #pragma unroll
;             for (int k = 0; k < h; ++k) {
;                 const cf a = v[b + k], c = v[b + k + h];
;                 v[b + k] = a + c;
;                 const cf d = a - c;
;                 const int m = k * (32 / s);
;                 const float wr = tw_cos(m), wi = INV ? tw_sin(m) : -tw_sin(m);
;                 v[b + k + h] = cf{d.x * wr - d.y * wi, d.x * wi + d.y * wr};
;             }
;         }
;     }
; }
	v_pk_add_f32 v[108:109], v[80:81], v[112:113]
	v_pk_add_f32 v[80:81], v[80:81], v[112:113] neg_lo:[0,1] neg_hi:[0,1]
	v_pk_mul_f32 v[110:111], v[80:81], s[24:25] op_sel_hi:[0,1]
	v_pk_fma_f32 v[80:81], v[80:81], s[34:35], v[110:111] op_sel:[1,0,0] neg_lo:[0,0,1] neg_hi:[0,0,1]
	v_pk_add_f32 v[110:111], v[82:83], v[114:115]
	v_pk_add_f32 v[82:83], v[82:83], v[114:115] neg_lo:[0,1] neg_hi:[0,1]
	v_pk_mul_f32 v[112:113], v[82:83], s[6:7] op_sel_hi:[0,1]
	v_pk_fma_f32 v[82:83], v[82:83], s[8:9], v[112:113] op_sel:[1,0,0] neg_lo:[0,0,1] neg_hi:[0,0,1]
	v_pk_add_f32 v[112:113], v[116:117], v[18:19]
	v_pk_add_f32 v[18:19], v[116:117], v[18:19] neg_lo:[0,1] neg_hi:[0,1]
	v_pk_add_f32 v[116:117], v[118:119], v[84:85]
	v_pk_add_f32 v[118:119], v[118:119], v[84:85] neg_lo:[0,1] neg_hi:[0,1]
	v_pk_mul_f32 v[84:85], v[118:119], s[84:85] op_sel_hi:[1,0]
	v_pk_fma_f32 v[114:115], v[118:119], s[16:17], v[84:85] op_sel:[0,0,1] op_sel_hi:[1,0,0] neg_hi:[0,0,1]
	v_pk_add_f32 v[118:119], v[6:7], v[100:101]
	v_pk_add_f32 v[6:7], v[6:7], v[100:101] neg_lo:[0,1] neg_hi:[0,1]
	v_pk_mul_f32 v[84:85], v[6:7], s[18:19] op_sel_hi:[1,0]
	v_pk_fma_f32 v[100:101], v[6:7], s[18:19], v[84:85] op_sel:[0,0,1] op_sel_hi:[1,0,0] neg_hi:[0,0,1]
	v_pk_add_f32 v[6:7], v[8:9], v[102:103]
	v_pk_add_f32 v[8:9], v[8:9], v[102:103] neg_lo:[0,1] neg_hi:[0,1]
	v_pk_mul_f32 v[84:85], v[8:9], s[16:17] op_sel_hi:[1,0]
	v_pk_fma_f32 v[102:103], v[8:9], s[84:85], v[84:85] op_sel:[0,0,1] op_sel_hi:[1,0,0] neg_hi:[0,0,1]
	v_pk_add_f32 v[8:9], v[10:11], v[104:105]
	v_pk_add_f32 v[10:11], v[10:11], v[104:105] neg_lo:[0,1] neg_hi:[0,1]
	v_pk_add_f32 v[84:85], v[12:13], v[106:107]
	v_pk_add_f32 v[12:13], v[12:13], v[106:107] neg_lo:[0,1] neg_hi:[0,1]
	v_pk_mul_f32 v[104:105], v[12:13], s[84:85] op_sel_hi:[0,1]
	v_pk_fma_f32 v[12:13], v[12:13], s[30:31], v[104:105] op_sel:[1,0,0] neg_lo:[0,0,1] neg_hi:[0,0,1]
	v_pk_add_f32 v[104:105], v[14:15], v[108:109]
	v_pk_add_f32 v[14:15], v[14:15], v[108:109] neg_lo:[0,1] neg_hi:[0,1]
	v_mul_f32_e32 v106, 0x3f3504f3, v14
	v_pk_fma_f32 v[14:15], v[14:15], s[28:29], v[106:107] op_sel:[1,0,0] op_sel_hi:[1,1,0] neg_lo:[0,0,1] neg_hi:[0,0,1]
	v_pk_add_f32 v[106:107], v[16:17], v[110:111]
	v_pk_add_f32 v[16:17], v[16:17], v[110:111] neg_lo:[0,1] neg_hi:[0,1]
	v_pk_mul_f32 v[108:109], v[16:17], s[24:25] op_sel_hi:[0,1]
	v_pk_fma_f32 v[16:17], v[16:17], s[34:35], v[108:109] op_sel:[1,0,0] neg_lo:[0,0,1] neg_hi:[0,0,1]
	v_pk_add_f32 v[108:109], v[4:5], v[68:69] op_sel:[0,1] op_sel_hi:[1,0] neg_hi:[0,1]
	v_pk_add_f32 v[68:69], v[4:5], v[68:69] op_sel:[0,1] op_sel_hi:[1,0] neg_lo:[0,1]
	v_pk_add_f32 v[4:5], v[86:87], v[70:71]
	v_pk_add_f32 v[70:71], v[86:87], v[70:71] neg_lo:[0,1] neg_hi:[0,1]
	v_pk_mul_f32 v[86:87], v[70:71], s[84:85] op_sel_hi:[1,0]
	v_pk_fma_f32 v[110:111], v[70:71], s[16:17], v[86:87] op_sel:[0,0,1] op_sel_hi:[1,0,0] neg_hi:[0,0,1]
	v_pk_add_f32 v[70:71], v[88:89], v[72:73]
	v_pk_add_f32 v[72:73], v[88:89], v[72:73] neg_lo:[0,1] neg_hi:[0,1]
	v_pk_mul_f32 v[86:87], v[72:73], s[18:19] op_sel_hi:[1,0]
	v_pk_fma_f32 v[88:89], v[72:73], s[18:19], v[86:87] op_sel:[0,0,1] op_sel_hi:[1,0,0] neg_hi:[0,0,1]
	v_pk_add_f32 v[72:73], v[90:91], v[74:75]
	v_pk_add_f32 v[74:75], v[90:91], v[74:75] neg_lo:[0,1] neg_hi:[0,1]
	v_pk_mul_f32 v[86:87], v[74:75], s[16:17] op_sel_hi:[1,0]
	v_pk_fma_f32 v[90:91], v[74:75], s[84:85], v[86:87] op_sel:[0,0,1] op_sel_hi:[1,0,0] neg_hi:[0,0,1]
	v_pk_add_f32 v[74:75], v[92:93], v[76:77]
	v_pk_add_f32 v[76:77], v[92:93], v[76:77] neg_lo:[0,1] neg_hi:[0,1]
	v_pk_add_f32 v[86:87], v[94:95], v[78:79]
	v_pk_add_f32 v[78:79], v[94:95], v[78:79] neg_lo:[0,1] neg_hi:[0,1]
	v_pk_mul_f32 v[92:93], v[78:79], s[84:85] op_sel_hi:[0,1]
	v_pk_fma_f32 v[78:79], v[78:79], s[30:31], v[92:93] op_sel:[1,0,0] neg_lo:[0,0,1] neg_hi:[0,0,1]
	v_pk_add_f32 v[92:93], v[96:97], v[80:81]
	v_pk_add_f32 v[80:81], v[96:97], v[80:81] neg_lo:[0,1] neg_hi:[0,1]
	v_mul_f32_e32 v94, 0x3f3504f3, v80
	v_pk_fma_f32 v[80:81], v[80:81], s[28:29], v[94:95] op_sel:[1,0,0] op_sel_hi:[1,1,0] neg_lo:[0,0,1] neg_hi:[0,0,1]
	v_pk_add_f32 v[94:95], v[98:99], v[82:83]
	v_pk_add_f32 v[82:83], v[98:99], v[82:83] neg_lo:[0,1] neg_hi:[0,1]
	v_pk_mul_f32 v[96:97], v[82:83], s[24:25] op_sel_hi:[0,1]
	v_pk_fma_f32 v[82:83], v[82:83], s[34:35], v[96:97] op_sel:[1,0,0] neg_lo:[0,0,1] neg_hi:[0,0,1]
	v_pk_add_f32 v[96:97], v[112:113], v[8:9]
	v_pk_add_f32 v[8:9], v[112:113], v[8:9] neg_lo:[0,1] neg_hi:[0,1]
	v_pk_add_f32 v[112:113], v[116:117], v[84:85]
	v_pk_add_f32 v[84:85], v[116:117], v[84:85] neg_lo:[0,1] neg_hi:[0,1]
	v_pk_mul_f32 v[116:117], v[84:85], s[18:19] op_sel_hi:[1,0]
	v_pk_fma_f32 v[98:99], v[84:85], s[18:19], v[116:117] op_sel:[0,0,1] op_sel_hi:[1,0,0] neg_hi:[0,0,1]
	v_pk_add_f32 v[84:85], v[118:119], v[104:105]
	v_pk_add_f32 v[118:119], v[118:119], v[104:105] neg_lo:[0,1] neg_hi:[0,1]
	v_pk_add_f32 v[116:117], v[6:7], v[106:107]
	v_pk_add_f32 v[6:7], v[6:7], v[106:107] neg_lo:[0,1] neg_hi:[0,1]
	v_mul_f32_e32 v104, 0x3f3504f3, v6
	v_pk_fma_f32 v[6:7], v[6:7], s[28:29], v[104:105] op_sel:[1,0,0] op_sel_hi:[1,1,0] neg_lo:[0,0,1] neg_hi:[0,0,1]
	v_pk_add_f32 v[104:105], v[18:19], v[10:11] op_sel:[0,1] op_sel_hi:[1,0] neg_hi:[0,1]
	v_pk_add_f32 v[10:11], v[18:19], v[10:11] op_sel:[0,1] op_sel_hi:[1,0] neg_lo:[0,1]
	v_pk_add_f32 v[18:19], v[114:115], v[12:13]
	v_pk_add_f32 v[12:13], v[114:115], v[12:13] neg_lo:[0,1] neg_hi:[0,1]
	v_pk_mul_f32 v[106:107], v[12:13], s[18:19] op_sel_hi:[1,0]
	v_pk_fma_f32 v[114:115], v[12:13], s[18:19], v[106:107] op_sel:[0,0,1] op_sel_hi:[1,0,0] neg_hi:[0,0,1]
	v_pk_add_f32 v[12:13], v[100:101], v[14:15]
; template <int R, bool INV> DEV void dft_regs(cf (&v)[R]) {
; #pragma unroll
;     for (int s = R; s >= 2; s >>= 1) {
;         const int h = s >> 1;
; #pragma unroll
;         for (int b = 0; b < R; b += s) {
; #pragma unroll
;             for (int k = 0; k < h; ++k) {
;                 const cf a = v[b + k], c = v[b + k + h];
;                 v[b + k] = a + c;
;                 const cf d = a - c;
;                 const int m = k * (32 / s);
;                 const float wr = tw_cos(m), wi = INV ? tw_sin(m) : -tw_sin(m);
;                 v[b + k + h] = cf{d.x * wr - d.y * wi, d.x * wi + d.y * wr};
;             }
;         }
;     }
; }
	v_pk_add_f32 v[14:15], v[100:101], v[14:15] neg_lo:[0,1] neg_hi:[0,1]
	v_pk_add_f32 v[100:101], v[102:103], v[16:17]
	v_pk_add_f32 v[16:17], v[102:103], v[16:17] neg_lo:[0,1] neg_hi:[0,1]
	v_mul_f32_e32 v102, 0x3f3504f3, v16
	v_pk_fma_f32 v[16:17], v[16:17], s[28:29], v[102:103] op_sel:[1,0,0] op_sel_hi:[1,1,0] neg_lo:[0,0,1] neg_hi:[0,0,1]
	v_pk_add_f32 v[102:103], v[108:109], v[74:75]
	v_pk_add_f32 v[74:75], v[108:109], v[74:75] neg_lo:[0,1] neg_hi:[0,1]
	v_pk_add_f32 v[108:109], v[4:5], v[86:87]
	v_pk_add_f32 v[86:87], v[4:5], v[86:87] neg_lo:[0,1] neg_hi:[0,1]
	v_pk_mul_f32 v[4:5], v[86:87], s[18:19] op_sel_hi:[1,0]
	v_pk_fma_f32 v[106:107], v[86:87], s[18:19], v[4:5] op_sel:[0,0,1] op_sel_hi:[1,0,0] neg_hi:[0,0,1]
	v_pk_add_f32 v[86:87], v[70:71], v[92:93]
	v_pk_add_f32 v[70:71], v[70:71], v[92:93] neg_lo:[0,1] neg_hi:[0,1]
	v_pk_add_f32 v[4:5], v[72:73], v[94:95]
	v_pk_add_f32 v[72:73], v[72:73], v[94:95] neg_lo:[0,1] neg_hi:[0,1]
	v_mul_f32_e32 v92, 0x3f3504f3, v72
	v_pk_fma_f32 v[72:73], v[72:73], s[28:29], v[92:93] op_sel:[1,0,0] op_sel_hi:[1,1,0] neg_lo:[0,0,1] neg_hi:[0,0,1]
	v_pk_add_f32 v[92:93], v[68:69], v[76:77] op_sel:[0,1] op_sel_hi:[1,0] neg_hi:[0,1]
	v_pk_add_f32 v[76:77], v[68:69], v[76:77] op_sel:[0,1] op_sel_hi:[1,0] neg_lo:[0,1]
	v_mov_b32_e32 v68, v76
	v_mov_b32_e32 v69, v77
	v_pk_add_f32 v[76:77], v[110:111], v[78:79]
	v_pk_add_f32 v[78:79], v[110:111], v[78:79] neg_lo:[0,1] neg_hi:[0,1]
	v_pk_mul_f32 v[94:95], v[78:79], s[18:19] op_sel_hi:[1,0]
	v_pk_fma_f32 v[110:111], v[78:79], s[18:19], v[94:95] op_sel:[0,0,1] op_sel_hi:[1,0,0] neg_hi:[0,0,1]
	v_pk_add_f32 v[78:79], v[88:89], v[80:81]
	v_pk_add_f32 v[80:81], v[88:89], v[80:81] neg_lo:[0,1] neg_hi:[0,1]
	v_pk_add_f32 v[88:89], v[90:91], v[82:83]
	v_pk_add_f32 v[82:83], v[90:91], v[82:83] neg_lo:[0,1] neg_hi:[0,1]
	v_mul_f32_e32 v90, 0x3f3504f3, v82
	v_pk_fma_f32 v[82:83], v[82:83], s[28:29], v[90:91] op_sel:[1,0,0] op_sel_hi:[1,1,0] neg_lo:[0,0,1] neg_hi:[0,0,1]
	v_pk_add_f32 v[90:91], v[96:97], v[84:85]
	v_pk_add_f32 v[84:85], v[96:97], v[84:85] neg_lo:[0,1] neg_hi:[0,1]
	v_pk_add_f32 v[96:97], v[112:113], v[116:117]
	v_pk_add_f32 v[116:117], v[112:113], v[116:117] neg_lo:[0,1] neg_hi:[0,1]
	v_pk_add_f32 v[112:113], v[8:9], v[118:119] op_sel:[0,1] op_sel_hi:[1,0] neg_hi:[0,1]
	v_pk_add_f32 v[118:119], v[8:9], v[118:119] op_sel:[0,1] op_sel_hi:[1,0] neg_lo:[0,1]
	v_pk_add_f32 v[8:9], v[98:99], v[6:7]
	v_pk_add_f32 v[6:7], v[98:99], v[6:7] neg_lo:[0,1] neg_hi:[0,1]
	v_pk_add_f32 v[94:95], v[104:105], v[12:13]
	v_pk_add_f32 v[12:13], v[104:105], v[12:13] neg_lo:[0,1] neg_hi:[0,1]
	v_pk_add_f32 v[98:99], v[10:11], v[14:15] op_sel:[0,1] op_sel_hi:[1,0] neg_lo:[0,1]
	v_pk_add_f32 v[104:105], v[18:19], v[100:101]
	v_pk_add_f32 v[100:101], v[18:19], v[100:101] neg_lo:[0,1] neg_hi:[0,1]
	v_pk_add_f32 v[18:19], v[10:11], v[14:15] op_sel:[0,1] op_sel_hi:[1,0] neg_hi:[0,1]
	v_pk_add_f32 v[10:11], v[114:115], v[16:17]
	v_pk_add_f32 v[16:17], v[114:115], v[16:17] neg_lo:[0,1] neg_hi:[0,1]
	v_pk_add_f32 v[14:15], v[102:103], v[86:87]
	v_pk_add_f32 v[86:87], v[102:103], v[86:87] neg_lo:[0,1] neg_hi:[0,1]
	v_pk_add_f32 v[114:115], v[108:109], v[4:5]
	v_pk_add_f32 v[4:5], v[108:109], v[4:5] neg_lo:[0,1] neg_hi:[0,1]
	v_pk_add_f32 v[108:109], v[74:75], v[70:71] op_sel:[0,1] op_sel_hi:[1,0] neg_hi:[0,1]
	v_pk_add_f32 v[70:71], v[74:75], v[70:71] op_sel:[0,1] op_sel_hi:[1,0] neg_lo:[0,1]
	v_pk_add_f32 v[74:75], v[106:107], v[72:73]
	v_pk_add_f32 v[72:73], v[106:107], v[72:73] neg_lo:[0,1] neg_hi:[0,1]
	v_pk_add_f32 v[102:103], v[92:93], v[78:79]
	v_pk_add_f32 v[78:79], v[92:93], v[78:79] neg_lo:[0,1] neg_hi:[0,1]
	v_pk_add_f32 v[106:107], v[76:77], v[88:89]
	v_pk_add_f32 v[88:89], v[76:77], v[88:89] neg_lo:[0,1] neg_hi:[0,1]
	v_pk_add_f32 v[76:77], v[68:69], v[80:81] op_sel:[0,1] op_sel_hi:[1,0] neg_hi:[0,1]
	v_pk_add_f32 v[80:81], v[68:69], v[80:81] op_sel:[0,1] op_sel_hi:[1,0] neg_lo:[0,1]
	v_pk_add_f32 v[68:69], v[110:111], v[82:83]
	v_pk_add_f32 v[82:83], v[110:111], v[82:83] neg_lo:[0,1] neg_hi:[0,1]
	v_pk_add_f32 v[92:93], v[90:91], v[96:97]
	v_pk_add_f32 v[96:97], v[90:91], v[96:97] neg_lo:[0,1] neg_hi:[0,1]
	v_pk_add_f32 v[110:111], v[84:85], v[116:117] op_sel:[0,1] op_sel_hi:[1,0] neg_hi:[0,1]
	v_pk_add_f32 v[116:117], v[84:85], v[116:117] op_sel:[0,1] op_sel_hi:[1,0] neg_lo:[0,1]
	v_pk_add_f32 v[84:85], v[112:113], v[8:9]
	v_pk_add_f32 v[112:113], v[112:113], v[8:9] neg_lo:[0,1] neg_hi:[0,1]
	v_pk_add_f32 v[8:9], v[118:119], v[6:7] op_sel:[0,1] op_sel_hi:[1,0] neg_lo:[0,1]
	v_pk_add_f32 v[90:91], v[118:119], v[6:7] op_sel:[0,1] op_sel_hi:[1,0] neg_hi:[0,1]
	v_pk_add_f32 v[118:119], v[94:95], v[104:105]
	v_pk_add_f32 v[6:7], v[94:95], v[104:105] neg_lo:[0,1] neg_hi:[0,1]
	v_pk_add_f32 v[104:105], v[12:13], v[100:101] op_sel:[0,1] op_sel_hi:[1,0] neg_lo:[0,1]
	v_pk_add_f32 v[94:95], v[12:13], v[100:101] op_sel:[0,1] op_sel_hi:[1,0] neg_hi:[0,1]
	v_pk_add_f32 v[12:13], v[18:19], v[10:11]
	v_pk_add_f32 v[100:101], v[18:19], v[10:11] neg_lo:[0,1] neg_hi:[0,1]
	v_pk_add_f32 v[18:19], v[98:99], v[16:17] op_sel:[0,1] op_sel_hi:[1,0] neg_lo:[0,1]
	v_pk_add_f32 v[10:11], v[98:99], v[16:17] op_sel:[0,1] op_sel_hi:[1,0] neg_hi:[0,1]
	v_pk_add_f32 v[98:99], v[14:15], v[114:115]
	v_pk_add_f32 v[16:17], v[14:15], v[114:115] neg_lo:[0,1] neg_hi:[0,1]
	v_pk_add_f32 v[14:15], v[86:87], v[4:5] op_sel:[0,1] op_sel_hi:[1,0] neg_hi:[0,1]
	v_pk_add_f32 v[4:5], v[86:87], v[4:5] op_sel:[0,1] op_sel_hi:[1,0] neg_lo:[0,1]
	v_pk_add_f32 v[86:87], v[108:109], v[74:75]
	v_pk_add_f32 v[108:109], v[108:109], v[74:75] neg_lo:[0,1] neg_hi:[0,1]
	v_pk_add_f32 v[114:115], v[70:71], v[72:73] op_sel:[0,1] op_sel_hi:[1,0] neg_lo:[0,1]
; #define SINCOSPI(x, s, c) do { const float hx_ = 0.5f * (x); *(s) = __builtin_amdgcn_sinf(hx_); *(c) = __builtin_amdgcn_cosf(hx_); } while (0)
; DEV void fft_f2(LAS cf* buf, int t8) {
;     ...
;     dft_regs<32, false>(v);
;     float sn, cs; SINCOSPI(-(float)(t8 & 15) * (2.0f / 512.0f), &sn, &cs);
;     const cf w = cf{cs, sn}; cf wp = cf{1.f, 0.f};
; #pragma unroll
;     for (int p = 0; p < 32; ++p) { pb[17 * p] = cmul(v[BR32[p]], wp); wp = cmul(wp, w); }
	v_pk_add_f32 v[74:75], v[70:71], v[72:73] op_sel:[0,1] op_sel_hi:[1,0] neg_hi:[0,1]
	v_pk_add_f32 v[70:71], v[102:103], v[106:107]
	v_pk_add_f32 v[72:73], v[102:103], v[106:107] neg_lo:[0,1] neg_hi:[0,1]
	v_pk_add_f32 v[106:107], v[78:79], v[88:89] op_sel:[0,1] op_sel_hi:[1,0] neg_lo:[0,1]
	v_pk_add_f32 v[102:103], v[78:79], v[88:89] op_sel:[0,1] op_sel_hi:[1,0] neg_hi:[0,1]
	v_pk_add_f32 v[78:79], v[76:77], v[68:69]
	v_pk_add_f32 v[88:89], v[76:77], v[68:69] neg_lo:[0,1] neg_hi:[0,1]
	v_pk_add_f32 v[76:77], v[80:81], v[82:83] op_sel:[0,1] op_sel_hi:[1,0] neg_lo:[0,1]
	v_pk_add_f32 v[68:69], v[80:81], v[82:83] op_sel:[0,1] op_sel_hi:[1,0] neg_hi:[0,1]
	v_mov_b32_e32 v80, v76
	v_mov_b32_e32 v81, v77
	v_pk_mul_f32 v[82:83], v[92:93], v[66:67] op_sel:[1,1] op_sel_hi:[1,0] neg_lo:[1,0]
	v_pk_fma_f32 v[92:93], v[92:93], v[66:67], v[82:83] op_sel_hi:[0,1,1]
	v_sin_f32_e32 v77, v3
	v_cos_f32_e32 v76, v3
	s_nop 0
	v_pk_mul_f32 v[82:83], v[66:67], v[76:77] op_sel:[1,1] op_sel_hi:[1,0] neg_lo:[1,0]
	v_pk_fma_f32 v[120:121], v[66:67], v[76:77], v[82:83] op_sel_hi:[0,1,1]
	v_pk_mul_f32 v[82:83], v[98:99], v[120:121] op_sel:[1,1] op_sel_hi:[1,0] neg_lo:[1,0]
	v_pk_fma_f32 v[98:99], v[98:99], v[120:121], v[82:83] op_sel_hi:[0,1,1]
	ds_write2_b64 v2, v[92:93], v[98:99] offset1:17
	v_pk_mul_f32 v[98:99], v[120:121], v[76:77] op_sel:[1,1] op_sel_hi:[1,0] neg_lo:[1,0]
	v_pk_fma_f32 v[82:83], v[120:121], v[76:77], v[98:99] op_sel_hi:[0,1,1]
	v_pk_mul_f32 v[98:99], v[118:119], v[82:83] op_sel:[1,1] op_sel_hi:[1,0] neg_lo:[1,0]
	v_pk_fma_f32 v[118:119], v[118:119], v[82:83], v[98:99] op_sel_hi:[0,1,1]
	v_pk_mul_f32 v[98:99], v[82:83], v[76:77] op_sel:[1,1] op_sel_hi:[1,0] neg_lo:[1,0]
	v_pk_fma_f32 v[82:83], v[82:83], v[76:77], v[98:99] op_sel_hi:[0,1,1]
	v_pk_mul_f32 v[92:93], v[70:71], v[82:83] op_sel:[1,1] op_sel_hi:[1,0] neg_lo:[1,0]
	v_pk_fma_f32 v[98:99], v[70:71], v[82:83], v[92:93] op_sel_hi:[0,1,1]
	ds_write2_b64 v2, v[118:119], v[98:99] offset0:34 offset1:51
	v_pk_mul_f32 v[118:119], v[82:83], v[76:77] op_sel:[1,1] op_sel_hi:[1,0] neg_lo:[1,0]
	v_pk_fma_f32 v[98:99], v[82:83], v[76:77], v[118:119] op_sel_hi:[0,1,1]
	v_pk_mul_f32 v[118:119], v[84:85], v[98:99] op_sel:[1,1] op_sel_hi:[1,0] neg_lo:[1,0]
	v_pk_fma_f32 v[84:85], v[84:85], v[98:99], v[118:119] op_sel_hi:[0,1,1]
	v_pk_mul_f32 v[118:119], v[98:99], v[76:77] op_sel:[1,1] op_sel_hi:[1,0] neg_lo:[1,0]
	v_pk_fma_f32 v[98:99], v[98:99], v[76:77], v[118:119] op_sel_hi:[0,1,1]
	v_pk_mul_f32 v[70:71], v[86:87], v[98:99] op_sel:[1,1] op_sel_hi:[1,0] neg_lo:[1,0]
	v_pk_fma_f32 v[118:119], v[86:87], v[98:99], v[70:71] op_sel_hi:[0,1,1]
	ds_write2_b64 v2, v[84:85], v[118:119] offset0:68 offset1:85
	v_pk_mul_f32 v[84:85], v[98:99], v[76:77] op_sel:[1,1] op_sel_hi:[1,0] neg_lo:[1,0]
	v_pk_fma_f32 v[118:119], v[98:99], v[76:77], v[84:85] op_sel_hi:[0,1,1]
	v_pk_mul_f32 v[98:99], v[12:13], v[118:119] op_sel:[1,1] op_sel_hi:[1,0] neg_lo:[1,0]
	v_pk_fma_f32 v[84:85], v[12:13], v[118:119], v[98:99] op_sel_hi:[0,1,1]
	v_pk_mul_f32 v[12:13], v[118:119], v[76:77] op_sel:[1,1] op_sel_hi:[1,0] neg_lo:[1,0]
	v_pk_fma_f32 v[118:119], v[118:119], v[76:77], v[12:13] op_sel_hi:[0,1,1]
	v_pk_mul_f32 v[98:99], v[78:79], v[118:119] op_sel:[1,1] op_sel_hi:[1,0] neg_lo:[1,0]
	v_pk_fma_f32 v[12:13], v[78:79], v[118:119], v[98:99] op_sel_hi:[0,1,1]
	ds_write2_b64 v2, v[84:85], v[12:13] offset0:102 offset1:119
	v_pk_mul_f32 v[84:85], v[118:119], v[76:77] op_sel:[1,1] op_sel_hi:[1,0] neg_lo:[1,0]
	v_pk_fma_f32 v[12:13], v[118:119], v[76:77], v[84:85] op_sel_hi:[0,1,1]
	v_pk_mul_f32 v[118:119], v[110:111], v[12:13] op_sel:[1,1] op_sel_hi:[1,0] neg_lo:[1,0]
	v_pk_fma_f32 v[84:85], v[110:111], v[12:13], v[118:119] op_sel_hi:[0,1,1]
	v_pk_mul_f32 v[110:111], v[12:13], v[76:77] op_sel:[1,1] op_sel_hi:[1,0] neg_lo:[1,0]
	v_pk_fma_f32 v[12:13], v[12:13], v[76:77], v[110:111] op_sel_hi:[0,1,1]
	v_pk_mul_f32 v[118:119], v[14:15], v[12:13] op_sel:[1,1] op_sel_hi:[1,0] neg_lo:[1,0]
	v_pk_fma_f32 v[110:111], v[14:15], v[12:13], v[118:119] op_sel_hi:[0,1,1]
	ds_write2_b64 v2, v[84:85], v[110:111] offset0:136 offset1:153
	v_pk_mul_f32 v[84:85], v[12:13], v[76:77] op_sel:[1,1] op_sel_hi:[1,0] neg_lo:[1,0]
	v_pk_fma_f32 v[110:111], v[12:13], v[76:77], v[84:85] op_sel_hi:[0,1,1]
	v_pk_mul_f32 v[84:85], v[94:95], v[110:111] op_sel:[1,1] op_sel_hi:[1,0] neg_lo:[1,0]
	v_pk_fma_f32 v[94:95], v[94:95], v[110:111], v[84:85] op_sel_hi:[0,1,1]
	v_pk_mul_f32 v[84:85], v[110:111], v[76:77] op_sel:[1,1] op_sel_hi:[1,0] neg_lo:[1,0]
	v_pk_fma_f32 v[110:111], v[110:111], v[76:77], v[84:85] op_sel_hi:[0,1,1]
	v_pk_mul_f32 v[12:13], v[102:103], v[110:111] op_sel:[1,1] op_sel_hi:[1,0] neg_lo:[1,0]
	v_pk_fma_f32 v[84:85], v[102:103], v[110:111], v[12:13] op_sel_hi:[0,1,1]
	ds_write2_b64 v2, v[94:95], v[84:85] offset0:170 offset1:187
	v_pk_mul_f32 v[94:95], v[110:111], v[76:77] op_sel:[1,1] op_sel_hi:[1,0] neg_lo:[1,0]
	v_pk_fma_f32 v[84:85], v[110:111], v[76:77], v[94:95] op_sel_hi:[0,1,1]
	v_pk_mul_f32 v[94:95], v[90:91], v[84:85] op_sel:[1,1] op_sel_hi:[1,0] neg_lo:[1,0]
	v_pk_fma_f32 v[90:91], v[90:91], v[84:85], v[94:95] op_sel_hi:[0,1,1]
	v_pk_mul_f32 v[94:95], v[84:85], v[76:77] op_sel:[1,1] op_sel_hi:[1,0] neg_lo:[1,0]
	v_pk_fma_f32 v[84:85], v[84:85], v[76:77], v[94:95] op_sel_hi:[0,1,1]
	v_pk_mul_f32 v[110:111], v[74:75], v[84:85] op_sel:[1,1] op_sel_hi:[1,0] neg_lo:[1,0]
	v_pk_fma_f32 v[94:95], v[74:75], v[84:85], v[110:111] op_sel_hi:[0,1,1]
	ds_write2_b64 v2, v[90:91], v[94:95] offset0:204 offset1:221
	v_pk_mul_f32 v[90:91], v[84:85], v[76:77] op_sel:[1,1] op_sel_hi:[1,0] neg_lo:[1,0]
	v_pk_fma_f32 v[94:95], v[84:85], v[76:77], v[90:91] op_sel_hi:[0,1,1]
; #define SINCOSPI(x, s, c) do { const float hx_ = 0.5f * (x); *(s) = __builtin_amdgcn_sinf(hx_); *(c) = __builtin_amdgcn_cosf(hx_); } while (0)
; DEV void fft_f2(LAS cf* buf, int t8) {
;     ...
;     float sn, cs; SINCOSPI(-(float)(t8 & 15) * (2.0f / 512.0f), &sn, &cs);
;     const cf w = cf{cs, sn}; cf wp = cf{1.f, 0.f};
; #pragma unroll
;     for (int p = 0; p < 32; ++p) { pb[17 * p] = cmul(v[BR32[p]], wp); wp = cmul(wp, w); }
	v_pk_mul_f32 v[84:85], v[10:11], v[94:95] op_sel:[1,1] op_sel_hi:[1,0] neg_lo:[1,0]
	v_pk_fma_f32 v[90:91], v[10:11], v[94:95], v[84:85] op_sel_hi:[0,1,1]
	v_pk_mul_f32 v[10:11], v[94:95], v[76:77] op_sel:[1,1] op_sel_hi:[1,0] neg_lo:[1,0]
	v_pk_fma_f32 v[94:95], v[94:95], v[76:77], v[10:11] op_sel_hi:[0,1,1]
	v_pk_mul_f32 v[110:111], v[68:69], v[94:95] op_sel:[1,1] op_sel_hi:[1,0] neg_lo:[1,0]
	v_pk_fma_f32 v[10:11], v[68:69], v[94:95], v[110:111] op_sel_hi:[0,1,1]
	ds_write2_b64 v2, v[90:91], v[10:11] offset0:238 offset1:255
	v_pk_mul_f32 v[2:3], v[94:95], v[76:77] op_sel:[1,1] op_sel_hi:[1,0] neg_lo:[1,0]
	v_pk_fma_f32 v[90:91], v[94:95], v[76:77], v[2:3] op_sel_hi:[0,1,1]
	v_pk_mul_f32 v[94:95], v[96:97], v[90:91] op_sel:[1,1] op_sel_hi:[1,0] neg_lo:[1,0]
	v_pk_fma_f32 v[2:3], v[96:97], v[90:91], v[94:95] op_sel_hi:[0,1,1]
	v_pk_mul_f32 v[94:95], v[90:91], v[76:77] op_sel:[1,1] op_sel_hi:[1,0] neg_lo:[1,0]
	v_pk_fma_f32 v[90:91], v[90:91], v[76:77], v[94:95] op_sel_hi:[0,1,1]
	v_pk_mul_f32 v[10:11], v[16:17], v[90:91] op_sel:[1,1] op_sel_hi:[1,0] neg_lo:[1,0]
	v_pk_fma_f32 v[94:95], v[16:17], v[90:91], v[10:11] op_sel_hi:[0,1,1]
	ds_write2_b64 v0, v[2:3], v[94:95] offset0:16 offset1:33
	v_pk_mul_f32 v[2:3], v[90:91], v[76:77] op_sel:[1,1] op_sel_hi:[1,0] neg_lo:[1,0]
	v_pk_fma_f32 v[90:91], v[90:91], v[76:77], v[2:3] op_sel_hi:[0,1,1]
	v_pk_mul_f32 v[94:95], v[6:7], v[90:91] op_sel:[1,1] op_sel_hi:[1,0] neg_lo:[1,0]
	v_pk_fma_f32 v[2:3], v[6:7], v[90:91], v[94:95] op_sel_hi:[0,1,1]
	v_pk_mul_f32 v[6:7], v[90:91], v[76:77] op_sel:[1,1] op_sel_hi:[1,0] neg_lo:[1,0]
	v_pk_fma_f32 v[90:91], v[90:91], v[76:77], v[6:7] op_sel_hi:[0,1,1]
	v_pk_mul_f32 v[10:11], v[72:73], v[90:91] op_sel:[1,1] op_sel_hi:[1,0] neg_lo:[1,0]
	v_pk_fma_f32 v[6:7], v[72:73], v[90:91], v[10:11] op_sel_hi:[0,1,1]
	ds_write2_b64 v0, v[2:3], v[6:7] offset0:50 offset1:67
	v_pk_mul_f32 v[2:3], v[90:91], v[76:77] op_sel:[1,1] op_sel_hi:[1,0] neg_lo:[1,0]
	v_pk_fma_f32 v[90:91], v[90:91], v[76:77], v[2:3] op_sel_hi:[0,1,1]
	v_pk_mul_f32 v[6:7], v[112:113], v[90:91] op_sel:[1,1] op_sel_hi:[1,0] neg_lo:[1,0]
	v_pk_fma_f32 v[2:3], v[112:113], v[90:91], v[6:7] op_sel_hi:[0,1,1]
	v_pk_mul_f32 v[6:7], v[90:91], v[76:77] op_sel:[1,1] op_sel_hi:[1,0] neg_lo:[1,0]
	v_pk_fma_f32 v[118:119], v[90:91], v[76:77], v[6:7] op_sel_hi:[0,1,1]
	v_pk_mul_f32 v[10:11], v[108:109], v[118:119] op_sel:[1,1] op_sel_hi:[1,0] neg_lo:[1,0]
	v_pk_fma_f32 v[6:7], v[108:109], v[118:119], v[10:11] op_sel_hi:[0,1,1]
	ds_write2_b64 v0, v[2:3], v[6:7] offset0:84 offset1:101
	v_pk_mul_f32 v[2:3], v[118:119], v[76:77] op_sel:[1,1] op_sel_hi:[1,0] neg_lo:[1,0]
	v_pk_fma_f32 v[118:119], v[118:119], v[76:77], v[2:3] op_sel_hi:[0,1,1]
	v_pk_mul_f32 v[6:7], v[100:101], v[118:119] op_sel:[1,1] op_sel_hi:[1,0] neg_lo:[1,0]
	v_pk_fma_f32 v[2:3], v[100:101], v[118:119], v[6:7] op_sel_hi:[0,1,1]
	v_pk_mul_f32 v[6:7], v[118:119], v[76:77] op_sel:[1,1] op_sel_hi:[1,0] neg_lo:[1,0]
	v_pk_fma_f32 v[118:119], v[118:119], v[76:77], v[6:7] op_sel_hi:[0,1,1]
	v_pk_mul_f32 v[10:11], v[88:89], v[118:119] op_sel:[1,1] op_sel_hi:[1,0] neg_lo:[1,0]
	v_pk_fma_f32 v[6:7], v[88:89], v[118:119], v[10:11] op_sel_hi:[0,1,1]
	ds_write2_b64 v0, v[2:3], v[6:7] offset0:118 offset1:135
	v_pk_mul_f32 v[2:3], v[118:119], v[76:77] op_sel:[1,1] op_sel_hi:[1,0] neg_lo:[1,0]
	v_pk_fma_f32 v[118:119], v[118:119], v[76:77], v[2:3] op_sel_hi:[0,1,1]
	v_pk_mul_f32 v[6:7], v[116:117], v[118:119] op_sel:[1,1] op_sel_hi:[1,0] neg_lo:[1,0]
	v_pk_fma_f32 v[2:3], v[116:117], v[118:119], v[6:7] op_sel_hi:[0,1,1]
	v_pk_mul_f32 v[6:7], v[118:119], v[76:77] op_sel:[1,1] op_sel_hi:[1,0] neg_lo:[1,0]
	v_pk_fma_f32 v[118:119], v[118:119], v[76:77], v[6:7] op_sel_hi:[0,1,1]
	v_pk_mul_f32 v[112:113], v[4:5], v[118:119] op_sel:[1,1] op_sel_hi:[1,0] neg_lo:[1,0]
	v_pk_fma_f32 v[6:7], v[4:5], v[118:119], v[112:113] op_sel_hi:[0,1,1]
	ds_write2_b64 v0, v[2:3], v[6:7] offset0:152 offset1:169
	v_pk_mul_f32 v[2:3], v[118:119], v[76:77] op_sel:[1,1] op_sel_hi:[1,0] neg_lo:[1,0]
	v_pk_fma_f32 v[118:119], v[118:119], v[76:77], v[2:3] op_sel_hi:[0,1,1]
	v_pk_mul_f32 v[6:7], v[104:105], v[118:119] op_sel:[1,1] op_sel_hi:[1,0] neg_lo:[1,0]
	v_pk_fma_f32 v[2:3], v[104:105], v[118:119], v[6:7] op_sel_hi:[0,1,1]
	v_pk_mul_f32 v[6:7], v[118:119], v[76:77] op_sel:[1,1] op_sel_hi:[1,0] neg_lo:[1,0]
	v_pk_fma_f32 v[118:119], v[118:119], v[76:77], v[6:7] op_sel_hi:[0,1,1]
	v_pk_mul_f32 v[112:113], v[106:107], v[118:119] op_sel:[1,1] op_sel_hi:[1,0] neg_lo:[1,0]
	v_pk_fma_f32 v[6:7], v[106:107], v[118:119], v[112:113] op_sel_hi:[0,1,1]
	ds_write2_b64 v0, v[2:3], v[6:7] offset0:186 offset1:203
	v_pk_mul_f32 v[2:3], v[118:119], v[76:77] op_sel:[1,1] op_sel_hi:[1,0] neg_lo:[1,0]
	v_pk_fma_f32 v[118:119], v[118:119], v[76:77], v[2:3] op_sel_hi:[0,1,1]
	v_pk_mul_f32 v[6:7], v[8:9], v[118:119] op_sel:[1,1] op_sel_hi:[1,0] neg_lo:[1,0]
	v_pk_fma_f32 v[2:3], v[8:9], v[118:119], v[6:7] op_sel_hi:[0,1,1]
	v_pk_mul_f32 v[6:7], v[118:119], v[76:77] op_sel:[1,1] op_sel_hi:[1,0] neg_lo:[1,0]
	v_pk_fma_f32 v[118:119], v[118:119], v[76:77], v[6:7] op_sel_hi:[0,1,1]
	v_pk_mul_f32 v[8:9], v[114:115], v[118:119] op_sel:[1,1] op_sel_hi:[1,0] neg_lo:[1,0]
	v_pk_fma_f32 v[6:7], v[114:115], v[118:119], v[8:9] op_sel_hi:[0,1,1]
	ds_write2_b64 v0, v[2:3], v[6:7] offset0:220 offset1:237
	v_pk_mul_f32 v[2:3], v[118:119], v[76:77] op_sel:[1,1] op_sel_hi:[1,0] neg_lo:[1,0]
	v_pk_fma_f32 v[118:119], v[118:119], v[76:77], v[2:3] op_sel_hi:[0,1,1]
	v_pk_mul_f32 v[6:7], v[18:19], v[118:119] op_sel:[1,1] op_sel_hi:[1,0] neg_lo:[1,0]
	v_pk_fma_f32 v[2:3], v[18:19], v[118:119], v[6:7] op_sel_hi:[0,1,1]
	v_pk_mul_f32 v[6:7], v[118:119], v[76:77] op_sel:[1,1] op_sel_hi:[1,0] neg_lo:[1,0]
	v_pk_fma_f32 v[118:119], v[118:119], v[76:77], v[6:7] op_sel_hi:[0,1,1]
	v_pk_mul_f32 v[6:7], v[80:81], v[118:119] op_sel:[1,1] op_sel_hi:[1,0] neg_lo:[1,0]
	v_pk_fma_f32 v[118:119], v[80:81], v[118:119], v[6:7] op_sel_hi:[0,1,1]
	ds_write2_b64 v1, v[2:3], v[118:119] offset0:126 offset1:143
	s_waitcnt lgkmcnt(0)
	s_barrier
; #define LAS __attribute__((address_space(3)))
; template <int R, bool INV> DEV void dft_regs(cf (&v)[R]) {
; #pragma unroll
;     for (int s = R; s >= 2; s >>= 1) {
;         const int h = s >> 1;
; #pragma unroll
;         for (int b = 0; b < R; b += s) {
; #pragma unroll
;             for (int k = 0; k < h; ++k) {
;                 const cf a = v[b + k], c = v[b + k + h];
;                 v[b + k] = a + c;
;                 const cf d = a - c;
;                 const int m = k * (32 / s);
;                 const float wr = tw_cos(m), wi = INV ? tw_sin(m) : -tw_sin(m);
;                 v[b + k + h] = cf{d.x * wr - d.y * wi, d.x * wi + d.y * wr};
;             }
;         }
;     }
; }
; DEV void fft_midx2(LAS cf* buf0, LAS cf* buf1, const unsigned* Kp, int blk) {
;     const int base = 16 * blk;
;     LAS cf* p0 = buf0 + 17 * blk; LAS cf* p1 = buf1 + 17 * blk;
;     cf v[16], u[16];
; #pragma unroll
;     for (int q = 0; q < 16; ++q) { v[q] = p0[q]; u[q] = p1[q]; }
;     dft_regs<16, false>(v); dft_regs<16, false>(u);
	ds_read2_b64 v[68:71], v161 offset1:1
	ds_read2_b64 v[8:11], v162 offset1:1
	ds_read2_b64 v[72:75], v161 offset0:2 offset1:3
	ds_read2_b64 v[12:15], v162 offset0:2 offset1:3
	ds_read2_b64 v[76:79], v161 offset0:4 offset1:5
	ds_read2_b64 v[0:3], v162 offset0:4 offset1:5
	ds_read2_b64 v[80:83], v161 offset0:6 offset1:7
	ds_read2_b64 v[4:7], v162 offset0:6 offset1:7
	ds_read2_b64 v[84:87], v161 offset0:8 offset1:9
	ds_read2_b64 v[100:103], v162 offset0:8 offset1:9
	ds_read2_b64 v[88:91], v161 offset0:10 offset1:11
	ds_read2_b64 v[104:107], v162 offset0:10 offset1:11
	ds_read2_b64 v[92:95], v161 offset0:12 offset1:13
	ds_read2_b64 v[16:19], v162 offset0:12 offset1:13
	ds_read2_b64 v[96:99], v161 offset0:14 offset1:15
	ds_read2_b64 v[108:111], v162 offset0:14 offset1:15
	s_waitcnt lgkmcnt(7)
	v_pk_add_f32 v[112:113], v[68:69], v[84:85]
	v_pk_add_f32 v[68:69], v[68:69], v[84:85] neg_lo:[0,1] neg_hi:[0,1]
	v_pk_add_f32 v[114:115], v[70:71], v[86:87]
	v_pk_add_f32 v[70:71], v[70:71], v[86:87] neg_lo:[0,1] neg_hi:[0,1]
	v_pk_mul_f32 v[84:85], v[70:71], s[84:85] op_sel_hi:[1,0]
	v_pk_fma_f32 v[86:87], v[70:71], s[16:17], v[84:85] op_sel:[0,0,1] op_sel_hi:[1,0,0] neg_hi:[0,0,1]
	s_waitcnt lgkmcnt(5)
	v_pk_add_f32 v[70:71], v[72:73], v[88:89]
	v_pk_add_f32 v[72:73], v[72:73], v[88:89] neg_lo:[0,1] neg_hi:[0,1]
	v_pk_mul_f32 v[84:85], v[72:73], s[18:19] op_sel_hi:[1,0]
	v_pk_fma_f32 v[88:89], v[72:73], s[18:19], v[84:85] op_sel:[0,0,1] op_sel_hi:[1,0,0]
	v_pk_fma_f32 v[72:73], v[72:73], s[18:19], v[84:85] op_sel_hi:[1,0,0] neg_lo:[0,0,1] neg_hi:[0,0,1]
	v_pk_add_f32 v[84:85], v[74:75], v[90:91]
	v_pk_add_f32 v[74:75], v[74:75], v[90:91] neg_lo:[0,1] neg_hi:[0,1]
	v_mov_b32_e32 v89, v73
	v_pk_mul_f32 v[90:91], v[74:75], s[16:17] op_sel_hi:[1,0]
	v_pk_fma_f32 v[116:117], v[74:75], s[84:85], v[90:91] op_sel:[0,0,1] op_sel_hi:[1,0,0] neg_hi:[0,0,1]
	s_waitcnt lgkmcnt(3)
	v_pk_add_f32 v[74:75], v[76:77], v[92:93]
	v_pk_add_f32 v[76:77], v[76:77], v[92:93] neg_lo:[0,1] neg_hi:[0,1]
	v_pk_add_f32 v[90:91], v[78:79], v[94:95]
	v_pk_add_f32 v[78:79], v[78:79], v[94:95] neg_lo:[0,1] neg_hi:[0,1]
	s_waitcnt lgkmcnt(1)
	v_pk_add_f32 v[94:95], v[82:83], v[98:99]
	v_pk_mul_f32 v[92:93], v[78:79], s[84:85] op_sel_hi:[0,1]
	v_pk_add_f32 v[82:83], v[82:83], v[98:99] neg_lo:[0,1] neg_hi:[0,1]
	v_pk_fma_f32 v[78:79], v[78:79], s[30:31], v[92:93] op_sel:[1,0,0] neg_lo:[0,0,1] neg_hi:[0,0,1]
	v_pk_add_f32 v[92:93], v[80:81], v[96:97]
	v_pk_add_f32 v[80:81], v[80:81], v[96:97] neg_lo:[0,1] neg_hi:[0,1]
	v_pk_mul_f32 v[96:97], v[82:83], s[24:25] op_sel_hi:[0,1]
	v_pk_fma_f32 v[82:83], v[82:83], s[34:35], v[96:97] op_sel:[1,0,0] neg_lo:[0,0,1] neg_hi:[0,0,1]
	v_pk_add_f32 v[96:97], v[112:113], v[74:75]
	v_pk_add_f32 v[74:75], v[112:113], v[74:75] neg_lo:[0,1] neg_hi:[0,1]
	v_mul_f32_e32 v72, 0x3f3504f3, v80
	v_pk_fma_f32 v[80:81], v[80:81], s[28:29], v[72:73] op_sel:[1,0,0] op_sel_hi:[1,1,0] neg_lo:[0,0,1] neg_hi:[0,0,1]
	v_pk_add_f32 v[72:73], v[88:89], v[80:81]
	v_pk_add_f32 v[112:113], v[114:115], v[90:91]
	v_pk_add_f32 v[114:115], v[114:115], v[90:91] neg_lo:[0,1] neg_hi:[0,1]
	v_pk_mul_f32 v[90:91], v[114:115], s[18:19] op_sel_hi:[1,0]
	v_pk_fma_f32 v[98:99], v[114:115], s[18:19], v[90:91] op_sel:[0,0,1] op_sel_hi:[1,0,0]
	v_pk_fma_f32 v[114:115], v[114:115], s[18:19], v[90:91] op_sel_hi:[1,0,0] neg_lo:[0,0,1] neg_hi:[0,0,1]
	v_pk_add_f32 v[90:91], v[70:71], v[92:93]
	v_pk_add_f32 v[70:71], v[70:71], v[92:93] neg_lo:[0,1] neg_hi:[0,1]
	v_mov_b32_e32 v99, v115
	v_pk_add_f32 v[92:93], v[84:85], v[94:95]
	v_pk_add_f32 v[84:85], v[84:85], v[94:95] neg_lo:[0,1] neg_hi:[0,1]
	v_pk_add_f32 v[94:95], v[68:69], v[76:77] op_sel:[0,1] op_sel_hi:[1,0] neg_hi:[0,1]
	v_pk_add_f32 v[76:77], v[68:69], v[76:77] op_sel:[0,1] op_sel_hi:[1,0] neg_lo:[0,1]
	v_mul_f32_e32 v114, 0x3f3504f3, v84
	v_pk_fma_f32 v[84:85], v[84:85], s[28:29], v[114:115] op_sel:[1,0,0] op_sel_hi:[1,1,0] neg_lo:[0,0,1] neg_hi:[0,0,1]
	v_pk_add_f32 v[118:119], v[86:87], v[78:79]
	v_pk_add_f32 v[78:79], v[86:87], v[78:79] neg_lo:[0,1] neg_hi:[0,1]
	v_pk_mul_f32 v[86:87], v[78:79], s[18:19] op_sel_hi:[1,0]
	v_pk_fma_f32 v[68:69], v[78:79], s[18:19], v[86:87] op_sel:[0,0,1] op_sel_hi:[1,0,0] neg_hi:[0,0,1]
	v_pk_add_f32 v[78:79], v[88:89], v[80:81] neg_lo:[0,1] neg_hi:[0,1]
	v_pk_add_f32 v[88:89], v[96:97], v[90:91]
	v_pk_add_f32 v[90:91], v[96:97], v[90:91] neg_lo:[0,1] neg_hi:[0,1]
	v_pk_add_f32 v[96:97], v[112:113], v[92:93]
	v_pk_add_f32 v[92:93], v[112:113], v[92:93] neg_lo:[0,1] neg_hi:[0,1]
	v_pk_add_f32 v[80:81], v[116:117], v[82:83]
	v_pk_add_f32 v[82:83], v[116:117], v[82:83] neg_lo:[0,1] neg_hi:[0,1]
	v_pk_add_f32 v[112:113], v[74:75], v[70:71] op_sel:[0,1] op_sel_hi:[1,0] neg_lo:[0,1]
	v_pk_add_f32 v[116:117], v[74:75], v[70:71] op_sel:[0,1] op_sel_hi:[1,0] neg_hi:[0,1]
	v_mul_f32_e32 v114, 0x3f3504f3, v82
	v_pk_fma_f32 v[82:83], v[82:83], s[28:29], v[114:115] op_sel:[1,0,0] op_sel_hi:[1,1,0] neg_lo:[0,0,1] neg_hi:[0,0,1]
	v_pk_add_f32 v[70:71], v[98:99], v[84:85] neg_lo:[0,1] neg_hi:[0,1]
	v_pk_add_f32 v[114:115], v[98:99], v[84:85]
	v_pk_add_f32 v[74:75], v[94:95], v[72:73]
	v_pk_add_f32 v[98:99], v[94:95], v[72:73] neg_lo:[0,1] neg_hi:[0,1]
	v_pk_add_f32 v[122:123], v[76:77], v[78:79] op_sel:[0,1] op_sel_hi:[1,0] neg_hi:[0,1]
	v_pk_add_f32 v[124:125], v[68:69], v[82:83]
	v_pk_add_f32 v[72:73], v[118:119], v[80:81]
	v_pk_add_f32 v[120:121], v[118:119], v[80:81] neg_lo:[0,1] neg_hi:[0,1]
	v_pk_add_f32 v[86:87], v[88:89], v[96:97]
	v_pk_add_f32 v[94:95], v[74:75], v[72:73]
	v_pk_add_f32 v[80:81], v[76:77], v[78:79] op_sel:[0,1] op_sel_hi:[1,0] neg_lo:[0,1]
	v_pk_add_f32 v[72:73], v[74:75], v[72:73] neg_lo:[0,1] neg_hi:[0,1]
; template <int R, bool INV> DEV void dft_regs(cf (&v)[R]) {
; #pragma unroll
;     for (int s = R; s >= 2; s >>= 1) {
;         const int h = s >> 1;
; #pragma unroll
;         for (int b = 0; b < R; b += s) {
; #pragma unroll
;             for (int k = 0; k < h; ++k) {
;                 const cf a = v[b + k], c = v[b + k + h];
;                 v[b + k] = a + c;
;                 const cf d = a - c;
;                 const int m = k * (32 / s);
;                 const float wr = tw_cos(m), wi = INV ? tw_sin(m) : -tw_sin(m);
;                 v[b + k + h] = cf{d.x * wr - d.y * wi, d.x * wi + d.y * wr};
;             }
;         }
;     }
; }
	v_pk_add_f32 v[84:85], v[112:113], v[70:71] op_sel:[0,1] op_sel_hi:[1,0] neg_hi:[0,1]
	v_pk_add_f32 v[74:75], v[8:9], v[100:101]
	v_pk_add_f32 v[76:77], v[68:69], v[82:83] neg_lo:[0,1] neg_hi:[0,1]
	v_pk_add_f32 v[82:83], v[90:91], v[92:93] op_sel:[0,1] op_sel_hi:[1,0] neg_hi:[0,1]
	v_pk_add_f32 v[92:93], v[90:91], v[92:93] op_sel:[0,1] op_sel_hi:[1,0] neg_lo:[0,1]
	v_pk_add_f32 v[90:91], v[88:89], v[96:97] neg_lo:[0,1] neg_hi:[0,1]
	v_pk_add_f32 v[88:89], v[116:117], v[114:115]
	v_pk_add_f32 v[114:115], v[116:117], v[114:115] neg_lo:[0,1] neg_hi:[0,1]
	v_mov_b32_e32 v96, v90
	v_mov_b32_e32 v97, v91
	v_mov_b32_e32 v90, v92
	v_mov_b32_e32 v91, v93
	v_mov_b32_e32 v92, v114
	v_mov_b32_e32 v93, v115
	v_pk_add_f32 v[78:79], v[112:113], v[70:71] op_sel:[0,1] op_sel_hi:[1,0] neg_lo:[0,1]
	v_pk_add_f32 v[8:9], v[8:9], v[100:101] neg_lo:[0,1] neg_hi:[0,1]
	v_mov_b32_e32 v114, v78
	v_mov_b32_e32 v115, v79
	v_mov_b32_e32 v78, v72
	v_mov_b32_e32 v79, v73
	v_pk_add_f32 v[118:119], v[98:99], v[120:121] op_sel:[0,1] op_sel_hi:[1,0] neg_hi:[0,1]
	v_pk_add_f32 v[120:121], v[98:99], v[120:121] op_sel:[0,1] op_sel_hi:[1,0] neg_lo:[0,1]
	v_mov_b32_e32 v72, v120
	v_mov_b32_e32 v73, v121
	v_pk_add_f32 v[70:71], v[122:123], v[124:125] neg_lo:[0,1] neg_hi:[0,1]
	v_pk_add_f32 v[68:69], v[122:123], v[124:125]
	v_pk_add_f32 v[98:99], v[80:81], v[76:77] op_sel:[0,1] op_sel_hi:[1,0] neg_lo:[0,1]
	v_pk_add_f32 v[120:121], v[80:81], v[76:77] op_sel:[0,1] op_sel_hi:[1,0] neg_hi:[0,1]
	v_pk_add_f32 v[76:77], v[10:11], v[102:103]
	v_pk_add_f32 v[10:11], v[10:11], v[102:103] neg_lo:[0,1] neg_hi:[0,1]
	v_pk_mul_f32 v[100:101], v[10:11], s[84:85] op_sel_hi:[1,0]
	v_pk_fma_f32 v[102:103], v[10:11], s[16:17], v[100:101] op_sel:[0,0,1] op_sel_hi:[1,0,0] neg_hi:[0,0,1]
	v_pk_add_f32 v[10:11], v[12:13], v[104:105]
	v_pk_add_f32 v[12:13], v[12:13], v[104:105] neg_lo:[0,1] neg_hi:[0,1]
	v_pk_mul_f32 v[100:101], v[12:13], s[18:19] op_sel_hi:[1,0]
	v_pk_fma_f32 v[104:105], v[12:13], s[18:19], v[100:101] op_sel:[0,0,1] op_sel_hi:[1,0,0] neg_hi:[0,0,1]
	v_pk_add_f32 v[12:13], v[14:15], v[106:107]
	v_pk_add_f32 v[14:15], v[14:15], v[106:107] neg_lo:[0,1] neg_hi:[0,1]
	v_pk_mul_f32 v[100:101], v[14:15], s[16:17] op_sel_hi:[1,0]
	v_pk_fma_f32 v[106:107], v[14:15], s[84:85], v[100:101] op_sel:[0,0,1] op_sel_hi:[1,0,0] neg_hi:[0,0,1]
	v_pk_add_f32 v[14:15], v[0:1], v[16:17]
	v_pk_add_f32 v[0:1], v[0:1], v[16:17] neg_lo:[0,1] neg_hi:[0,1]
	v_pk_add_f32 v[16:17], v[2:3], v[18:19]
	v_pk_add_f32 v[2:3], v[2:3], v[18:19] neg_lo:[0,1] neg_hi:[0,1]
	v_pk_mul_f32 v[18:19], v[2:3], s[84:85] op_sel_hi:[0,1]
	v_pk_fma_f32 v[2:3], v[2:3], s[30:31], v[18:19] op_sel:[1,0,0] neg_lo:[0,0,1] neg_hi:[0,0,1]
	s_waitcnt lgkmcnt(0)
	v_pk_add_f32 v[18:19], v[4:5], v[108:109]
	v_pk_add_f32 v[4:5], v[4:5], v[108:109] neg_lo:[0,1] neg_hi:[0,1]
	v_mul_f32_e32 v100, 0x3f3504f3, v4
	v_pk_fma_f32 v[4:5], v[4:5], s[28:29], v[100:101] op_sel:[1,0,0] op_sel_hi:[1,1,0] neg_lo:[0,0,1] neg_hi:[0,0,1]
	v_pk_add_f32 v[100:101], v[6:7], v[110:111]
	v_pk_add_f32 v[6:7], v[6:7], v[110:111] neg_lo:[0,1] neg_hi:[0,1]
	v_pk_mul_f32 v[108:109], v[6:7], s[24:25] op_sel_hi:[0,1]
	v_pk_fma_f32 v[6:7], v[6:7], s[34:35], v[108:109] op_sel:[1,0,0] neg_lo:[0,0,1] neg_hi:[0,0,1]
	v_pk_add_f32 v[108:109], v[74:75], v[14:15]
	v_pk_add_f32 v[14:15], v[74:75], v[14:15] neg_lo:[0,1] neg_hi:[0,1]
	v_pk_add_f32 v[74:75], v[76:77], v[16:17]
	v_pk_add_f32 v[16:17], v[76:77], v[16:17] neg_lo:[0,1] neg_hi:[0,1]
	v_pk_mul_f32 v[76:77], v[16:17], s[18:19] op_sel_hi:[1,0]
	v_pk_fma_f32 v[110:111], v[16:17], s[18:19], v[76:77] op_sel:[0,0,1] op_sel_hi:[1,0,0] neg_hi:[0,0,1]
	v_pk_add_f32 v[76:77], v[10:11], v[18:19] neg_lo:[0,1] neg_hi:[0,1]
	v_pk_add_f32 v[16:17], v[10:11], v[18:19]
	v_pk_add_f32 v[10:11], v[12:13], v[100:101]
	v_pk_add_f32 v[12:13], v[12:13], v[100:101] neg_lo:[0,1] neg_hi:[0,1]
	v_mul_f32_e32 v18, 0x3f3504f3, v12
	v_pk_fma_f32 v[12:13], v[12:13], s[28:29], v[18:19] op_sel:[1,0,0] op_sel_hi:[1,1,0] neg_lo:[0,0,1] neg_hi:[0,0,1]
	v_pk_add_f32 v[18:19], v[8:9], v[0:1] op_sel:[0,1] op_sel_hi:[1,0] neg_hi:[0,1]
	v_pk_add_f32 v[0:1], v[8:9], v[0:1] op_sel:[0,1] op_sel_hi:[1,0] neg_lo:[0,1]
	v_pk_add_f32 v[8:9], v[102:103], v[2:3]
	v_pk_add_f32 v[2:3], v[102:103], v[2:3] neg_lo:[0,1] neg_hi:[0,1]
	v_pk_mul_f32 v[100:101], v[2:3], s[18:19] op_sel_hi:[1,0]
	v_pk_fma_f32 v[102:103], v[2:3], s[18:19], v[100:101] op_sel:[0,0,1] op_sel_hi:[1,0,0] neg_hi:[0,0,1]
	v_pk_add_f32 v[2:3], v[104:105], v[4:5]
	v_pk_add_f32 v[4:5], v[104:105], v[4:5] neg_lo:[0,1] neg_hi:[0,1]
	v_pk_add_f32 v[100:101], v[106:107], v[6:7]
	v_pk_add_f32 v[6:7], v[106:107], v[6:7] neg_lo:[0,1] neg_hi:[0,1]
	v_mul_f32_e32 v104, 0x3f3504f3, v6
	v_pk_fma_f32 v[6:7], v[6:7], s[28:29], v[104:105] op_sel:[1,0,0] op_sel_hi:[1,1,0] neg_lo:[0,0,1] neg_hi:[0,0,1]
	v_pk_add_f32 v[104:105], v[108:109], v[16:17]
	v_pk_add_f32 v[16:17], v[108:109], v[16:17] neg_lo:[0,1] neg_hi:[0,1]
	v_pk_add_f32 v[166:167], v[102:103], v[6:7]
	v_pk_add_f32 v[6:7], v[102:103], v[6:7] neg_lo:[0,1] neg_hi:[0,1]
	v_pk_add_f32 v[108:109], v[74:75], v[10:11]
	v_pk_add_f32 v[10:11], v[74:75], v[10:11] neg_lo:[0,1] neg_hi:[0,1]
	v_pk_add_f32 v[74:75], v[10:11], 0 op_sel:[1,0] op_sel_hi:[0,0] neg_hi:[1,0]
	v_pk_add_f32 v[122:123], v[104:105], v[108:109]
	v_pk_add_f32 v[10:11], v[14:15], v[76:77] op_sel:[0,1] op_sel_hi:[1,0] neg_hi:[0,1]
	v_pk_add_f32 v[76:77], v[14:15], v[76:77] op_sel:[0,1] op_sel_hi:[1,0] neg_lo:[0,1]
	v_pk_add_f32 v[108:109], v[104:105], v[108:109] neg_lo:[0,1] neg_hi:[0,1]
	v_pk_add_f32 v[116:117], v[110:111], v[12:13]
	v_pk_add_f32 v[12:13], v[110:111], v[12:13] neg_lo:[0,1] neg_hi:[0,1]
; DEV cf kunpack(unsigned w) { return cf{U2F(w << 16), U2F(w & 0xffff0000u)}; }
; DEV void fft_midx2(LAS cf* buf0, LAS cf* buf1, const unsigned* Kp, int blk) {
;     ...
;     dft_regs<16, false>(v); dft_regs<16, false>(u);
;     cf w[16], x[16];
;     u32x4 kw[4];
; #pragma unroll
;     for (int j = 0; j < 4; ++j) kw[j] = *(const u32x4*)(Kp + base + 4 * j);
; #pragma unroll
;     for (int p = 0; p < 16; ++p) { const cf k = kunpack(kw[p >> 2][p & 3]); w[p] = cmul(v[BR16[p]], k); x[p] = cmul(u[BR16[p]], k); }
	v_pk_add_f32 v[110:111], v[18:19], v[2:3]
	v_pk_add_f32 v[2:3], v[18:19], v[2:3] neg_lo:[0,1] neg_hi:[0,1]
	v_pk_add_f32 v[106:107], v[16:17], v[74:75] neg_lo:[0,1] neg_hi:[0,1]
	v_pk_add_f32 v[124:125], v[8:9], v[100:101]
	v_pk_add_f32 v[100:101], v[8:9], v[100:101] neg_lo:[0,1] neg_hi:[0,1]
	v_pk_add_f32 v[8:9], v[0:1], v[4:5] op_sel:[0,1] op_sel_hi:[1,0] neg_lo:[0,1]
	v_pk_add_f32 v[164:165], v[0:1], v[4:5] op_sel:[0,1] op_sel_hi:[1,0] neg_hi:[0,1]
	v_pk_add_f32 v[18:19], v[10:11], v[116:117] neg_lo:[0,1] neg_hi:[0,1]
	v_pk_add_f32 v[126:127], v[110:111], v[124:125]
	v_pk_add_f32 v[14:15], v[76:77], v[12:13] op_sel:[0,1] op_sel_hi:[1,0] neg_hi:[0,1]
	v_mov_b32_e32 v104, v18
	v_mov_b32_e32 v105, v19
	v_pk_add_f32 v[4:5], v[16:17], v[74:75]
	v_pk_add_f32 v[0:1], v[76:77], v[12:13] op_sel:[0,1] op_sel_hi:[1,0] neg_lo:[0,1]
	v_pk_add_f32 v[76:77], v[8:9], v[6:7] op_sel:[0,1] op_sel_hi:[1,0] neg_hi:[0,1]
	v_pk_add_f32 v[112:113], v[10:11], v[116:117]
	v_pk_add_f32 v[80:81], v[2:3], v[100:101] op_sel:[0,1] op_sel_hi:[1,0] neg_hi:[0,1]
	v_pk_add_f32 v[16:17], v[110:111], v[124:125] neg_lo:[0,1] neg_hi:[0,1]
	s_mov_b32 s28, s95
	s_mov_b32 s29, s94
	v_pk_add_f32 v[110:111], v[2:3], v[100:101] op_sel:[0,1] op_sel_hi:[1,0] neg_lo:[0,1]
	v_pk_add_f32 v[124:125], v[164:165], v[166:167]
	v_pk_add_f32 v[102:103], v[164:165], v[166:167] neg_lo:[0,1] neg_hi:[0,1]
	v_mov_b32_e32 v166, v98
	v_mov_b32_e32 v167, v99
	v_pk_add_f32 v[18:19], v[8:9], v[6:7] op_sel:[0,1] op_sel_hi:[1,0] neg_lo:[0,1]
	s_nop 0
	s_waitcnt vmcnt(0)
	v_lshlrev_b32_e32 v98, 16, v182
	v_and_b32_e32 v99, 0xffff0000, v182
	v_lshlrev_b32_e32 v12, 16, v183
	v_and_b32_e32 v13, 0xffff0000, v183
	v_pk_mul_f32 v[168:169], v[86:87], v[98:99] op_sel:[1,1] op_sel_hi:[1,0] neg_lo:[1,0]
	v_pk_fma_f32 v[164:165], v[86:87], v[98:99], v[168:169] op_sel_hi:[0,1,1]
	v_pk_mul_f32 v[168:169], v[122:123], v[98:99] op_sel:[1,1] op_sel_hi:[1,0] neg_lo:[1,0]
	v_pk_fma_f32 v[86:87], v[122:123], v[98:99], v[168:169] op_sel_hi:[0,1,1]
	v_pk_mul_f32 v[98:99], v[94:95], v[12:13] op_sel:[1,1] op_sel_hi:[1,0] neg_lo:[1,0]
	v_pk_fma_f32 v[94:95], v[94:95], v[12:13], v[98:99] op_sel_hi:[0,1,1]
	v_pk_mul_f32 v[98:99], v[126:127], v[12:13] op_sel:[1,1] op_sel_hi:[1,0] neg_lo:[1,0]
	v_pk_fma_f32 v[12:13], v[126:127], v[12:13], v[98:99] op_sel_hi:[0,1,1]
	v_lshlrev_b32_e32 v98, 16, v184
	v_and_b32_e32 v99, 0xffff0000, v184
	v_lshlrev_b32_e32 v74, 16, v185
	v_and_b32_e32 v75, 0xffff0000, v185
	v_pk_mul_f32 v[126:127], v[88:89], v[98:99] op_sel:[1,1] op_sel_hi:[1,0] neg_lo:[1,0]
	v_pk_fma_f32 v[122:123], v[88:89], v[98:99], v[126:127] op_sel_hi:[0,1,1]
	v_pk_mul_f32 v[126:127], v[112:113], v[98:99] op_sel:[1,1] op_sel_hi:[1,0] neg_lo:[1,0]
	v_pk_fma_f32 v[88:89], v[112:113], v[98:99], v[126:127] op_sel_hi:[0,1,1]
	v_pk_mul_f32 v[98:99], v[68:69], v[74:75] op_sel:[1,1] op_sel_hi:[1,0] neg_lo:[1,0]
	v_pk_fma_f32 v[10:11], v[68:69], v[74:75], v[98:99] op_sel_hi:[0,1,1]
	v_pk_mul_f32 v[98:99], v[124:125], v[74:75] op_sel:[1,1] op_sel_hi:[1,0] neg_lo:[1,0]
	v_pk_fma_f32 v[74:75], v[124:125], v[74:75], v[98:99] op_sel_hi:[0,1,1]
	v_lshlrev_b32_e32 v98, 16, v178
	v_and_b32_e32 v99, 0xffff0000, v178
	v_lshlrev_b32_e32 v68, 16, v179
	v_and_b32_e32 v69, 0xffff0000, v179
	v_pk_mul_f32 v[124:125], v[82:83], v[98:99] op_sel:[1,1] op_sel_hi:[1,0] neg_lo:[1,0]
	v_pk_fma_f32 v[112:113], v[82:83], v[98:99], v[124:125] op_sel_hi:[0,1,1]
	v_pk_mul_f32 v[124:125], v[4:5], v[98:99] op_sel:[1,1] op_sel_hi:[1,0] neg_lo:[1,0]
	v_pk_fma_f32 v[82:83], v[4:5], v[98:99], v[124:125] op_sel_hi:[0,1,1]
	v_pk_mul_f32 v[98:99], v[118:119], v[68:69] op_sel:[1,1] op_sel_hi:[1,0] neg_lo:[1,0]
	v_pk_fma_f32 v[118:119], v[118:119], v[68:69], v[98:99] op_sel_hi:[0,1,1]
	v_pk_mul_f32 v[98:99], v[80:81], v[68:69] op_sel:[1,1] op_sel_hi:[1,0] neg_lo:[1,0]
	v_pk_fma_f32 v[100:101], v[80:81], v[68:69], v[98:99] op_sel_hi:[0,1,1]
	v_lshlrev_b32_e32 v98, 16, v180
	v_and_b32_e32 v99, 0xffff0000, v180
	v_lshlrev_b32_e32 v116, 16, v181
	v_and_b32_e32 v117, 0xffff0000, v181
	v_pk_mul_f32 v[80:81], v[84:85], v[98:99] op_sel:[1,1] op_sel_hi:[1,0] neg_lo:[1,0]
	v_pk_fma_f32 v[68:69], v[84:85], v[98:99], v[80:81] op_sel_hi:[0,1,1]
	v_pk_mul_f32 v[80:81], v[14:15], v[98:99] op_sel:[1,1] op_sel_hi:[1,0] neg_lo:[1,0]
	v_pk_fma_f32 v[84:85], v[14:15], v[98:99], v[80:81] op_sel_hi:[0,1,1]
	v_pk_mul_f32 v[98:99], v[120:121], v[116:117] op_sel:[1,1] op_sel_hi:[1,0] neg_lo:[1,0]
	v_pk_fma_f32 v[80:81], v[120:121], v[116:117], v[98:99] op_sel_hi:[0,1,1]
	v_pk_mul_f32 v[98:99], v[76:77], v[116:117] op_sel:[1,1] op_sel_hi:[1,0] neg_lo:[1,0]
	v_pk_fma_f32 v[116:117], v[76:77], v[116:117], v[98:99] op_sel_hi:[0,1,1]
	v_lshlrev_b32_e32 v98, 16, v174
	v_and_b32_e32 v99, 0xffff0000, v174
	v_pk_mul_f32 v[14:15], v[96:97], v[98:99] op_sel:[1,1] op_sel_hi:[1,0] neg_lo:[1,0]
	v_pk_fma_f32 v[96:97], v[96:97], v[98:99], v[14:15] op_sel_hi:[0,1,1]
	v_lshlrev_b32_e32 v4, 16, v175
	v_pk_mul_f32 v[14:15], v[108:109], v[98:99] op_sel:[1,1] op_sel_hi:[1,0] neg_lo:[1,0]
	v_pk_fma_f32 v[98:99], v[108:109], v[98:99], v[14:15] op_sel_hi:[0,1,1]
	v_and_b32_e32 v5, 0xffff0000, v175
	v_pk_mul_f32 v[108:109], v[78:79], v[4:5] op_sel:[1,1] op_sel_hi:[1,0] neg_lo:[1,0]
	v_pk_fma_f32 v[78:79], v[78:79], v[4:5], v[108:109] op_sel_hi:[0,1,1]
	v_pk_mul_f32 v[14:15], v[16:17], v[4:5] op_sel:[1,1] op_sel_hi:[1,0] neg_lo:[1,0]
	v_pk_fma_f32 v[108:109], v[16:17], v[4:5], v[14:15] op_sel_hi:[0,1,1]
	v_lshlrev_b32_e32 v4, 16, v176
	v_and_b32_e32 v5, 0xffff0000, v176
	v_pk_mul_f32 v[8:9], v[92:93], v[4:5] op_sel:[1,1] op_sel_hi:[1,0] neg_lo:[1,0]
	v_pk_fma_f32 v[14:15], v[92:93], v[4:5], v[8:9] op_sel_hi:[0,1,1]
; DEV cf kunpack(unsigned w) { return cf{U2F(w << 16), U2F(w & 0xffff0000u)}; }
; template <int R, bool INV> DEV void dft_regs(cf (&v)[R]) {
; #pragma unroll
;     for (int s = R; s >= 2; s >>= 1) {
;         const int h = s >> 1;
; #pragma unroll
;         for (int b = 0; b < R; b += s) {
; #pragma unroll
;             for (int k = 0; k < h; ++k) {
;                 const cf a = v[b + k], c = v[b + k + h];
;                 v[b + k] = a + c;
;                 const cf d = a - c;
;                 const int m = k * (32 / s);
;                 const float wr = tw_cos(m), wi = INV ? tw_sin(m) : -tw_sin(m);
;                 v[b + k + h] = cf{d.x * wr - d.y * wi, d.x * wi + d.y * wr};
;             }
;         }
;     }
; }
; DEV void fft_midx2(LAS cf* buf0, LAS cf* buf1, const unsigned* Kp, int blk) {
;     ...
;     for (int p = 0; p < 16; ++p) { const cf k = kunpack(kw[p >> 2][p & 3]); w[p] = cmul(v[BR16[p]], k); x[p] = cmul(u[BR16[p]], k); }
;     dft_regs<16, true>(w); dft_regs<16, true>(x);
	v_pk_mul_f32 v[8:9], v[104:105], v[4:5] op_sel:[1,1] op_sel_hi:[1,0] neg_lo:[1,0]
	v_pk_fma_f32 v[104:105], v[104:105], v[4:5], v[8:9] op_sel_hi:[0,1,1]
	v_lshlrev_b32_e32 v4, 16, v177
	v_and_b32_e32 v5, 0xffff0000, v177
	v_pk_mul_f32 v[8:9], v[70:71], v[4:5] op_sel:[1,1] op_sel_hi:[1,0] neg_lo:[1,0]
	v_pk_fma_f32 v[6:7], v[70:71], v[4:5], v[8:9] op_sel_hi:[0,1,1]
	v_pk_mul_f32 v[70:71], v[102:103], v[4:5] op_sel:[1,1] op_sel_hi:[1,0] neg_lo:[1,0]
	v_pk_fma_f32 v[8:9], v[102:103], v[4:5], v[70:71] op_sel_hi:[0,1,1]
	v_lshlrev_b32_e32 v4, 16, v170
	v_and_b32_e32 v5, 0xffff0000, v170
	v_lshlrev_b32_e32 v16, 16, v171
	v_and_b32_e32 v17, 0xffff0000, v171
	v_pk_mul_f32 v[70:71], v[90:91], v[4:5] op_sel:[1,1] op_sel_hi:[1,0] neg_lo:[1,0]
	v_pk_fma_f32 v[120:121], v[90:91], v[4:5], v[70:71] op_sel_hi:[0,1,1]
	v_pk_mul_f32 v[70:71], v[106:107], v[4:5] op_sel:[1,1] op_sel_hi:[1,0] neg_lo:[1,0]
	v_pk_fma_f32 v[102:103], v[106:107], v[4:5], v[70:71] op_sel_hi:[0,1,1]
	v_pk_mul_f32 v[106:107], v[72:73], v[16:17] op_sel:[1,1] op_sel_hi:[1,0] neg_lo:[1,0]
	v_pk_fma_f32 v[4:5], v[72:73], v[16:17], v[106:107] op_sel_hi:[0,1,1]
	v_pk_mul_f32 v[106:107], v[110:111], v[16:17] op_sel:[1,1] op_sel_hi:[1,0] neg_lo:[1,0]
	v_pk_fma_f32 v[110:111], v[110:111], v[16:17], v[106:107] op_sel_hi:[0,1,1]
	v_lshlrev_b32_e32 v16, 16, v172
	v_and_b32_e32 v17, 0xffff0000, v172
	v_pk_mul_f32 v[72:73], v[114:115], v[16:17] op_sel:[1,1] op_sel_hi:[1,0] neg_lo:[1,0]
	v_pk_fma_f32 v[106:107], v[114:115], v[16:17], v[72:73] op_sel_hi:[0,1,1]
	v_pk_mul_f32 v[114:115], v[0:1], v[16:17] op_sel:[1,1] op_sel_hi:[1,0] neg_lo:[1,0]
	v_pk_fma_f32 v[92:93], v[0:1], v[16:17], v[114:115] op_sel_hi:[0,1,1]
	v_lshlrev_b32_e32 v16, 16, v173
	v_and_b32_e32 v17, 0xffff0000, v173
	v_pk_mul_f32 v[0:1], v[166:167], v[16:17] op_sel:[1,1] op_sel_hi:[1,0] neg_lo:[1,0]
	v_pk_fma_f32 v[2:3], v[166:167], v[16:17], v[0:1] op_sel_hi:[0,1,1]
	v_pk_mul_f32 v[0:1], v[18:19], v[16:17] op_sel:[1,1] op_sel_hi:[1,0] neg_lo:[1,0]
	v_pk_fma_f32 v[18:19], v[18:19], v[16:17], v[0:1] op_sel_hi:[0,1,1]
	v_pk_add_f32 v[0:1], v[164:165], v[96:97]
	v_pk_add_f32 v[16:17], v[164:165], v[96:97] neg_lo:[0,1] neg_hi:[0,1]
	v_pk_add_f32 v[114:115], v[94:95], v[78:79] neg_lo:[0,1] neg_hi:[0,1]
	v_pk_mul_f32 v[96:97], v[114:115], s[84:85] op_sel_hi:[1,0]
	v_pk_add_f32 v[72:73], v[94:95], v[78:79]
	v_pk_fma_f32 v[70:71], v[114:115], s[16:17], v[96:97] op_sel:[0,0,1] op_sel_hi:[1,0,0] neg_lo:[0,0,1]
	v_pk_add_f32 v[114:115], v[122:123], v[14:15]
	v_pk_add_f32 v[14:15], v[122:123], v[14:15] neg_lo:[0,1] neg_hi:[0,1]
	v_pk_mul_f32 v[96:97], v[14:15], s[18:19] op_sel_hi:[1,0]
	v_pk_fma_f32 v[78:79], v[14:15], s[18:19], v[96:97] op_sel:[0,0,1] op_sel_hi:[1,0,0] neg_lo:[0,0,1]
	v_pk_add_f32 v[14:15], v[10:11], v[6:7]
	v_pk_add_f32 v[6:7], v[10:11], v[6:7] neg_lo:[0,1] neg_hi:[0,1]
	v_pk_mul_f32 v[96:97], v[6:7], s[16:17] op_sel_hi:[1,0]
	v_pk_fma_f32 v[94:95], v[6:7], s[84:85], v[96:97] op_sel:[0,0,1] op_sel_hi:[1,0,0] neg_lo:[0,0,1]
	v_pk_add_f32 v[6:7], v[112:113], v[120:121]
	v_pk_add_f32 v[120:121], v[112:113], v[120:121] neg_lo:[0,1] neg_hi:[0,1]
	v_pk_add_f32 v[112:113], v[118:119], v[4:5]
	v_pk_add_f32 v[4:5], v[118:119], v[4:5] neg_lo:[0,1] neg_hi:[0,1]
	v_pk_mul_f32 v[90:91], v[4:5], s[24:25] op_sel:[1,0]
	v_pk_fma_f32 v[4:5], v[4:5], s[0:1], v[90:91] op_sel_hi:[0,1,1] neg_lo:[0,0,1] neg_hi:[0,0,1]
	v_pk_add_f32 v[90:91], v[68:69], v[106:107]
	v_pk_add_f32 v[106:107], v[68:69], v[106:107] neg_lo:[0,1] neg_hi:[0,1]
	v_mul_f32_e32 v10, 0x3f3504f3, v107
	v_pk_fma_f32 v[106:107], v[106:107], s[96:97], v[10:11] op_sel_hi:[0,1,0] neg_lo:[0,0,1] neg_hi:[0,0,1]
	v_pk_add_f32 v[76:77], v[80:81], v[2:3]
	v_pk_add_f32 v[2:3], v[80:81], v[2:3] neg_lo:[0,1] neg_hi:[0,1]
	v_pk_mul_f32 v[80:81], v[2:3], s[84:85] op_sel:[1,0]
	v_pk_fma_f32 v[2:3], v[2:3], s[88:89], v[80:81] op_sel_hi:[0,1,1] neg_lo:[0,0,1] neg_hi:[0,0,1]
	v_pk_add_f32 v[80:81], v[0:1], v[6:7]
	v_pk_add_f32 v[0:1], v[0:1], v[6:7] neg_lo:[0,1] neg_hi:[0,1]
	v_pk_add_f32 v[6:7], v[72:73], v[112:113] neg_lo:[0,1] neg_hi:[0,1]
	v_pk_add_f32 v[68:69], v[72:73], v[112:113]
	v_pk_mul_f32 v[72:73], v[6:7], s[18:19] op_sel_hi:[1,0]
	v_pk_fma_f32 v[112:113], v[6:7], s[18:19], v[72:73] op_sel:[0,0,1] op_sel_hi:[1,0,0] neg_lo:[0,0,1]
	v_pk_add_f32 v[72:73], v[114:115], v[90:91] neg_lo:[0,1] neg_hi:[0,1]
	v_pk_add_f32 v[6:7], v[114:115], v[90:91]
	v_pk_add_f32 v[114:115], v[14:15], v[76:77]
	v_pk_add_f32 v[14:15], v[14:15], v[76:77] neg_lo:[0,1] neg_hi:[0,1]
	v_mul_f32_e32 v90, 0x3f3504f3, v15
	v_pk_fma_f32 v[14:15], v[14:15], s[96:97], v[90:91] op_sel_hi:[0,1,0] neg_lo:[0,0,1] neg_hi:[0,0,1]
	v_pk_add_f32 v[90:91], v[16:17], v[120:121] op_sel:[0,1] op_sel_hi:[1,0] neg_lo:[0,1]
	v_pk_add_f32 v[16:17], v[16:17], v[120:121] op_sel:[0,1] op_sel_hi:[1,0] neg_hi:[0,1]
	v_pk_add_f32 v[76:77], v[70:71], v[4:5]
	v_pk_add_f32 v[4:5], v[70:71], v[4:5] neg_lo:[0,1] neg_hi:[0,1]
	v_pk_mul_f32 v[96:97], v[4:5], s[18:19] op_sel_hi:[1,0]
	v_pk_fma_f32 v[70:71], v[4:5], s[18:19], v[96:97] op_sel:[0,0,1] op_sel_hi:[1,0,0] neg_lo:[0,0,1]
	v_pk_add_f32 v[4:5], v[78:79], v[106:107]
	v_pk_add_f32 v[106:107], v[78:79], v[106:107] neg_lo:[0,1] neg_hi:[0,1]
	v_pk_add_f32 v[10:11], v[90:91], v[4:5]
	v_pk_add_f32 v[96:97], v[106:107], 0 op_sel:[1,0] op_sel_hi:[0,0] neg_lo:[1,0]
	v_pk_add_f32 v[4:5], v[90:91], v[4:5] neg_lo:[0,1] neg_hi:[0,1]
	v_pk_add_f32 v[106:107], v[94:95], v[2:3]
	v_pk_add_f32 v[2:3], v[94:95], v[2:3] neg_lo:[0,1] neg_hi:[0,1]
	v_pk_add_f32 v[118:119], v[76:77], v[106:107]
	v_mul_f32_e32 v78, 0x3f3504f3, v3
	v_pk_fma_f32 v[2:3], v[2:3], s[96:97], v[78:79] op_sel_hi:[0,1,0] neg_lo:[0,0,1] neg_hi:[0,0,1]
; template <int R, bool INV> DEV void dft_regs(cf (&v)[R]) {
; #pragma unroll
;     for (int s = R; s >= 2; s >>= 1) {
;         const int h = s >> 1;
; #pragma unroll
;         for (int b = 0; b < R; b += s) {
; #pragma unroll
;             for (int k = 0; k < h; ++k) {
;                 const cf a = v[b + k], c = v[b + k + h];
;                 v[b + k] = a + c;
;                 const cf d = a - c;
;                 const int m = k * (32 / s);
;                 const float wr = tw_cos(m), wi = INV ? tw_sin(m) : -tw_sin(m);
;                 v[b + k + h] = cf{d.x * wr - d.y * wi, d.x * wi + d.y * wr};
;             }
;         }
;     }
; }
	v_pk_add_f32 v[78:79], v[80:81], v[6:7]
	v_pk_add_f32 v[6:7], v[80:81], v[6:7] neg_lo:[0,1] neg_hi:[0,1]
	v_pk_add_f32 v[122:123], v[70:71], v[2:3]
	v_pk_add_f32 v[2:3], v[70:71], v[2:3] neg_lo:[0,1] neg_hi:[0,1]
	v_pk_add_f32 v[80:81], v[2:3], 0 op_sel:[1,0] op_sel_hi:[0,0] neg_lo:[1,0]
	v_pk_add_f32 v[94:95], v[68:69], v[114:115]
	v_pk_add_f32 v[68:69], v[68:69], v[114:115] neg_lo:[0,1] neg_hi:[0,1]
	v_pk_add_f32 v[120:121], v[16:17], v[96:97]
	v_pk_add_f32 v[114:115], v[0:1], v[72:73] op_sel:[0,1] op_sel_hi:[1,0] neg_lo:[0,1]
	v_pk_add_f32 v[72:73], v[0:1], v[72:73] op_sel:[0,1] op_sel_hi:[1,0] neg_hi:[0,1]
	v_pk_add_f32 v[2:3], v[78:79], v[94:95] neg_lo:[0,1] neg_hi:[0,1]
	v_pk_add_f32 v[70:71], v[112:113], v[14:15]
	v_pk_add_f32 v[0:1], v[112:113], v[14:15] neg_lo:[0,1] neg_hi:[0,1]
	v_pk_add_f32 v[124:125], v[78:79], v[94:95]
	v_pk_add_f32 v[14:15], v[0:1], 0 op_sel:[1,0] op_sel_hi:[0,0] neg_lo:[1,0]
	v_pk_add_f32 v[78:79], v[6:7], v[68:69] op_sel:[0,1] op_sel_hi:[1,0] neg_lo:[0,1]
	v_pk_add_f32 v[90:91], v[76:77], v[106:107] neg_lo:[0,1] neg_hi:[0,1]
	v_pk_add_f32 v[76:77], v[16:17], v[96:97] neg_lo:[0,1] neg_hi:[0,1]
	v_pk_add_f32 v[126:127], v[4:5], v[90:91] op_sel:[0,1] op_sel_hi:[1,0] neg_lo:[0,1]
	v_pk_add_f32 v[16:17], v[4:5], v[90:91] op_sel:[0,1] op_sel_hi:[1,0] neg_hi:[0,1]
	v_pk_add_f32 v[90:91], v[120:121], v[122:123]
	v_pk_add_f32 v[164:165], v[76:77], v[80:81]
	v_mov_b32_e32 v106, v2
	v_mov_b32_e32 v107, v3
	v_mov_b32_e32 v0, v2
	v_mov_b32_e32 v1, v3
	v_pk_add_f32 v[4:5], v[6:7], v[68:69] op_sel:[0,1] op_sel_hi:[1,0] neg_hi:[0,1]
	v_pk_add_f32 v[94:95], v[114:115], v[70:71]
	v_pk_add_f32 v[68:69], v[114:115], v[70:71] neg_lo:[0,1] neg_hi:[0,1]
	v_mov_b32_e32 v2, v4
	v_mov_b32_e32 v3, v5
	v_pk_add_f32 v[112:113], v[72:73], v[14:15]
	v_mov_b32_e32 v70, v68
	v_mov_b32_e32 v71, v69
	v_pk_add_f32 v[6:7], v[72:73], v[14:15] neg_lo:[0,1] neg_hi:[0,1]
	v_pk_add_f32 v[72:73], v[10:11], v[118:119]
	v_pk_add_f32 v[80:81], v[76:77], v[80:81] neg_lo:[0,1] neg_hi:[0,1]
	v_mov_b32_e32 v114, v6
	v_mov_b32_e32 v115, v7
	v_pk_add_f32 v[14:15], v[10:11], v[118:119] neg_lo:[0,1] neg_hi:[0,1]
	v_mov_b32_e32 v10, v14
	v_mov_b32_e32 v11, v15
	v_mov_b32_e32 v118, v14
	v_mov_b32_e32 v119, v15
	v_mov_b32_e32 v107, v1
	v_mov_b32_e32 v96, v16
	v_mov_b32_e32 v97, v17
	v_pk_add_f32 v[14:15], v[120:121], v[122:123] neg_lo:[0,1] neg_hi:[0,1]
	v_mov_b32_e32 v11, v119
	v_mov_b32_e32 v69, v71
	v_mov_b32_e32 v122, v14
	v_mov_b32_e32 v123, v15
	v_mov_b32_e32 v120, v14
	v_mov_b32_e32 v121, v15
	v_pk_add_f32 v[76:77], v[86:87], v[98:99]
	v_pk_add_f32 v[86:87], v[86:87], v[98:99] neg_lo:[0,1] neg_hi:[0,1]
	v_mov_b32_e32 v123, v121
	v_mov_b32_e32 v166, v86
	v_mov_b32_e32 v167, v87
	v_pk_add_f32 v[86:87], v[12:13], v[108:109]
	v_pk_add_f32 v[12:13], v[12:13], v[108:109] neg_lo:[0,1] neg_hi:[0,1]
	v_mov_b32_e32 v17, v97
	v_pk_mul_f32 v[98:99], v[12:13], s[84:85] op_sel_hi:[1,0]
	v_pk_fma_f32 v[108:109], v[12:13], s[16:17], v[98:99] op_sel:[0,0,1] op_sel_hi:[1,0,0] neg_lo:[0,0,1]
	v_pk_add_f32 v[12:13], v[88:89], v[104:105]
	v_pk_add_f32 v[88:89], v[88:89], v[104:105] neg_lo:[0,1] neg_hi:[0,1]
	v_pk_mul_f32 v[98:99], v[88:89], s[18:19] op_sel_hi:[1,0]
	v_pk_fma_f32 v[104:105], v[88:89], s[18:19], v[98:99] op_sel:[0,0,1] op_sel_hi:[1,0,0] neg_lo:[0,0,1]
	v_pk_add_f32 v[88:89], v[74:75], v[8:9]
	v_pk_add_f32 v[74:75], v[74:75], v[8:9] neg_lo:[0,1] neg_hi:[0,1]
	v_pk_mul_f32 v[98:99], v[74:75], s[16:17] op_sel_hi:[1,0]
	v_pk_fma_f32 v[8:9], v[74:75], s[84:85], v[98:99] op_sel:[0,0,1] op_sel_hi:[1,0,0] neg_lo:[0,0,1]
	v_pk_add_f32 v[74:75], v[82:83], v[102:103]
	v_pk_add_f32 v[82:83], v[82:83], v[102:103] neg_lo:[0,1] neg_hi:[0,1]
	v_pk_add_f32 v[102:103], v[116:117], v[18:19]
	v_pk_add_f32 v[116:117], v[116:117], v[18:19] neg_lo:[0,1] neg_hi:[0,1]
	v_pk_mul_f32 v[18:19], v[116:117], s[84:85] op_sel:[1,0]
	v_pk_add_f32 v[98:99], v[100:101], v[110:111]
	v_pk_add_f32 v[100:101], v[100:101], v[110:111] neg_lo:[0,1] neg_hi:[0,1]
	v_pk_fma_f32 v[116:117], v[116:117], s[88:89], v[18:19] op_sel_hi:[0,1,1] neg_lo:[0,0,1] neg_hi:[0,0,1]
	v_pk_add_f32 v[18:19], v[76:77], v[74:75]
	v_pk_add_f32 v[74:75], v[76:77], v[74:75] neg_lo:[0,1] neg_hi:[0,1]
	v_pk_mul_f32 v[110:111], v[100:101], s[24:25] op_sel:[1,0]
	v_pk_fma_f32 v[100:101], v[100:101], s[0:1], v[110:111] op_sel_hi:[0,1,1] neg_lo:[0,0,1] neg_hi:[0,0,1]
	v_pk_add_f32 v[110:111], v[84:85], v[92:93]
	v_pk_add_f32 v[84:85], v[84:85], v[92:93] neg_lo:[0,1] neg_hi:[0,1]
	v_mul_f32_e32 v4, 0x3f3504f3, v85
	v_pk_add_f32 v[92:93], v[86:87], v[98:99]
	v_pk_add_f32 v[98:99], v[86:87], v[98:99] neg_lo:[0,1] neg_hi:[0,1]
	v_pk_fma_f32 v[84:85], v[84:85], s[96:97], v[4:5] op_sel_hi:[0,1,0] neg_lo:[0,0,1] neg_hi:[0,0,1]
	v_pk_mul_f32 v[86:87], v[98:99], s[18:19] op_sel_hi:[1,0]
	v_pk_fma_f32 v[96:97], v[98:99], s[18:19], v[86:87] op_sel:[0,0,1] op_sel_hi:[1,0,0] neg_lo:[0,0,1]
	v_pk_add_f32 v[98:99], v[12:13], v[110:111]
	v_pk_add_f32 v[12:13], v[12:13], v[110:111] neg_lo:[0,1] neg_hi:[0,1]
	v_pk_add_f32 v[110:111], v[166:167], v[82:83] op_sel:[0,1] op_sel_hi:[1,0] neg_lo:[0,1]
	v_pk_add_f32 v[82:83], v[166:167], v[82:83] op_sel:[0,1] op_sel_hi:[1,0] neg_hi:[0,1]
	v_pk_add_f32 v[86:87], v[88:89], v[102:103]
	v_pk_add_f32 v[88:89], v[88:89], v[102:103] neg_lo:[0,1] neg_hi:[0,1]
	v_mul_f32_e32 v4, 0x3f3504f3, v89
	v_pk_fma_f32 v[88:89], v[88:89], s[96:97], v[4:5] op_sel_hi:[0,1,0] neg_lo:[0,0,1] neg_hi:[0,0,1]
	v_pk_add_f32 v[166:167], v[108:109], v[100:101]
	v_pk_add_f32 v[100:101], v[108:109], v[100:101] neg_lo:[0,1] neg_hi:[0,1]
	v_pk_mul_f32 v[108:109], v[100:101], s[18:19] op_sel_hi:[1,0]
; #define LAS __attribute__((address_space(3)))
; #define SINCOSPI(x, s, c) do { const float hx_ = 0.5f * (x); *(s) = __builtin_amdgcn_sinf(hx_); *(c) = __builtin_amdgcn_cosf(hx_); } while (0)
; #define OPAQUE_I(x) asm volatile("" : "+v"(x))
; template <int R, bool INV> DEV void dft_regs(cf (&v)[R]) {
; #pragma unroll
;     for (int s = R; s >= 2; s >>= 1) {
;         const int h = s >> 1;
; #pragma unroll
;         for (int b = 0; b < R; b += s) {
; #pragma unroll
;             for (int k = 0; k < h; ++k) {
;                 const cf a = v[b + k], c = v[b + k + h];
;                 v[b + k] = a + c;
;                 const cf d = a - c;
;                 const int m = k * (32 / s);
;                 const float wr = tw_cos(m), wi = INV ? tw_sin(m) : -tw_sin(m);
;                 v[b + k + h] = cf{d.x * wr - d.y * wi, d.x * wi + d.y * wr};
;             }
;         }
;     }
; }
; DEV void fft_midx2(LAS cf* buf0, LAS cf* buf1, const unsigned* Kp, int blk) {
;     ...
;     dft_regs<16, true>(w); dft_regs<16, true>(x);
; #pragma unroll
;     for (int q = 0; q < 16; ++q) { p0[q] = w[BR16[q]]; p1[q] = x[BR16[q]]; }
; }
; DEV void fft_i2(LAS cf* buf, int t8) {
;     OPAQUE_I(t8);
;     LAS cf* pb = buf + (t8 >> 4) * 544 + (t8 & 15);
;     float sn, cs; SINCOSPI(-(float)(t8 & 15) * (2.0f / 512.0f), &sn, &cs);
;     const cf w = cf{cs, sn}; cf wp = cf{1.f, 0.f};
;     cf v[32];
; #pragma unroll
;     for (int p = 0; p < 32; ++p) { v[p] = cmulc(pb[17 * p], wp); wp = cmul(wp, w); }
	v_pk_fma_f32 v[102:103], v[100:101], s[18:19], v[108:109] op_sel:[0,0,1] op_sel_hi:[1,0,0] neg_lo:[0,0,1]
	v_pk_add_f32 v[108:109], v[18:19], v[98:99]
	v_pk_add_f32 v[100:101], v[104:105], v[84:85]
	v_pk_add_f32 v[84:85], v[104:105], v[84:85] neg_lo:[0,1] neg_hi:[0,1]
	v_pk_add_f32 v[98:99], v[18:19], v[98:99] neg_lo:[0,1] neg_hi:[0,1]
	v_pk_add_f32 v[104:105], v[8:9], v[116:117]
	v_pk_add_f32 v[116:117], v[8:9], v[116:117] neg_lo:[0,1] neg_hi:[0,1]
	v_mul_f32_e32 v4, 0x3f3504f3, v117
	v_pk_add_f32 v[8:9], v[92:93], v[86:87]
	v_pk_add_f32 v[86:87], v[92:93], v[86:87] neg_lo:[0,1] neg_hi:[0,1]
	v_pk_fma_f32 v[116:117], v[116:117], s[96:97], v[4:5] op_sel_hi:[0,1,0] neg_lo:[0,0,1] neg_hi:[0,0,1]
	v_pk_add_f32 v[92:93], v[74:75], v[12:13] op_sel:[0,1] op_sel_hi:[1,0] neg_lo:[0,1]
	v_pk_add_f32 v[12:13], v[74:75], v[12:13] op_sel:[0,1] op_sel_hi:[1,0] neg_hi:[0,1]
	v_pk_add_f32 v[74:75], v[96:97], v[88:89]
	v_pk_add_f32 v[88:89], v[96:97], v[88:89] neg_lo:[0,1] neg_hi:[0,1]
	v_pk_add_f32 v[96:97], v[110:111], v[100:101]
	v_pk_add_f32 v[18:19], v[110:111], v[100:101] neg_lo:[0,1] neg_hi:[0,1]
	v_pk_add_f32 v[100:101], v[82:83], v[84:85] op_sel:[0,1] op_sel_hi:[1,0] neg_hi:[0,1]
	v_pk_add_f32 v[110:111], v[166:167], v[104:105]
	v_pk_add_f32 v[104:105], v[166:167], v[104:105] neg_lo:[0,1] neg_hi:[0,1]
	v_pk_add_f32 v[166:167], v[82:83], v[84:85] op_sel:[0,1] op_sel_hi:[1,0] neg_lo:[0,1]
	v_pk_add_f32 v[82:83], v[102:103], v[116:117]
	v_pk_add_f32 v[116:117], v[102:103], v[116:117] neg_lo:[0,1] neg_hi:[0,1]
	v_pk_add_f32 v[84:85], v[108:109], v[8:9]
	v_pk_add_f32 v[8:9], v[108:109], v[8:9] neg_lo:[0,1] neg_hi:[0,1]
	v_pk_add_f32 v[108:109], v[98:99], v[86:87] op_sel:[0,1] op_sel_hi:[1,0] neg_lo:[0,1]
	v_pk_add_f32 v[86:87], v[98:99], v[86:87] op_sel:[0,1] op_sel_hi:[1,0] neg_hi:[0,1]
	v_pk_add_f32 v[102:103], v[92:93], v[74:75]
	v_pk_add_f32 v[92:93], v[92:93], v[74:75] neg_lo:[0,1] neg_hi:[0,1]
	v_pk_add_f32 v[74:75], v[12:13], v[88:89] op_sel:[0,1] op_sel_hi:[1,0] neg_lo:[0,1]
	v_pk_add_f32 v[88:89], v[12:13], v[88:89] op_sel:[0,1] op_sel_hi:[1,0] neg_hi:[0,1]
	v_pk_add_f32 v[168:169], v[96:97], v[110:111]
	v_pk_add_f32 v[110:111], v[96:97], v[110:111] neg_lo:[0,1] neg_hi:[0,1]
	v_pk_add_f32 v[96:97], v[18:19], v[104:105] op_sel:[0,1] op_sel_hi:[1,0] neg_lo:[0,1]
	v_pk_add_f32 v[104:105], v[18:19], v[104:105] op_sel:[0,1] op_sel_hi:[1,0] neg_hi:[0,1]
	v_mov_b32_e32 v176, v104
	v_mov_b32_e32 v177, v105
	v_pk_add_f32 v[174:175], v[166:167], v[82:83]
	v_pk_add_f32 v[104:105], v[166:167], v[82:83] neg_lo:[0,1] neg_hi:[0,1]
	v_pk_add_f32 v[98:99], v[100:101], v[116:117] op_sel:[0,1] op_sel_hi:[1,0] neg_lo:[0,1]
	v_pk_add_f32 v[116:117], v[100:101], v[116:117] op_sel:[0,1] op_sel_hi:[1,0] neg_hi:[0,1]
	ds_write2_b64 v161, v[124:125], v[72:73] offset1:1
	ds_write2_b64 v162, v[84:85], v[168:169] offset1:1
	ds_write2_b64 v161, v[94:95], v[90:91] offset0:2 offset1:3
	ds_write2_b64 v162, v[102:103], v[174:175] offset0:2 offset1:3
	ds_write2_b64 v161, v[78:79], v[126:127] offset0:4 offset1:5
	ds_write2_b64 v162, v[108:109], v[96:97] offset0:4 offset1:5
	ds_write2_b64 v161, v[112:113], v[164:165] offset0:6 offset1:7
	ds_write2_b64 v162, v[74:75], v[98:99] offset0:6 offset1:7
	ds_write2_b64 v161, v[114:115], v[80:81] offset0:14 offset1:15
	v_mov_b32_e32 v114, v160
	ds_write2_b64 v161, v[106:107], v[10:11] offset0:8 offset1:9
	ds_write2_b64 v162, v[8:9], v[110:111] offset0:8 offset1:9
	ds_write2_b64 v161, v[68:69], v[122:123] offset0:10 offset1:11
	ds_write2_b64 v162, v[92:93], v[104:105] offset0:10 offset1:11
	ds_write2_b64 v161, v[2:3], v[16:17] offset0:12 offset1:13
	ds_write2_b64 v162, v[86:87], v[176:177] offset0:12 offset1:13
	ds_write2_b64 v162, v[88:89], v[116:117] offset0:14 offset1:15
	s_waitcnt lgkmcnt(0)
	s_barrier
	s_lshl_b32 s100, s19, 10
	s_add_i32 s100, s79, s100
	s_ashr_i32 s101, s100, 31
	s_lshl_b64 s[100:101], s[100:101], 13
	v_lshl_add_u64 v[218:219], v[56:57], 0, s[100:101]
	global_load_dwordx4 v[222:225], v[218:219], off
	s_add_u32 s100, s100, 0x1800000
	s_addc_u32 s101, s101, 0
	v_lshl_add_u64 v[220:221], v[56:57], 0, s[100:101]
	global_load_dwordx4 v[226:229], v[220:221], off
	s_add_u32 s100, s100, 0x1800000
	s_addc_u32 s101, s101, 0
	v_lshl_add_u64 v[218:219], v[56:57], 0, s[100:101]
	global_load_dwordx4 v[236:239], v[218:219], off
	s_add_u32 s100, s100, 0x1800000
	s_addc_u32 s101, s101, 0
	v_lshl_add_u64 v[220:221], v[56:57], 0, s[100:101]
	global_load_dwordx4 v[240:243], v[220:221], off
	s_nop 0
	v_lshrrev_b32_e32 v115, 4, v114
	v_and_b32_e32 v114, 15, v114
	v_mul_lo_u32 v115, v115, s15
	v_lshlrev_b32_e32 v2, 3, v114
	v_cvt_f32_ubyte0_e32 v114, v114
	v_add3_u32 v74, v159, v115, v2
	v_mul_f32_e32 v114, 0xbb800000, v114
	v_mul_f32_e32 v114, 0.5, v114
	v_add_u32_e32 v232, 0x800, v74
	v_add_u32_e32 v233, 0xc00, v74
	ds_read2_b64 v[166:169], v74 offset1:17
	ds_read2_b64 v[170:173], v74 offset0:34 offset1:51
	ds_read2_b64 v[174:177], v74 offset0:68 offset1:85
	ds_read2_b64 v[178:181], v74 offset0:102 offset1:119
	ds_read2_b64 v[182:185], v74 offset0:136 offset1:153
	ds_read2_b64 v[186:189], v74 offset0:170 offset1:187
	ds_read2_b64 v[190:193], v74 offset0:204 offset1:221
	ds_read2_b64 v[194:197], v74 offset0:238 offset1:255
	ds_read2_b64 v[198:201], v232 offset0:16 offset1:33
	ds_read2_b64 v[202:205], v232 offset0:50 offset1:67
	ds_read2_b64 v[208:211], v232 offset0:84 offset1:101
	ds_read2_b64 v[214:217], v232 offset0:118 offset1:135
	ds_read2_b64 v[218:221], v232 offset0:152 offset1:169
	v_sin_f32_e32 v115, v114
	v_cos_f32_e32 v114, v114
	s_waitcnt lgkmcnt(12)
; #define LAS __attribute__((address_space(3)))
; #define SINCOSPI(x, s, c) do { const float hx_ = 0.5f * (x); *(s) = __builtin_amdgcn_sinf(hx_); *(c) = __builtin_amdgcn_cosf(hx_); } while (0)
; #define OPAQUE_I(x) asm volatile("" : "+v"(x))
; DEV void fft_i2(LAS cf* buf, int t8) {
;     OPAQUE_I(t8);
;     LAS cf* pb = buf + (t8 >> 4) * 544 + (t8 & 15);
;     float sn, cs; SINCOSPI(-(float)(t8 & 15) * (2.0f / 512.0f), &sn, &cs);
;     const cf w = cf{cs, sn}; cf wp = cf{1.f, 0.f};
;     cf v[32];
; #pragma unroll
;     for (int p = 0; p < 32; ++p) { v[p] = cmulc(pb[17 * p], wp); wp = cmul(wp, w); }
	v_pk_mul_f32 v[2:3], v[166:167], v[66:67] op_sel:[1,1] op_sel_hi:[1,0]
	v_pk_fma_f32 v[4:5], v[166:167], v[66:67], v[2:3] op_sel_hi:[0,1,1] neg_hi:[1,0,0]
	v_add_u32_e32 v75, 0x800, v74
	v_pk_mul_f32 v[2:3], v[66:67], v[114:115] op_sel:[1,1] op_sel_hi:[1,0] neg_lo:[1,0]
	v_pk_fma_f32 v[8:9], v[66:67], v[114:115], v[2:3] op_sel_hi:[0,1,1]
	v_pk_mul_f32 v[10:11], v[168:169], v[8:9] op_sel:[1,1] op_sel_hi:[1,0]
	v_pk_fma_f32 v[2:3], v[168:169], v[8:9], v[10:11] op_sel_hi:[0,1,1] neg_hi:[1,0,0]
	v_pk_mul_f32 v[6:7], v[8:9], v[114:115] op_sel:[1,1] op_sel_hi:[1,0] neg_lo:[1,0]
	v_pk_fma_f32 v[12:13], v[8:9], v[114:115], v[6:7] op_sel_hi:[0,1,1]
	ds_read2_b64 v[166:169], v232 offset0:186 offset1:203
	s_waitcnt lgkmcnt(12)
	v_pk_mul_f32 v[14:15], v[170:171], v[12:13] op_sel:[1,1] op_sel_hi:[1,0]
	v_pk_fma_f32 v[10:11], v[170:171], v[12:13], v[14:15] op_sel_hi:[0,1,1] neg_hi:[1,0,0]
	v_pk_mul_f32 v[6:7], v[12:13], v[114:115] op_sel:[1,1] op_sel_hi:[1,0] neg_lo:[1,0]
	v_pk_fma_f32 v[12:13], v[12:13], v[114:115], v[6:7] op_sel_hi:[0,1,1]
	v_pk_mul_f32 v[14:15], v[172:173], v[12:13] op_sel:[1,1] op_sel_hi:[1,0]
	v_pk_fma_f32 v[6:7], v[172:173], v[12:13], v[14:15] op_sel_hi:[0,1,1] neg_hi:[1,0,0]
	v_pk_mul_f32 v[8:9], v[12:13], v[114:115] op_sel:[1,1] op_sel_hi:[1,0] neg_lo:[1,0]
	v_pk_fma_f32 v[16:17], v[12:13], v[114:115], v[8:9] op_sel_hi:[0,1,1]
	ds_read2_b64 v[170:173], v232 offset0:220 offset1:237
	s_waitcnt lgkmcnt(12)
	v_pk_mul_f32 v[8:9], v[174:175], v[16:17] op_sel:[1,1] op_sel_hi:[1,0]
	v_pk_fma_f32 v[12:13], v[174:175], v[16:17], v[8:9] op_sel_hi:[0,1,1] neg_hi:[1,0,0]
	v_pk_mul_f32 v[8:9], v[16:17], v[114:115] op_sel:[1,1] op_sel_hi:[1,0] neg_lo:[1,0]
	v_pk_fma_f32 v[16:17], v[16:17], v[114:115], v[8:9] op_sel_hi:[0,1,1]
	v_pk_mul_f32 v[18:19], v[176:177], v[16:17] op_sel:[1,1] op_sel_hi:[1,0]
	v_pk_fma_f32 v[8:9], v[176:177], v[16:17], v[18:19] op_sel_hi:[0,1,1] neg_hi:[1,0,0]
	v_pk_mul_f32 v[14:15], v[16:17], v[114:115] op_sel:[1,1] op_sel_hi:[1,0] neg_lo:[1,0]
	v_pk_fma_f32 v[68:69], v[16:17], v[114:115], v[14:15] op_sel_hi:[0,1,1]
	ds_read2_b64 v[174:177], v233 offset0:126 offset1:143
	s_waitcnt lgkmcnt(12)
	v_pk_mul_f32 v[14:15], v[178:179], v[68:69] op_sel:[1,1] op_sel_hi:[1,0]
	v_pk_fma_f32 v[16:17], v[178:179], v[68:69], v[14:15] op_sel_hi:[0,1,1] neg_hi:[1,0,0]
	v_pk_mul_f32 v[14:15], v[68:69], v[114:115] op_sel:[1,1] op_sel_hi:[1,0] neg_lo:[1,0]
	v_pk_fma_f32 v[68:69], v[68:69], v[114:115], v[14:15] op_sel_hi:[0,1,1]
	v_pk_mul_f32 v[70:71], v[180:181], v[68:69] op_sel:[1,1] op_sel_hi:[1,0]
	v_pk_fma_f32 v[14:15], v[180:181], v[68:69], v[70:71] op_sel_hi:[0,1,1] neg_hi:[1,0,0]
	v_pk_mul_f32 v[18:19], v[68:69], v[114:115] op_sel:[1,1] op_sel_hi:[1,0] neg_lo:[1,0]
	v_pk_fma_f32 v[72:73], v[68:69], v[114:115], v[18:19] op_sel_hi:[0,1,1]
	s_waitcnt lgkmcnt(11)
	v_pk_mul_f32 v[18:19], v[182:183], v[72:73] op_sel:[1,1] op_sel_hi:[1,0]
	v_pk_fma_f32 v[68:69], v[182:183], v[72:73], v[18:19] op_sel_hi:[0,1,1] neg_hi:[1,0,0]
	v_pk_mul_f32 v[18:19], v[72:73], v[114:115] op_sel:[1,1] op_sel_hi:[1,0] neg_lo:[1,0]
	v_pk_fma_f32 v[72:73], v[72:73], v[114:115], v[18:19] op_sel_hi:[0,1,1]
	v_pk_mul_f32 v[86:87], v[184:185], v[72:73] op_sel:[1,1] op_sel_hi:[1,0]
	v_pk_fma_f32 v[18:19], v[184:185], v[72:73], v[86:87] op_sel_hi:[0,1,1] neg_hi:[1,0,0]
	v_pk_mul_f32 v[70:71], v[72:73], v[114:115] op_sel:[1,1] op_sel_hi:[1,0] neg_lo:[1,0]
	v_pk_fma_f32 v[76:77], v[72:73], v[114:115], v[70:71] op_sel_hi:[0,1,1]
	s_waitcnt lgkmcnt(10)
	v_pk_mul_f32 v[70:71], v[186:187], v[76:77] op_sel:[1,1] op_sel_hi:[1,0]
	v_pk_fma_f32 v[72:73], v[186:187], v[76:77], v[70:71] op_sel_hi:[0,1,1] neg_hi:[1,0,0]
	v_pk_mul_f32 v[70:71], v[76:77], v[114:115] op_sel:[1,1] op_sel_hi:[1,0] neg_lo:[1,0]
	v_pk_fma_f32 v[76:77], v[76:77], v[114:115], v[70:71] op_sel_hi:[0,1,1]
	v_pk_mul_f32 v[78:79], v[188:189], v[76:77] op_sel:[1,1] op_sel_hi:[1,0]
	v_pk_fma_f32 v[70:71], v[188:189], v[76:77], v[78:79] op_sel_hi:[0,1,1] neg_hi:[1,0,0]
	v_pk_mul_f32 v[86:87], v[76:77], v[114:115] op_sel:[1,1] op_sel_hi:[1,0] neg_lo:[1,0]
	v_pk_fma_f32 v[80:81], v[76:77], v[114:115], v[86:87] op_sel_hi:[0,1,1]
	s_waitcnt lgkmcnt(9)
	v_pk_mul_f32 v[86:87], v[190:191], v[80:81] op_sel:[1,1] op_sel_hi:[1,0]
	v_pk_fma_f32 v[76:77], v[190:191], v[80:81], v[86:87] op_sel_hi:[0,1,1] neg_hi:[1,0,0]
	v_pk_mul_f32 v[86:87], v[80:81], v[114:115] op_sel:[1,1] op_sel_hi:[1,0] neg_lo:[1,0]
	v_pk_fma_f32 v[80:81], v[80:81], v[114:115], v[86:87] op_sel_hi:[0,1,1]
	v_pk_mul_f32 v[82:83], v[192:193], v[80:81] op_sel:[1,1] op_sel_hi:[1,0]
	v_pk_fma_f32 v[86:87], v[192:193], v[80:81], v[82:83] op_sel_hi:[0,1,1] neg_hi:[1,0,0]
	v_pk_mul_f32 v[78:79], v[80:81], v[114:115] op_sel:[1,1] op_sel_hi:[1,0] neg_lo:[1,0]
	v_pk_fma_f32 v[84:85], v[80:81], v[114:115], v[78:79] op_sel_hi:[0,1,1]
	s_waitcnt lgkmcnt(8)
	v_pk_mul_f32 v[78:79], v[194:195], v[84:85] op_sel:[1,1] op_sel_hi:[1,0]
	v_pk_fma_f32 v[80:81], v[194:195], v[84:85], v[78:79] op_sel_hi:[0,1,1] neg_hi:[1,0,0]
	v_pk_mul_f32 v[78:79], v[84:85], v[114:115] op_sel:[1,1] op_sel_hi:[1,0] neg_lo:[1,0]
	v_pk_fma_f32 v[84:85], v[84:85], v[114:115], v[78:79] op_sel_hi:[0,1,1]
	v_pk_mul_f32 v[88:89], v[196:197], v[84:85] op_sel:[1,1] op_sel_hi:[1,0]
	v_pk_fma_f32 v[78:79], v[196:197], v[84:85], v[88:89] op_sel_hi:[0,1,1] neg_hi:[1,0,0]
	v_pk_mul_f32 v[82:83], v[84:85], v[114:115] op_sel:[1,1] op_sel_hi:[1,0] neg_lo:[1,0]
	v_pk_fma_f32 v[92:93], v[84:85], v[114:115], v[82:83] op_sel_hi:[0,1,1]
	s_waitcnt lgkmcnt(7)
; #define LAS __attribute__((address_space(3)))
; #define SINCOSPI(x, s, c) do { const float hx_ = 0.5f * (x); *(s) = __builtin_amdgcn_sinf(hx_); *(c) = __builtin_amdgcn_cosf(hx_); } while (0)
; #define OPAQUE_I(x) asm volatile("" : "+v"(x))
; DEV void fft_i2(LAS cf* buf, int t8) {
;     OPAQUE_I(t8);
;     LAS cf* pb = buf + (t8 >> 4) * 544 + (t8 & 15);
;     float sn, cs; SINCOSPI(-(float)(t8 & 15) * (2.0f / 512.0f), &sn, &cs);
;     const cf w = cf{cs, sn}; cf wp = cf{1.f, 0.f};
;     cf v[32];
; #pragma unroll
;     for (int p = 0; p < 32; ++p) { v[p] = cmulc(pb[17 * p], wp); wp = cmul(wp, w); }
	v_pk_mul_f32 v[82:83], v[198:199], v[92:93] op_sel:[1,1] op_sel_hi:[1,0]
	v_pk_fma_f32 v[84:85], v[198:199], v[92:93], v[82:83] op_sel_hi:[0,1,1] neg_hi:[1,0,0]
	v_pk_mul_f32 v[82:83], v[92:93], v[114:115] op_sel:[1,1] op_sel_hi:[1,0] neg_lo:[1,0]
	v_pk_fma_f32 v[88:89], v[92:93], v[114:115], v[82:83] op_sel_hi:[0,1,1]
	v_pk_mul_f32 v[92:93], v[200:201], v[88:89] op_sel:[1,1] op_sel_hi:[1,0]
	v_pk_fma_f32 v[82:83], v[200:201], v[88:89], v[92:93] op_sel_hi:[0,1,1] neg_hi:[1,0,0]
	v_pk_mul_f32 v[90:91], v[88:89], v[114:115] op_sel:[1,1] op_sel_hi:[1,0] neg_lo:[1,0]
	v_pk_fma_f32 v[92:93], v[88:89], v[114:115], v[90:91] op_sel_hi:[0,1,1]
	s_waitcnt lgkmcnt(6)
	v_pk_mul_f32 v[96:97], v[202:203], v[92:93] op_sel:[1,1] op_sel_hi:[1,0]
	v_pk_fma_f32 v[94:95], v[202:203], v[92:93], v[96:97] op_sel_hi:[0,1,1] neg_hi:[1,0,0]
	v_pk_mul_f32 v[88:89], v[92:93], v[114:115] op_sel:[1,1] op_sel_hi:[1,0] neg_lo:[1,0]
	v_pk_fma_f32 v[92:93], v[92:93], v[114:115], v[88:89] op_sel_hi:[0,1,1]
	v_pk_mul_f32 v[88:89], v[204:205], v[92:93] op_sel:[1,1] op_sel_hi:[1,0]
	v_pk_fma_f32 v[96:97], v[204:205], v[92:93], v[88:89] op_sel_hi:[0,1,1] neg_hi:[1,0,0]
	v_pk_mul_f32 v[88:89], v[92:93], v[114:115] op_sel:[1,1] op_sel_hi:[1,0] neg_lo:[1,0]
	v_pk_fma_f32 v[92:93], v[92:93], v[114:115], v[88:89] op_sel_hi:[0,1,1]
	s_waitcnt lgkmcnt(5)
	v_pk_mul_f32 v[100:101], v[208:209], v[92:93] op_sel:[1,1] op_sel_hi:[1,0]
	v_pk_fma_f32 v[98:99], v[208:209], v[92:93], v[100:101] op_sel_hi:[0,1,1] neg_hi:[1,0,0]
	v_pk_mul_f32 v[88:89], v[92:93], v[114:115] op_sel:[1,1] op_sel_hi:[1,0] neg_lo:[1,0]
	v_pk_fma_f32 v[92:93], v[92:93], v[114:115], v[88:89] op_sel_hi:[0,1,1]
	v_pk_mul_f32 v[88:89], v[210:211], v[92:93] op_sel:[1,1] op_sel_hi:[1,0]
	v_pk_fma_f32 v[100:101], v[210:211], v[92:93], v[88:89] op_sel_hi:[0,1,1] neg_hi:[1,0,0]
	v_pk_mul_f32 v[88:89], v[92:93], v[114:115] op_sel:[1,1] op_sel_hi:[1,0] neg_lo:[1,0]
	v_pk_fma_f32 v[92:93], v[92:93], v[114:115], v[88:89] op_sel_hi:[0,1,1]
	s_waitcnt lgkmcnt(4)
	v_pk_mul_f32 v[104:105], v[214:215], v[92:93] op_sel:[1,1] op_sel_hi:[1,0]
	v_pk_fma_f32 v[102:103], v[214:215], v[92:93], v[104:105] op_sel_hi:[0,1,1] neg_hi:[1,0,0]
	v_pk_mul_f32 v[88:89], v[92:93], v[114:115] op_sel:[1,1] op_sel_hi:[1,0] neg_lo:[1,0]
	v_pk_fma_f32 v[92:93], v[92:93], v[114:115], v[88:89] op_sel_hi:[0,1,1]
	v_pk_mul_f32 v[88:89], v[216:217], v[92:93] op_sel:[1,1] op_sel_hi:[1,0]
	v_pk_fma_f32 v[104:105], v[216:217], v[92:93], v[88:89] op_sel_hi:[0,1,1] neg_hi:[1,0,0]
	v_pk_mul_f32 v[88:89], v[92:93], v[114:115] op_sel:[1,1] op_sel_hi:[1,0] neg_lo:[1,0]
	v_pk_fma_f32 v[92:93], v[92:93], v[114:115], v[88:89] op_sel_hi:[0,1,1]
	s_waitcnt lgkmcnt(3)
	v_pk_mul_f32 v[108:109], v[218:219], v[92:93] op_sel:[1,1] op_sel_hi:[1,0]
	v_pk_fma_f32 v[106:107], v[218:219], v[92:93], v[108:109] op_sel_hi:[0,1,1] neg_hi:[1,0,0]
	v_pk_mul_f32 v[88:89], v[92:93], v[114:115] op_sel:[1,1] op_sel_hi:[1,0] neg_lo:[1,0]
	v_pk_fma_f32 v[92:93], v[92:93], v[114:115], v[88:89] op_sel_hi:[0,1,1]
	v_pk_mul_f32 v[88:89], v[220:221], v[92:93] op_sel:[1,1] op_sel_hi:[1,0]
	v_pk_fma_f32 v[108:109], v[220:221], v[92:93], v[88:89] op_sel_hi:[0,1,1] neg_hi:[1,0,0]
	v_pk_mul_f32 v[88:89], v[92:93], v[114:115] op_sel:[1,1] op_sel_hi:[1,0] neg_lo:[1,0]
	v_pk_fma_f32 v[92:93], v[92:93], v[114:115], v[88:89] op_sel_hi:[0,1,1]
	s_waitcnt lgkmcnt(2)
	v_pk_mul_f32 v[112:113], v[166:167], v[92:93] op_sel:[1,1] op_sel_hi:[1,0]
	v_pk_fma_f32 v[110:111], v[166:167], v[92:93], v[112:113] op_sel_hi:[0,1,1] neg_hi:[1,0,0]
	v_pk_mul_f32 v[88:89], v[92:93], v[114:115] op_sel:[1,1] op_sel_hi:[1,0] neg_lo:[1,0]
	v_pk_fma_f32 v[92:93], v[92:93], v[114:115], v[88:89] op_sel_hi:[0,1,1]
	v_pk_mul_f32 v[88:89], v[168:169], v[92:93] op_sel:[1,1] op_sel_hi:[1,0]
	v_pk_fma_f32 v[112:113], v[168:169], v[92:93], v[88:89] op_sel_hi:[0,1,1] neg_hi:[1,0,0]
	v_pk_mul_f32 v[88:89], v[92:93], v[114:115] op_sel:[1,1] op_sel_hi:[1,0] neg_lo:[1,0]
	v_pk_fma_f32 v[92:93], v[92:93], v[114:115], v[88:89] op_sel_hi:[0,1,1]
	s_waitcnt lgkmcnt(1)
	v_pk_mul_f32 v[116:117], v[170:171], v[92:93] op_sel:[1,1] op_sel_hi:[1,0]
	v_pk_fma_f32 v[0:1], v[170:171], v[92:93], v[116:117] op_sel_hi:[0,1,1] neg_hi:[1,0,0]
	v_pk_mul_f32 v[88:89], v[92:93], v[114:115] op_sel:[1,1] op_sel_hi:[1,0] neg_lo:[1,0]
	v_pk_fma_f32 v[92:93], v[92:93], v[114:115], v[88:89] op_sel_hi:[0,1,1]
	v_pk_mul_f32 v[88:89], v[172:173], v[92:93] op_sel:[1,1] op_sel_hi:[1,0]
	v_pk_fma_f32 v[116:117], v[172:173], v[92:93], v[88:89] op_sel_hi:[0,1,1] neg_hi:[1,0,0]
	v_pk_mul_f32 v[88:89], v[92:93], v[114:115] op_sel:[1,1] op_sel_hi:[1,0] neg_lo:[1,0]
	v_pk_fma_f32 v[118:119], v[92:93], v[114:115], v[88:89] op_sel_hi:[0,1,1]
	v_add_u32_e32 v88, 0xc00, v74
	v_pk_mul_f32 v[120:121], v[118:119], v[114:115] op_sel:[1,1] op_sel_hi:[1,0] neg_lo:[1,0]
	v_pk_fma_f32 v[114:115], v[118:119], v[114:115], v[120:121] op_sel_hi:[0,1,1]
	s_waitcnt lgkmcnt(0)
; template <int R, bool INV> DEV void dft_regs(cf (&v)[R]) {
; #pragma unroll
;     for (int s = R; s >= 2; s >>= 1) {
;         const int h = s >> 1;
; #pragma unroll
;         for (int b = 0; b < R; b += s) {
; #pragma unroll
;             for (int k = 0; k < h; ++k) {
;                 const cf a = v[b + k], c = v[b + k + h];
;                 v[b + k] = a + c;
;                 const cf d = a - c;
;                 const int m = k * (32 / s);
;                 const float wr = tw_cos(m), wi = INV ? tw_sin(m) : -tw_sin(m);
;                 v[b + k + h] = cf{d.x * wr - d.y * wi, d.x * wi + d.y * wr};
;             }
;         }
;     }
; }
	v_pk_mul_f32 v[120:121], v[174:175], v[118:119] op_sel:[1,1] op_sel_hi:[1,0]
	v_pk_fma_f32 v[90:91], v[174:175], v[118:119], v[120:121] op_sel_hi:[0,1,1] neg_hi:[1,0,0]
	v_pk_mul_f32 v[118:119], v[176:177], v[114:115] op_sel:[1,1] op_sel_hi:[1,0]
	v_pk_fma_f32 v[114:115], v[176:177], v[114:115], v[118:119] op_sel_hi:[0,1,1] neg_hi:[1,0,0]
	v_pk_add_f32 v[92:93], v[4:5], v[84:85]
	v_pk_add_f32 v[4:5], v[4:5], v[84:85] neg_lo:[0,1] neg_hi:[0,1]
	v_mov_b32_e32 v118, v4
	v_mov_b32_e32 v119, v5
	v_pk_add_f32 v[4:5], v[2:3], v[82:83]
	v_pk_add_f32 v[2:3], v[2:3], v[82:83] neg_lo:[0,1] neg_hi:[0,1]
	v_pk_mul_f32 v[82:83], v[2:3], s[82:83] op_sel_hi:[1,0]
	v_pk_fma_f32 v[84:85], v[2:3], s[94:95], v[82:83] op_sel:[0,0,1] op_sel_hi:[1,0,0] neg_lo:[0,0,1]
	v_pk_add_f32 v[2:3], v[10:11], v[94:95]
	v_pk_add_f32 v[10:11], v[10:11], v[94:95] neg_lo:[0,1] neg_hi:[0,1]
	v_pk_mul_f32 v[82:83], v[10:11], s[84:85] op_sel_hi:[1,0]
	v_pk_fma_f32 v[94:95], v[10:11], s[16:17], v[82:83] op_sel:[0,0,1] op_sel_hi:[1,0,0] neg_lo:[0,0,1]
	v_pk_add_f32 v[10:11], v[6:7], v[96:97]
	v_pk_add_f32 v[6:7], v[6:7], v[96:97] neg_lo:[0,1] neg_hi:[0,1]
	v_pk_mul_f32 v[82:83], v[6:7], s[4:5] op_sel_hi:[1,0]
	v_pk_fma_f32 v[96:97], v[6:7], s[86:87], v[82:83] op_sel:[0,0,1] op_sel_hi:[1,0,0] neg_lo:[0,0,1]
	v_pk_add_f32 v[6:7], v[12:13], v[98:99]
	v_pk_add_f32 v[12:13], v[12:13], v[98:99] neg_lo:[0,1] neg_hi:[0,1]
	v_pk_mul_f32 v[82:83], v[12:13], s[18:19] op_sel_hi:[1,0]
	v_pk_fma_f32 v[98:99], v[12:13], s[18:19], v[82:83] op_sel:[0,0,1] op_sel_hi:[1,0,0] neg_lo:[0,0,1]
	v_pk_add_f32 v[12:13], v[8:9], v[100:101]
	v_pk_add_f32 v[8:9], v[8:9], v[100:101] neg_lo:[0,1] neg_hi:[0,1]
	v_pk_mul_f32 v[82:83], v[8:9], s[86:87] op_sel_hi:[1,0]
	v_pk_fma_f32 v[100:101], v[8:9], s[4:5], v[82:83] op_sel:[0,0,1] op_sel_hi:[1,0,0] neg_lo:[0,0,1]
	v_pk_add_f32 v[8:9], v[16:17], v[102:103]
	v_pk_add_f32 v[16:17], v[16:17], v[102:103] neg_lo:[0,1] neg_hi:[0,1]
	v_pk_mul_f32 v[82:83], v[16:17], s[16:17] op_sel_hi:[1,0]
	v_pk_fma_f32 v[102:103], v[16:17], s[84:85], v[82:83] op_sel:[0,0,1] op_sel_hi:[1,0,0] neg_lo:[0,0,1]
	v_pk_add_f32 v[16:17], v[14:15], v[104:105]
	v_pk_add_f32 v[14:15], v[14:15], v[104:105] neg_lo:[0,1] neg_hi:[0,1]
	v_pk_mul_f32 v[82:83], v[14:15], s[94:95] op_sel_hi:[1,0]
	v_pk_fma_f32 v[104:105], v[14:15], s[82:83], v[82:83] op_sel:[0,0,1] op_sel_hi:[1,0,0] neg_lo:[0,0,1]
	v_pk_add_f32 v[14:15], v[68:69], v[106:107]
	v_pk_add_f32 v[68:69], v[68:69], v[106:107] neg_lo:[0,1] neg_hi:[0,1]
	v_pk_add_f32 v[82:83], v[18:19], v[108:109]
	v_pk_add_f32 v[18:19], v[18:19], v[108:109] neg_lo:[0,1] neg_hi:[0,1]
	v_pk_mul_f32 v[106:107], v[18:19], s[6:7] op_sel:[1,0]
	s_mov_b32 s6, s87
	v_pk_fma_f32 v[18:19], v[18:19], s[28:29], v[106:107] op_sel_hi:[0,1,1] neg_lo:[0,0,1] neg_hi:[0,0,1]
	v_pk_add_f32 v[106:107], v[72:73], v[110:111]
	v_pk_add_f32 v[72:73], v[72:73], v[110:111] neg_lo:[0,1] neg_hi:[0,1]
	s_mov_b32 s7, s86
	v_pk_mul_f32 v[108:109], v[72:73], s[24:25] op_sel:[1,0]
	v_pk_fma_f32 v[72:73], v[72:73], s[0:1], v[108:109] op_sel_hi:[0,1,1] neg_lo:[0,0,1] neg_hi:[0,0,1]
	v_pk_add_f32 v[108:109], v[70:71], v[112:113]
	v_pk_add_f32 v[70:71], v[70:71], v[112:113] neg_lo:[0,1] neg_hi:[0,1]
	v_pk_mul_f32 v[110:111], v[70:71], s[2:3] op_sel:[1,0]
	s_mov_b32 s2, s11
	v_pk_fma_f32 v[70:71], v[70:71], s[6:7], v[110:111] op_sel_hi:[0,1,1] neg_lo:[0,0,1] neg_hi:[0,0,1]
	v_pk_add_f32 v[110:111], v[76:77], v[0:1]
	v_pk_add_f32 v[76:77], v[76:77], v[0:1] neg_lo:[0,1] neg_hi:[0,1]
	v_mul_f32_e32 v112, 0x3f3504f3, v77
	v_pk_fma_f32 v[76:77], v[76:77], s[96:97], v[112:113] op_sel_hi:[0,1,0] neg_lo:[0,0,1] neg_hi:[0,0,1]
	v_pk_add_f32 v[112:113], v[86:87], v[116:117]
	v_pk_add_f32 v[86:87], v[86:87], v[116:117] neg_lo:[0,1] neg_hi:[0,1]
	v_pk_mul_f32 v[0:1], v[86:87], s[4:5] op_sel:[1,0]
	s_lshl_b32 s5, s19, 10
	v_pk_fma_f32 v[86:87], v[86:87], s[2:3], v[0:1] op_sel_hi:[0,1,1] neg_lo:[0,0,1] neg_hi:[0,0,1]
	v_pk_add_f32 v[0:1], v[80:81], v[90:91]
	v_pk_add_f32 v[80:81], v[80:81], v[90:91] neg_lo:[0,1] neg_hi:[0,1]
	s_mov_b32 s2, s9
	v_pk_mul_f32 v[90:91], v[80:81], s[84:85] op_sel:[1,0]
	s_mov_b32 s3, s82
	v_pk_fma_f32 v[80:81], v[80:81], s[88:89], v[90:91] op_sel_hi:[0,1,1] neg_lo:[0,0,1] neg_hi:[0,0,1]
	v_pk_add_f32 v[90:91], v[78:79], v[114:115]
	v_pk_add_f32 v[114:115], v[78:79], v[114:115] neg_lo:[0,1] neg_hi:[0,1]
	s_add_i32 s6, s79, s5
	v_pk_mul_f32 v[78:79], v[114:115], s[82:83] op_sel:[1,0]
	s_ashr_i32 s7, s6, 31
	v_pk_fma_f32 v[114:115], v[114:115], s[2:3], v[78:79] op_sel_hi:[0,1,1] neg_lo:[0,0,1] neg_hi:[0,0,1]
	v_pk_add_f32 v[78:79], v[92:93], v[14:15]
	v_pk_add_f32 v[14:15], v[92:93], v[14:15] neg_lo:[0,1] neg_hi:[0,1]
	s_lshl_b64 s[2:3], s[6:7], 13
	v_mov_b32_e32 v116, v14
	v_mov_b32_e32 v117, v15
	v_pk_add_f32 v[14:15], v[4:5], v[82:83]
	v_pk_add_f32 v[4:5], v[4:5], v[82:83] neg_lo:[0,1] neg_hi:[0,1]
	v_pk_mul_f32 v[82:83], v[4:5], s[84:85] op_sel_hi:[1,0]
	v_pk_fma_f32 v[92:93], v[4:5], s[16:17], v[82:83] op_sel:[0,0,1] op_sel_hi:[1,0,0] neg_lo:[0,0,1]
	v_pk_add_f32 v[4:5], v[2:3], v[106:107]
	v_pk_add_f32 v[2:3], v[2:3], v[106:107] neg_lo:[0,1] neg_hi:[0,1]
	v_pk_mul_f32 v[82:83], v[2:3], s[18:19] op_sel_hi:[1,0]
	v_pk_fma_f32 v[106:107], v[2:3], s[18:19], v[82:83] op_sel:[0,0,1] op_sel_hi:[1,0,0] neg_lo:[0,0,1]
	v_pk_add_f32 v[2:3], v[10:11], v[108:109]
	v_pk_add_f32 v[10:11], v[10:11], v[108:109] neg_lo:[0,1] neg_hi:[0,1]
	v_pk_mul_f32 v[82:83], v[10:11], s[16:17] op_sel_hi:[1,0]
	v_pk_fma_f32 v[108:109], v[10:11], s[84:85], v[82:83] op_sel:[0,0,1] op_sel_hi:[1,0,0] neg_lo:[0,0,1]
	v_pk_add_f32 v[10:11], v[6:7], v[110:111]
	v_pk_add_f32 v[6:7], v[6:7], v[110:111] neg_lo:[0,1] neg_hi:[0,1]
; template <int R, bool INV> DEV void dft_regs(cf (&v)[R]) {
; #pragma unroll
;     for (int s = R; s >= 2; s >>= 1) {
;         const int h = s >> 1;
; #pragma unroll
;         for (int b = 0; b < R; b += s) {
; #pragma unroll
;             for (int k = 0; k < h; ++k) {
;                 const cf a = v[b + k], c = v[b + k + h];
;                 v[b + k] = a + c;
;                 const cf d = a - c;
;                 const int m = k * (32 / s);
;                 const float wr = tw_cos(m), wi = INV ? tw_sin(m) : -tw_sin(m);
;                 v[b + k + h] = cf{d.x * wr - d.y * wi, d.x * wi + d.y * wr};
;             }
;         }
;     }
; }
	v_pk_add_f32 v[82:83], v[6:7], 0 op_sel:[1,0] op_sel_hi:[0,0] neg_lo:[1,0]
	v_pk_add_f32 v[6:7], v[12:13], v[112:113]
	v_pk_add_f32 v[12:13], v[12:13], v[112:113] neg_lo:[0,1] neg_hi:[0,1]
	v_pk_mul_f32 v[110:111], v[12:13], s[24:25] op_sel:[1,0]
	v_pk_fma_f32 v[12:13], v[12:13], s[0:1], v[110:111] op_sel_hi:[0,1,1] neg_lo:[0,0,1] neg_hi:[0,0,1]
	v_pk_add_f32 v[110:111], v[8:9], v[0:1]
	v_pk_add_f32 v[8:9], v[8:9], v[0:1] neg_lo:[0,1] neg_hi:[0,1]
	v_mul_f32_e32 v112, 0x3f3504f3, v9
	v_pk_fma_f32 v[8:9], v[8:9], s[96:97], v[112:113] op_sel_hi:[0,1,0] neg_lo:[0,0,1] neg_hi:[0,0,1]
	v_pk_add_f32 v[112:113], v[16:17], v[90:91]
	v_pk_add_f32 v[16:17], v[16:17], v[90:91] neg_lo:[0,1] neg_hi:[0,1]
	v_pk_mul_f32 v[90:91], v[16:17], s[84:85] op_sel:[1,0]
	v_pk_fma_f32 v[16:17], v[16:17], s[88:89], v[90:91] op_sel_hi:[0,1,1] neg_lo:[0,0,1] neg_hi:[0,0,1]
	v_pk_add_f32 v[90:91], v[118:119], v[68:69] op_sel:[0,1] op_sel_hi:[1,0] neg_lo:[0,1]
	v_pk_add_f32 v[68:69], v[118:119], v[68:69] op_sel:[0,1] op_sel_hi:[1,0] neg_hi:[0,1]
	v_pk_add_f32 v[118:119], v[84:85], v[18:19]
	v_pk_add_f32 v[18:19], v[84:85], v[18:19] neg_lo:[0,1] neg_hi:[0,1]
	v_pk_mul_f32 v[84:85], v[18:19], s[84:85] op_sel_hi:[1,0]
	v_pk_fma_f32 v[0:1], v[18:19], s[16:17], v[84:85] op_sel:[0,0,1] op_sel_hi:[1,0,0] neg_lo:[0,0,1]
	v_pk_add_f32 v[18:19], v[94:95], v[72:73]
	v_pk_add_f32 v[72:73], v[94:95], v[72:73] neg_lo:[0,1] neg_hi:[0,1]
	v_pk_mul_f32 v[84:85], v[72:73], s[18:19] op_sel_hi:[1,0]
	v_pk_fma_f32 v[94:95], v[72:73], s[18:19], v[84:85] op_sel:[0,0,1] op_sel_hi:[1,0,0] neg_lo:[0,0,1]
	v_pk_add_f32 v[72:73], v[96:97], v[70:71]
	v_pk_add_f32 v[70:71], v[96:97], v[70:71] neg_lo:[0,1] neg_hi:[0,1]
	v_pk_mul_f32 v[84:85], v[70:71], s[16:17] op_sel_hi:[1,0]
	v_pk_fma_f32 v[96:97], v[70:71], s[84:85], v[84:85] op_sel:[0,0,1] op_sel_hi:[1,0,0] neg_lo:[0,0,1]
	v_pk_add_f32 v[70:71], v[98:99], v[76:77]
	v_pk_add_f32 v[76:77], v[98:99], v[76:77] neg_lo:[0,1] neg_hi:[0,1]
	v_pk_add_f32 v[84:85], v[100:101], v[86:87]
	v_pk_add_f32 v[86:87], v[100:101], v[86:87] neg_lo:[0,1] neg_hi:[0,1]
	v_pk_mul_f32 v[98:99], v[86:87], s[24:25] op_sel:[1,0]
	v_pk_fma_f32 v[86:87], v[86:87], s[0:1], v[98:99] op_sel_hi:[0,1,1] neg_lo:[0,0,1] neg_hi:[0,0,1]
	v_pk_add_f32 v[98:99], v[102:103], v[80:81]
	v_pk_add_f32 v[80:81], v[102:103], v[80:81] neg_lo:[0,1] neg_hi:[0,1]
	v_mul_f32_e32 v100, 0x3f3504f3, v81
	v_pk_fma_f32 v[80:81], v[80:81], s[96:97], v[100:101] op_sel_hi:[0,1,0] neg_lo:[0,0,1] neg_hi:[0,0,1]
	v_pk_add_f32 v[100:101], v[104:105], v[114:115]
	v_pk_add_f32 v[114:115], v[104:105], v[114:115] neg_lo:[0,1] neg_hi:[0,1]
	v_pk_mul_f32 v[102:103], v[114:115], s[84:85] op_sel:[1,0]
	v_pk_fma_f32 v[114:115], v[114:115], s[88:89], v[102:103] op_sel_hi:[0,1,1] neg_lo:[0,0,1] neg_hi:[0,0,1]
	v_pk_add_f32 v[102:103], v[78:79], v[10:11]
	v_pk_add_f32 v[10:11], v[78:79], v[10:11] neg_lo:[0,1] neg_hi:[0,1]
	v_mov_b32_e32 v104, v10
	v_mov_b32_e32 v105, v11
	v_pk_add_f32 v[10:11], v[14:15], v[6:7]
	v_pk_add_f32 v[6:7], v[14:15], v[6:7] neg_lo:[0,1] neg_hi:[0,1]
	v_pk_mul_f32 v[14:15], v[6:7], s[18:19] op_sel_hi:[1,0]
	v_pk_fma_f32 v[78:79], v[6:7], s[18:19], v[14:15] op_sel:[0,0,1] op_sel_hi:[1,0,0] neg_lo:[0,0,1]
	v_pk_add_f32 v[6:7], v[4:5], v[110:111]
	v_pk_add_f32 v[4:5], v[4:5], v[110:111] neg_lo:[0,1] neg_hi:[0,1]
	v_pk_add_f32 v[14:15], v[2:3], v[112:113]
	v_pk_add_f32 v[2:3], v[2:3], v[112:113] neg_lo:[0,1] neg_hi:[0,1]
	v_mul_f32_e32 v110, 0x3f3504f3, v3
	v_pk_fma_f32 v[2:3], v[2:3], s[96:97], v[110:111] op_sel_hi:[0,1,0] neg_lo:[0,0,1] neg_hi:[0,0,1]
	v_pk_add_f32 v[110:111], v[116:117], v[82:83]
	v_pk_add_f32 v[82:83], v[116:117], v[82:83] neg_lo:[0,1] neg_hi:[0,1]
	v_pk_add_f32 v[116:117], v[92:93], v[12:13]
	v_pk_add_f32 v[12:13], v[92:93], v[12:13] neg_lo:[0,1] neg_hi:[0,1]
	v_pk_mul_f32 v[92:93], v[12:13], s[18:19] op_sel_hi:[1,0]
	v_pk_fma_f32 v[112:113], v[12:13], s[18:19], v[92:93] op_sel:[0,0,1] op_sel_hi:[1,0,0] neg_lo:[0,0,1]
	v_pk_add_f32 v[12:13], v[106:107], v[8:9]
	v_pk_add_f32 v[8:9], v[106:107], v[8:9] neg_lo:[0,1] neg_hi:[0,1]
	v_pk_add_f32 v[92:93], v[8:9], 0 op_sel:[1,0] op_sel_hi:[0,0] neg_lo:[1,0]
	v_pk_add_f32 v[8:9], v[108:109], v[16:17]
	v_pk_add_f32 v[16:17], v[108:109], v[16:17] neg_lo:[0,1] neg_hi:[0,1]
	v_mul_f32_e32 v106, 0x3f3504f3, v17
	v_pk_fma_f32 v[16:17], v[16:17], s[96:97], v[106:107] op_sel_hi:[0,1,0] neg_lo:[0,0,1] neg_hi:[0,0,1]
	v_pk_add_f32 v[106:107], v[90:91], v[70:71]
	v_pk_add_f32 v[70:71], v[90:91], v[70:71] neg_lo:[0,1] neg_hi:[0,1]
	v_pk_add_f32 v[108:109], v[118:119], v[84:85]
	v_pk_add_f32 v[84:85], v[118:119], v[84:85] neg_lo:[0,1] neg_hi:[0,1]
	v_pk_mul_f32 v[118:119], v[84:85], s[18:19] op_sel_hi:[1,0]
	v_pk_fma_f32 v[90:91], v[84:85], s[18:19], v[118:119] op_sel:[0,0,1] op_sel_hi:[1,0,0] neg_lo:[0,0,1]
	v_pk_add_f32 v[84:85], v[18:19], v[98:99]
	v_pk_add_f32 v[18:19], v[18:19], v[98:99] neg_lo:[0,1] neg_hi:[0,1]
	v_pk_add_f32 v[118:119], v[72:73], v[100:101]
	v_pk_add_f32 v[72:73], v[72:73], v[100:101] neg_lo:[0,1] neg_hi:[0,1]
	v_mul_f32_e32 v98, 0x3f3504f3, v73
	v_pk_fma_f32 v[72:73], v[72:73], s[96:97], v[98:99] op_sel_hi:[0,1,0] neg_lo:[0,0,1] neg_hi:[0,0,1]
	v_pk_add_f32 v[98:99], v[68:69], v[76:77] op_sel:[0,1] op_sel_hi:[1,0] neg_lo:[0,1]
	v_pk_add_f32 v[76:77], v[68:69], v[76:77] op_sel:[0,1] op_sel_hi:[1,0] neg_hi:[0,1]
	v_pk_add_f32 v[68:69], v[0:1], v[86:87]
	v_pk_add_f32 v[86:87], v[0:1], v[86:87] neg_lo:[0,1] neg_hi:[0,1]
	v_pk_mul_f32 v[100:101], v[86:87], s[18:19] op_sel_hi:[1,0]
	v_pk_fma_f32 v[0:1], v[86:87], s[18:19], v[100:101] op_sel:[0,0,1] op_sel_hi:[1,0,0] neg_lo:[0,0,1]
	v_pk_add_f32 v[86:87], v[94:95], v[80:81]
; template <int R, bool INV> DEV void dft_regs(cf (&v)[R]) {
; #pragma unroll
;     for (int s = R; s >= 2; s >>= 1) {
;         const int h = s >> 1;
; #pragma unroll
;         for (int b = 0; b < R; b += s) {
; #pragma unroll
;             for (int k = 0; k < h; ++k) {
;                 const cf a = v[b + k], c = v[b + k + h];
;                 v[b + k] = a + c;
;                 const cf d = a - c;
;                 const int m = k * (32 / s);
;                 const float wr = tw_cos(m), wi = INV ? tw_sin(m) : -tw_sin(m);
;                 v[b + k + h] = cf{d.x * wr - d.y * wi, d.x * wi + d.y * wr};
;             }
;         }
;     }
; }
; DEV void fft_i2(LAS cf* buf, int t8) {
;     ...
;     dft_regs<32, true>(v);
; #pragma unroll
;     for (int q = 0; q < 32; ++q) pb[17 * q] = v[BR32[q]];
	v_pk_add_f32 v[80:81], v[94:95], v[80:81] neg_lo:[0,1] neg_hi:[0,1]
	v_pk_add_f32 v[94:95], v[96:97], v[114:115]
	v_pk_add_f32 v[114:115], v[96:97], v[114:115] neg_lo:[0,1] neg_hi:[0,1]
	v_mul_f32_e32 v96, 0x3f3504f3, v115
	v_pk_fma_f32 v[114:115], v[114:115], s[96:97], v[96:97] op_sel_hi:[0,1,0] neg_lo:[0,0,1] neg_hi:[0,0,1]
	v_pk_add_f32 v[96:97], v[102:103], v[6:7]
	v_pk_add_f32 v[6:7], v[102:103], v[6:7] neg_lo:[0,1] neg_hi:[0,1]
	v_mov_b32_e32 v102, v6
	v_mov_b32_e32 v103, v7
	v_pk_add_f32 v[6:7], v[10:11], v[14:15]
	v_pk_add_f32 v[14:15], v[10:11], v[14:15] neg_lo:[0,1] neg_hi:[0,1]
	v_pk_add_f32 v[10:11], v[14:15], 0 op_sel:[1,0] op_sel_hi:[0,0] neg_lo:[1,0]
	v_pk_add_f32 v[14:15], v[104:105], v[4:5] op_sel:[0,1] op_sel_hi:[1,0] neg_lo:[0,1]
	v_pk_add_f32 v[4:5], v[104:105], v[4:5] op_sel:[0,1] op_sel_hi:[1,0] neg_hi:[0,1]
	v_mov_b32_e32 v104, v4
	v_mov_b32_e32 v105, v5
	v_pk_add_f32 v[4:5], v[78:79], v[2:3]
	v_pk_add_f32 v[2:3], v[78:79], v[2:3] neg_lo:[0,1] neg_hi:[0,1]
	v_pk_add_f32 v[78:79], v[110:111], v[12:13]
	v_pk_add_f32 v[12:13], v[110:111], v[12:13] neg_lo:[0,1] neg_hi:[0,1]
	v_mov_b32_e32 v110, v12
	v_mov_b32_e32 v111, v13
	v_pk_add_f32 v[12:13], v[116:117], v[8:9]
	v_pk_add_f32 v[8:9], v[116:117], v[8:9] neg_lo:[0,1] neg_hi:[0,1]
	v_pk_add_f32 v[116:117], v[82:83], v[92:93]
	v_pk_add_f32 v[92:93], v[82:83], v[92:93] neg_lo:[0,1] neg_hi:[0,1]
	v_mov_b32_e32 v82, v92
	v_mov_b32_e32 v83, v93
	v_pk_add_f32 v[92:93], v[112:113], v[16:17]
	v_pk_add_f32 v[16:17], v[112:113], v[16:17] neg_lo:[0,1] neg_hi:[0,1]
	v_pk_add_f32 v[100:101], v[106:107], v[84:85]
	v_pk_add_f32 v[84:85], v[106:107], v[84:85] neg_lo:[0,1] neg_hi:[0,1]
	v_pk_add_f32 v[112:113], v[108:109], v[118:119]
	v_pk_add_f32 v[118:119], v[108:109], v[118:119] neg_lo:[0,1] neg_hi:[0,1]
	v_pk_add_f32 v[108:109], v[70:71], v[18:19] op_sel:[0,1] op_sel_hi:[1,0] neg_lo:[0,1]
	v_pk_add_f32 v[18:19], v[70:71], v[18:19] op_sel:[0,1] op_sel_hi:[1,0] neg_hi:[0,1]
	v_pk_add_f32 v[70:71], v[90:91], v[72:73]
	v_pk_add_f32 v[72:73], v[90:91], v[72:73] neg_lo:[0,1] neg_hi:[0,1]
	v_pk_add_f32 v[90:91], v[98:99], v[86:87]
	v_pk_add_f32 v[86:87], v[98:99], v[86:87] neg_lo:[0,1] neg_hi:[0,1]
	v_pk_add_f32 v[106:107], v[68:69], v[94:95]
	v_pk_add_f32 v[94:95], v[68:69], v[94:95] neg_lo:[0,1] neg_hi:[0,1]
	v_pk_add_f32 v[68:69], v[76:77], v[80:81] op_sel:[0,1] op_sel_hi:[1,0] neg_lo:[0,1]
	v_pk_add_f32 v[80:81], v[76:77], v[80:81] op_sel:[0,1] op_sel_hi:[1,0] neg_hi:[0,1]
	v_pk_add_f32 v[76:77], v[0:1], v[114:115]
	v_pk_add_f32 v[114:115], v[0:1], v[114:115] neg_lo:[0,1] neg_hi:[0,1]
	v_pk_add_f32 v[98:99], v[114:115], 0 op_sel:[1,0] op_sel_hi:[0,0] neg_lo:[1,0]
	v_pk_add_f32 v[0:1], v[96:97], v[6:7]
	v_pk_add_f32 v[6:7], v[96:97], v[6:7] neg_lo:[0,1] neg_hi:[0,1]
	v_mov_b32_e32 v114, v6
	v_mov_b32_e32 v115, v7
	v_pk_add_f32 v[6:7], v[102:103], v[10:11]
	v_pk_add_f32 v[10:11], v[102:103], v[10:11] neg_lo:[0,1] neg_hi:[0,1]
	v_mov_b32_e32 v102, v10
	v_mov_b32_e32 v103, v11
	v_pk_add_f32 v[10:11], v[14:15], v[4:5]
	v_pk_add_f32 v[14:15], v[14:15], v[4:5] neg_lo:[0,1] neg_hi:[0,1]
	v_mov_b32_e32 v96, v14
	v_mov_b32_e32 v97, v15
	v_pk_add_f32 v[14:15], v[104:105], v[2:3] op_sel:[0,1] op_sel_hi:[1,0] neg_hi:[0,1]
	v_pk_add_f32 v[4:5], v[104:105], v[2:3] op_sel:[0,1] op_sel_hi:[1,0] neg_lo:[0,1]
	v_mov_b32_e32 v104, v14
	v_mov_b32_e32 v105, v15
	v_pk_add_f32 v[14:15], v[78:79], v[12:13]
	v_pk_add_f32 v[2:3], v[78:79], v[12:13] neg_lo:[0,1] neg_hi:[0,1]
	v_mov_b32_e32 v78, v2
	v_mov_b32_e32 v79, v3
	v_pk_add_f32 v[12:13], v[110:111], v[8:9] op_sel:[0,1] op_sel_hi:[1,0] neg_hi:[0,1]
	v_pk_add_f32 v[2:3], v[110:111], v[8:9] op_sel:[0,1] op_sel_hi:[1,0] neg_lo:[0,1]
	v_mov_b32_e32 v110, v12
	v_mov_b32_e32 v111, v13
	v_pk_add_f32 v[12:13], v[116:117], v[92:93]
	v_pk_add_f32 v[8:9], v[116:117], v[92:93] neg_lo:[0,1] neg_hi:[0,1]
	v_mov_b32_e32 v92, v8
	v_mov_b32_e32 v93, v9
	v_pk_add_f32 v[116:117], v[82:83], v[16:17] op_sel:[0,1] op_sel_hi:[1,0] neg_hi:[0,1]
	v_pk_add_f32 v[8:9], v[82:83], v[16:17] op_sel:[0,1] op_sel_hi:[1,0] neg_lo:[0,1]
	v_pk_add_f32 v[82:83], v[100:101], v[112:113]
	v_pk_add_f32 v[16:17], v[100:101], v[112:113] neg_lo:[0,1] neg_hi:[0,1]
	v_pk_add_f32 v[100:101], v[84:85], v[118:119] op_sel:[0,1] op_sel_hi:[1,0] neg_lo:[0,1]
	v_pk_add_f32 v[118:119], v[84:85], v[118:119] op_sel:[0,1] op_sel_hi:[1,0] neg_hi:[0,1]
	v_pk_add_f32 v[84:85], v[108:109], v[70:71]
	v_pk_add_f32 v[108:109], v[108:109], v[70:71] neg_lo:[0,1] neg_hi:[0,1]
	v_pk_add_f32 v[112:113], v[18:19], v[72:73] op_sel:[0,1] op_sel_hi:[1,0] neg_hi:[0,1]
	v_pk_add_f32 v[70:71], v[18:19], v[72:73] op_sel:[0,1] op_sel_hi:[1,0] neg_lo:[0,1]
	v_pk_add_f32 v[18:19], v[90:91], v[106:107]
	v_pk_add_f32 v[72:73], v[90:91], v[106:107] neg_lo:[0,1] neg_hi:[0,1]
	v_pk_add_f32 v[106:107], v[86:87], v[94:95] op_sel:[0,1] op_sel_hi:[1,0] neg_hi:[0,1]
	v_pk_add_f32 v[90:91], v[86:87], v[94:95] op_sel:[0,1] op_sel_hi:[1,0] neg_lo:[0,1]
	v_pk_add_f32 v[86:87], v[68:69], v[76:77]
	v_pk_add_f32 v[94:95], v[68:69], v[76:77] neg_lo:[0,1] neg_hi:[0,1]
	v_pk_add_f32 v[68:69], v[80:81], v[98:99] neg_lo:[0,1] neg_hi:[0,1]
	v_pk_add_f32 v[76:77], v[80:81], v[98:99]
	v_mov_b32_e32 v80, v68
	v_mov_b32_e32 v81, v69
	ds_write2_b64 v74, v[0:1], v[82:83] offset1:17
	ds_write2_b64 v74, v[14:15], v[18:19] offset0:34 offset1:51
	ds_write2_b64 v74, v[10:11], v[84:85] offset0:68 offset1:85
	ds_write2_b64 v74, v[12:13], v[86:87] offset0:102 offset1:119
	ds_write2_b64 v74, v[6:7], v[100:101] offset0:136 offset1:153
	ds_write2_b64 v74, v[2:3], v[90:91] offset0:170 offset1:187
	ds_write2_b64 v74, v[4:5], v[70:71] offset0:204 offset1:221
	ds_write2_b64 v74, v[8:9], v[76:77] offset0:238 offset1:255
	ds_write2_b64 v75, v[114:115], v[16:17] offset0:16 offset1:33
	ds_write2_b64 v75, v[78:79], v[72:73] offset0:50 offset1:67
	ds_write2_b64 v75, v[96:97], v[108:109] offset0:84 offset1:101
	ds_write2_b64 v75, v[92:93], v[94:95] offset0:118 offset1:135
	ds_write2_b64 v75, v[102:103], v[118:119] offset0:152 offset1:169
	ds_write2_b64 v75, v[110:111], v[106:107] offset0:186 offset1:203
	ds_write2_b64 v75, v[104:105], v[112:113] offset0:220 offset1:237
	ds_write2_b64 v88, v[116:117], v[80:81] offset0:126 offset1:143
	s_mov_b32 s2, 0x1800000
	s_mov_b32 s2, 0x3000000
	s_nop 0
	s_mov_b32 s2, 0x4800000
	s_nop 0
	s_waitcnt lgkmcnt(0)
	s_barrier
; #define LAS __attribute__((address_space(3)))
; #define SINCOSPI(x, s, c) do { const float hx_ = 0.5f * (x); *(s) = __builtin_amdgcn_sinf(hx_); *(c) = __builtin_amdgcn_cosf(hx_); } while (0)
; #define OPAQUE_I(x) asm volatile("" : "+v"(x))
; DEV void fft_i1x2(LAS cf* buf0, LAS cf* buf1, cf (&y0)[8], cf (&y1)[8], int tid) {
;     OPAQUE_I(tid);
;     float sn, cs; SINCOSPI(-(float)tid * (2.0f / 8192.0f), &sn, &cs);
;     const cf w = cf{cs, sn}; cf wp = cf{1.f, 0.f};
;     cf v[16], u[16];
;     const LAS cf* p0 = buf0 + PADI(tid); const LAS cf* p1 = buf1 + PADI(tid);
; #pragma unroll
;     for (int p = 0; p < 16; ++p) { v[p] = cmulc(p0[544 * p], wp); u[p] = cmulc(p1[544 * p], wp); wp = cmul(wp, w); }
	s_nop 0
	v_mov_b32_e32 v100, v21
	s_andn2_b64 vcc, exec, s[26:27]
	v_cvt_f32_i32_e32 v101, v100
	v_mul_f32_e32 v101, 0xb9800000, v101
	v_mul_f32_e32 v101, 0.5, v101
	v_sin_f32_e32 v93, v101
	v_cos_f32_e32 v92, v101
	v_ashrrev_i32_e32 v101, 4, v100
	v_add_lshl_u32 v100, v101, v100, 3
	v_add_u32_e32 v163, 0, v100
	v_add_u32_e32 v164, s33, v100
	ds_read_b64 v[166:167], v163
	ds_read_b64 v[168:169], v164
	ds_read_b64 v[170:171], v163 offset:4352
	ds_read_b64 v[172:173], v164 offset:4352
	ds_read_b64 v[174:175], v163 offset:8704
	ds_read_b64 v[176:177], v164 offset:8704
	ds_read_b64 v[178:179], v163 offset:13056
	ds_read_b64 v[180:181], v164 offset:13056
	ds_read_b64 v[182:183], v163 offset:17408
	ds_read_b64 v[184:185], v164 offset:17408
	ds_read_b64 v[186:187], v163 offset:21760
	ds_read_b64 v[188:189], v164 offset:21760
	ds_read_b64 v[190:191], v163 offset:26112
	s_waitcnt lgkmcnt(12)
	v_pk_mul_f32 v[18:19], v[166:167], v[66:67] op_sel:[1,1] op_sel_hi:[1,0]
	v_pk_fma_f32 v[76:77], v[166:167], v[66:67], v[18:19] op_sel_hi:[0,1,1] neg_hi:[1,0,0]
	ds_read_b64 v[166:167], v164 offset:26112
	s_waitcnt lgkmcnt(12)
	v_pk_mul_f32 v[18:19], v[168:169], v[66:67] op_sel:[1,1] op_sel_hi:[1,0]
	v_pk_fma_f32 v[16:17], v[168:169], v[66:67], v[18:19] op_sel_hi:[0,1,1] neg_hi:[1,0,0]
	v_pk_mul_f32 v[18:19], v[66:67], v[92:93] op_sel:[1,1] op_sel_hi:[1,0] neg_lo:[1,0]
	v_pk_fma_f32 v[66:67], v[66:67], v[92:93], v[18:19] op_sel_hi:[0,1,1]
	ds_read_b64 v[168:169], v163 offset:30464
	s_waitcnt lgkmcnt(12)
	v_pk_mul_f32 v[68:69], v[170:171], v[66:67] op_sel:[1,1] op_sel_hi:[1,0]
	v_pk_fma_f32 v[78:79], v[170:171], v[66:67], v[68:69] op_sel_hi:[0,1,1] neg_hi:[1,0,0]
	ds_read_b64 v[170:171], v164 offset:30464
	s_waitcnt lgkmcnt(12)
	v_pk_mul_f32 v[68:69], v[172:173], v[66:67] op_sel:[1,1] op_sel_hi:[1,0]
	v_pk_fma_f32 v[18:19], v[172:173], v[66:67], v[68:69] op_sel_hi:[0,1,1] neg_hi:[1,0,0]
	v_pk_mul_f32 v[68:69], v[66:67], v[92:93] op_sel:[1,1] op_sel_hi:[1,0] neg_lo:[1,0]
	v_pk_fma_f32 v[70:71], v[66:67], v[92:93], v[68:69] op_sel_hi:[0,1,1]
	ds_read_b64 v[172:173], v163 offset:34816
	s_waitcnt lgkmcnt(12)
	v_pk_mul_f32 v[68:69], v[174:175], v[70:71] op_sel:[1,1] op_sel_hi:[1,0]
	v_pk_fma_f32 v[82:83], v[174:175], v[70:71], v[68:69] op_sel_hi:[0,1,1] neg_hi:[1,0,0]
	ds_read_b64 v[174:175], v164 offset:34816
	s_waitcnt lgkmcnt(12)
	v_pk_mul_f32 v[68:69], v[176:177], v[70:71] op_sel:[1,1] op_sel_hi:[1,0]
	v_pk_fma_f32 v[66:67], v[176:177], v[70:71], v[68:69] op_sel_hi:[0,1,1] neg_hi:[1,0,0]
	v_pk_mul_f32 v[68:69], v[70:71], v[92:93] op_sel:[1,1] op_sel_hi:[1,0] neg_lo:[1,0]
	v_pk_fma_f32 v[70:71], v[70:71], v[92:93], v[68:69] op_sel_hi:[0,1,1]
	ds_read_b64 v[176:177], v163 offset:39168
	s_waitcnt lgkmcnt(12)
	v_pk_mul_f32 v[72:73], v[178:179], v[70:71] op_sel:[1,1] op_sel_hi:[1,0]
	v_pk_fma_f32 v[84:85], v[178:179], v[70:71], v[72:73] op_sel_hi:[0,1,1] neg_hi:[1,0,0]
	ds_read_b64 v[178:179], v164 offset:39168
	s_waitcnt lgkmcnt(12)
	v_pk_mul_f32 v[72:73], v[180:181], v[70:71] op_sel:[1,1] op_sel_hi:[1,0]
	v_pk_fma_f32 v[68:69], v[180:181], v[70:71], v[72:73] op_sel_hi:[0,1,1] neg_hi:[1,0,0]
	v_pk_mul_f32 v[72:73], v[70:71], v[92:93] op_sel:[1,1] op_sel_hi:[1,0] neg_lo:[1,0]
	v_pk_fma_f32 v[74:75], v[70:71], v[92:93], v[72:73] op_sel_hi:[0,1,1]
	ds_read_b64 v[180:181], v163 offset:43520
	s_waitcnt lgkmcnt(12)
	v_pk_mul_f32 v[72:73], v[182:183], v[74:75] op_sel:[1,1] op_sel_hi:[1,0]
	v_pk_fma_f32 v[86:87], v[182:183], v[74:75], v[72:73] op_sel_hi:[0,1,1] neg_hi:[1,0,0]
	ds_read_b64 v[182:183], v164 offset:43520
	s_waitcnt lgkmcnt(12)
	v_pk_mul_f32 v[72:73], v[184:185], v[74:75] op_sel:[1,1] op_sel_hi:[1,0]
	v_pk_fma_f32 v[70:71], v[184:185], v[74:75], v[72:73] op_sel_hi:[0,1,1] neg_hi:[1,0,0]
	v_pk_mul_f32 v[72:73], v[74:75], v[92:93] op_sel:[1,1] op_sel_hi:[1,0] neg_lo:[1,0]
	v_pk_fma_f32 v[74:75], v[74:75], v[92:93], v[72:73] op_sel_hi:[0,1,1]
	ds_read_b64 v[184:185], v163 offset:47872
	s_waitcnt lgkmcnt(12)
	v_pk_mul_f32 v[80:81], v[186:187], v[74:75] op_sel:[1,1] op_sel_hi:[1,0]
	v_pk_fma_f32 v[90:91], v[186:187], v[74:75], v[80:81] op_sel_hi:[0,1,1] neg_hi:[1,0,0]
	ds_read_b64 v[186:187], v164 offset:47872
	s_waitcnt lgkmcnt(12)
	v_pk_mul_f32 v[80:81], v[188:189], v[74:75] op_sel:[1,1] op_sel_hi:[1,0]
	v_pk_fma_f32 v[72:73], v[188:189], v[74:75], v[80:81] op_sel_hi:[0,1,1] neg_hi:[1,0,0]
	v_pk_mul_f32 v[80:81], v[74:75], v[92:93] op_sel:[1,1] op_sel_hi:[1,0] neg_lo:[1,0]
	v_pk_fma_f32 v[88:89], v[74:75], v[92:93], v[80:81] op_sel_hi:[0,1,1]
	ds_read_b64 v[188:189], v163 offset:52224
	s_waitcnt lgkmcnt(12)
	v_pk_mul_f32 v[80:81], v[190:191], v[88:89] op_sel:[1,1] op_sel_hi:[1,0]
	v_pk_fma_f32 v[94:95], v[190:191], v[88:89], v[80:81] op_sel_hi:[0,1,1] neg_hi:[1,0,0]
	ds_read_b64 v[190:191], v164 offset:52224
	s_waitcnt lgkmcnt(12)
	v_pk_mul_f32 v[80:81], v[166:167], v[88:89] op_sel:[1,1] op_sel_hi:[1,0]
	v_pk_fma_f32 v[74:75], v[166:167], v[88:89], v[80:81] op_sel_hi:[0,1,1] neg_hi:[1,0,0]
	v_pk_mul_f32 v[80:81], v[88:89], v[92:93] op_sel:[1,1] op_sel_hi:[1,0] neg_lo:[1,0]
	v_pk_fma_f32 v[88:89], v[88:89], v[92:93], v[80:81] op_sel_hi:[0,1,1]
	ds_read_b64 v[166:167], v163 offset:56576
	s_waitcnt lgkmcnt(12)
	v_pk_mul_f32 v[96:97], v[168:169], v[88:89] op_sel:[1,1] op_sel_hi:[1,0]
	v_pk_fma_f32 v[98:99], v[168:169], v[88:89], v[96:97] op_sel_hi:[0,1,1] neg_hi:[1,0,0]
	ds_read_b64 v[168:169], v164 offset:56576
	s_waitcnt lgkmcnt(12)
; #define LAS __attribute__((address_space(3)))
; DEV void fft_i1x2(LAS cf* buf0, LAS cf* buf1, cf (&y0)[8], cf (&y1)[8], int tid) {
;     ...
;     const cf w = cf{cs, sn}; cf wp = cf{1.f, 0.f};
;     cf v[16], u[16];
;     const LAS cf* p0 = buf0 + PADI(tid); const LAS cf* p1 = buf1 + PADI(tid);
; #pragma unroll
;     for (int p = 0; p < 16; ++p) { v[p] = cmulc(p0[544 * p], wp); u[p] = cmulc(p1[544 * p], wp); wp = cmul(wp, w); }
; DEV void hyena_issue_rows(const bf16_t* UT, int s, int c, u32x4 (&r)[4], int tid) {
; #pragma unroll
;     for (int b = 0; b < 4; ++b) r[b] = *(const u32x4*)(UT + ((size_t)(b * 3072 + s * 1024 + c)) * 4096 + tid * 8);
; }
; DEV void hyena_commit_rows(LAS unsigned char* lds, const u32x4 (&r)[4], int tid) {
; #pragma unroll
;     for (int b = 0; b < 4; ++b) *(LAS u32x4*)(lds + b * 8192 + tid * 16) = r[b];
; }
	v_pk_mul_f32 v[96:97], v[170:171], v[88:89] op_sel:[1,1] op_sel_hi:[1,0]
	v_pk_fma_f32 v[80:81], v[170:171], v[88:89], v[96:97] op_sel_hi:[0,1,1] neg_hi:[1,0,0]
	v_pk_mul_f32 v[96:97], v[88:89], v[92:93] op_sel:[1,1] op_sel_hi:[1,0] neg_lo:[1,0]
	v_pk_fma_f32 v[102:103], v[88:89], v[92:93], v[96:97] op_sel_hi:[0,1,1]
	ds_read_b64 v[170:171], v163 offset:60928
	s_waitcnt lgkmcnt(12)
	v_pk_mul_f32 v[96:97], v[172:173], v[102:103] op_sel:[1,1] op_sel_hi:[1,0]
	v_pk_fma_f32 v[100:101], v[172:173], v[102:103], v[96:97] op_sel_hi:[0,1,1] neg_hi:[1,0,0]
	ds_read_b64 v[172:173], v164 offset:60928
	s_waitcnt lgkmcnt(12)
	v_pk_mul_f32 v[96:97], v[174:175], v[102:103] op_sel:[1,1] op_sel_hi:[1,0]
	v_pk_fma_f32 v[88:89], v[174:175], v[102:103], v[96:97] op_sel_hi:[0,1,1] neg_hi:[1,0,0]
	v_pk_mul_f32 v[96:97], v[102:103], v[92:93] op_sel:[1,1] op_sel_hi:[1,0] neg_lo:[1,0]
	v_pk_fma_f32 v[102:103], v[102:103], v[92:93], v[96:97] op_sel_hi:[0,1,1]
	ds_read_b64 v[174:175], v163 offset:65280
	s_waitcnt lgkmcnt(12)
	v_pk_mul_f32 v[104:105], v[176:177], v[102:103] op_sel:[1,1] op_sel_hi:[1,0]
	v_pk_fma_f32 v[112:113], v[176:177], v[102:103], v[104:105] op_sel_hi:[0,1,1] neg_hi:[1,0,0]
	ds_read_b64 v[176:177], v164 offset:65280
	s_waitcnt lgkmcnt(12)
	v_pk_mul_f32 v[104:105], v[178:179], v[102:103] op_sel:[1,1] op_sel_hi:[1,0]
	v_pk_fma_f32 v[96:97], v[178:179], v[102:103], v[104:105] op_sel_hi:[0,1,1] neg_hi:[1,0,0]
	v_pk_mul_f32 v[104:105], v[102:103], v[92:93] op_sel:[1,1] op_sel_hi:[1,0] neg_lo:[1,0]
	v_pk_fma_f32 v[106:107], v[102:103], v[92:93], v[104:105] op_sel_hi:[0,1,1]
	s_waitcnt lgkmcnt(11)
	v_pk_mul_f32 v[104:105], v[180:181], v[106:107] op_sel:[1,1] op_sel_hi:[1,0]
	v_pk_fma_f32 v[116:117], v[180:181], v[106:107], v[104:105] op_sel_hi:[0,1,1] neg_hi:[1,0,0]
	s_waitcnt lgkmcnt(10)
	v_pk_mul_f32 v[104:105], v[182:183], v[106:107] op_sel:[1,1] op_sel_hi:[1,0]
	v_pk_fma_f32 v[102:103], v[182:183], v[106:107], v[104:105] op_sel_hi:[0,1,1] neg_hi:[1,0,0]
	v_pk_mul_f32 v[104:105], v[106:107], v[92:93] op_sel:[1,1] op_sel_hi:[1,0] neg_lo:[1,0]
	v_pk_fma_f32 v[106:107], v[106:107], v[92:93], v[104:105] op_sel_hi:[0,1,1]
	s_waitcnt lgkmcnt(9)
	v_pk_mul_f32 v[108:109], v[184:185], v[106:107] op_sel:[1,1] op_sel_hi:[1,0]
	v_pk_fma_f32 v[118:119], v[184:185], v[106:107], v[108:109] op_sel_hi:[0,1,1] neg_hi:[1,0,0]
	s_waitcnt lgkmcnt(8)
	v_pk_mul_f32 v[108:109], v[186:187], v[106:107] op_sel:[1,1] op_sel_hi:[1,0]
	v_pk_fma_f32 v[104:105], v[186:187], v[106:107], v[108:109] op_sel_hi:[0,1,1] neg_hi:[1,0,0]
	v_pk_mul_f32 v[108:109], v[106:107], v[92:93] op_sel:[1,1] op_sel_hi:[1,0] neg_lo:[1,0]
	v_pk_fma_f32 v[110:111], v[106:107], v[92:93], v[108:109] op_sel_hi:[0,1,1]
	s_waitcnt lgkmcnt(7)
	v_pk_mul_f32 v[108:109], v[188:189], v[110:111] op_sel:[1,1] op_sel_hi:[1,0]
	v_pk_fma_f32 v[120:121], v[188:189], v[110:111], v[108:109] op_sel_hi:[0,1,1] neg_hi:[1,0,0]
	s_waitcnt lgkmcnt(6)
	v_pk_mul_f32 v[108:109], v[190:191], v[110:111] op_sel:[1,1] op_sel_hi:[1,0]
	v_pk_fma_f32 v[106:107], v[190:191], v[110:111], v[108:109] op_sel_hi:[0,1,1] neg_hi:[1,0,0]
	v_pk_mul_f32 v[108:109], v[110:111], v[92:93] op_sel:[1,1] op_sel_hi:[1,0] neg_lo:[1,0]
	v_pk_fma_f32 v[110:111], v[110:111], v[92:93], v[108:109] op_sel_hi:[0,1,1]
	s_waitcnt lgkmcnt(5)
	v_pk_mul_f32 v[114:115], v[166:167], v[110:111] op_sel:[1,1] op_sel_hi:[1,0]
	v_pk_fma_f32 v[122:123], v[166:167], v[110:111], v[114:115] op_sel_hi:[0,1,1] neg_hi:[1,0,0]
	s_waitcnt lgkmcnt(4)
	v_pk_mul_f32 v[114:115], v[168:169], v[110:111] op_sel:[1,1] op_sel_hi:[1,0]
	v_pk_fma_f32 v[108:109], v[168:169], v[110:111], v[114:115] op_sel_hi:[0,1,1] neg_hi:[1,0,0]
	v_pk_mul_f32 v[114:115], v[110:111], v[92:93] op_sel:[1,1] op_sel_hi:[1,0] neg_lo:[1,0]
	v_pk_fma_f32 v[126:127], v[110:111], v[92:93], v[114:115] op_sel_hi:[0,1,1]
	s_waitcnt lgkmcnt(3)
	v_pk_mul_f32 v[114:115], v[170:171], v[126:127] op_sel:[1,1] op_sel_hi:[1,0]
	v_pk_fma_f32 v[124:125], v[170:171], v[126:127], v[114:115] op_sel_hi:[0,1,1] neg_hi:[1,0,0]
	s_waitcnt lgkmcnt(2)
	v_pk_mul_f32 v[114:115], v[172:173], v[126:127] op_sel:[1,1] op_sel_hi:[1,0]
	v_pk_fma_f32 v[110:111], v[172:173], v[126:127], v[114:115] op_sel_hi:[0,1,1] neg_hi:[1,0,0]
	v_pk_mul_f32 v[114:115], v[126:127], v[92:93] op_sel:[1,1] op_sel_hi:[1,0] neg_lo:[1,0]
	v_pk_fma_f32 v[126:127], v[126:127], v[92:93], v[114:115] op_sel_hi:[0,1,1]
	s_waitcnt lgkmcnt(1)
	v_pk_mul_f32 v[114:115], v[174:175], v[126:127] op_sel:[1,1] op_sel_hi:[1,0]
	v_pk_fma_f32 v[92:93], v[174:175], v[126:127], v[114:115] op_sel_hi:[0,1,1] neg_hi:[1,0,0]
	s_waitcnt lgkmcnt(0)
	v_pk_mul_f32 v[164:165], v[176:177], v[126:127] op_sel:[1,1] op_sel_hi:[1,0]
	v_pk_fma_f32 v[114:115], v[176:177], v[126:127], v[164:165] op_sel_hi:[0,1,1] neg_hi:[1,0,0]
	s_barrier
	s_waitcnt vmcnt(3)
	ds_write_b128 v128, v[222:225]
	s_waitcnt vmcnt(2)
	ds_write_b128 v128, v[226:229] offset:8192
	s_waitcnt vmcnt(1)
	ds_write_b128 v128, v[236:239] offset:16384
	s_waitcnt vmcnt(0)
	ds_write_b128 v128, v[240:243] offset:24576
	s_cbranch_vccnz .LBB0_518
	s_andn2_b64 vcc, exec, s[20:21]
	s_cbranch_vccnz .LBB0_518
	global_load_dwordx4 v[0:3], v[58:59], off
	global_load_dwordx4 v[4:7], v[60:61], off
	global_load_dwordx4 v[8:11], v[62:63], off
	global_load_dwordx4 v[12:15], v[64:65], off
	s_branch .LBB0_518
